# GEMM main loops (5 copies): loop-back barrier rotated to the loop head, counter/pointer bumps and exit test moved in front of it, exit path gets its own barrier copy
# baseline (speedup 1.0000x reference)
; #define STAGE_B(P, br, kt) do { const char* _gb = (const char*)(Bt + ((long)(br) * K + (long)(kt) * BK)); \
;     __builtin_amdgcn_global_load_lds((const unsigned*)(_gb + bofl0), (unsigned*)((char*)(P) + gtid_ * 16), 16, 0, 0); \
;     __builtin_amdgcn_global_load_lds((const unsigned*)(_gb + (long)K * 128 + bofl0), (unsigned*)((char*)(P) + gtid_ * 16 + 8192), 16, 0, 0); } while (0)
; #define LDA(dst, b, h) for (int m = 0; m < 4; ++m) for (int k = 0; k < 2; ++k) \
;     dst[m][k] = *reinterpret_cast<const bf16x8*>((char*)SA(b, h) + lds_byte(wr * 64 + m * 16 + fr, k * 32 + fq * 8))
; #define LDB(dst, b, h) for (int n = 0; n < 2; ++n) for (int k = 0; k < 2; ++k) \
;     dst[n][k] = *reinterpret_cast<const bf16x8*>((char*)SB(b, h) + lds_byte(wc * 32 + n * 16 + fr, k * 32 + fq * 8))
; #define MMA(ai, bj, At_, Bt_) do { __builtin_amdgcn_s_setprio(1); \
;     for (int m = 0; m < 4; ++m) for (int n = 0; n < 2; ++n) for (int k = 0; k < 2; ++k) \
;       acc[ai][bj][m][n] = __builtin_amdgcn_mfma_f32_16x16x32_bf16(At_[m][k], Bt_[n][k], acc[ai][bj][m][n], 0, 0, 0); \
;     __builtin_amdgcn_s_setprio(0); } while (0)
; #define WAIT_V(n) asm volatile("s_waitcnt vmcnt(" #n ")" ::: "memory")
; #define WAIT_L(n) asm volatile("s_waitcnt lgkmcnt(" #n ")" ::: "memory")
; #define BAR __builtin_amdgcn_s_barrier()
; #define SCHED __builtin_amdgcn_sched_barrier(0)
; template <int EPI>
; __device__ __forceinline__ void gemm_tile(const GemmArgs& g, int brow, int bcol, int parity, bool first, bool nvalid, int nbrow, int nbcol) {
;     ...
;   for (int t = 0; t < nt - 2; t += 2) {
;     LDB(B0, 0, 0); SCHED; LDA(At, 0, 0); STAGE_A(SA(1, 1), brow + HALF, t + 1);
;     WAIT_L(8); BAR; WAIT_L(0); MMA(0, 0, At, B0); BAR; SCHED;
;     LDB(B1, 0, 1); STAGE_B(SB(0, 0), bcol, t + 2);
;     BAR; WAIT_L(0); MMA(0, 1, At, B1); BAR; SCHED;
;     LDA(At, 0, 1); STAGE_A(SA(0, 0), brow, t + 2);
;     BAR; WAIT_L(0); MMA(1, 0, At, B0); BAR; SCHED;
;     STAGE_B(SB(0, 1), bcol + HALF, t + 2);
;     WAIT_V(6); BAR; MMA(1, 1, At, B1); BAR; SCHED;
;     LDB(B0, 1, 0); SCHED; LDA(At, 1, 0); STAGE_A(SA(0, 1), brow + HALF, t + 2);
;     WAIT_L(8); BAR; WAIT_L(0); MMA(0, 0, At, B0); BAR; SCHED;
.LBB0_90:
	s_barrier
	ds_read_b128 v[164:167], v157
	ds_read_b128 v[168:171], v157 offset:1024
	ds_read_b128 v[172:175], v157 offset:2048
	ds_read_b128 v[176:179], v157 offset:3072
	ds_read_b128 v[180:183], v147
	ds_read_b128 v[184:187], v147 offset:1024
	ds_read_b128 v[188:191], v146
	ds_read_b128 v[192:195], v146 offset:1024
	ds_read_b128 v[196:199], v145
	ds_read_b128 v[202:205], v145 offset:1024
	ds_read_b128 v[206:209], v144
	ds_read_b128 v[216:219], v144 offset:1024
	s_waitcnt lgkmcnt(6)
	ds_read_b128 v[228:231], v154
	ds_read_b128 v[232:235], v154 offset:1024
	ds_read_b128 v[236:239], v154 offset:2048
	ds_read_b128 v[240:243], v154 offset:3072
	v_add_u32_e32 v161, 0xc000, v137
	v_lshl_add_u64 v[210:211], s[0:1], 0, v[130:131]
	v_readfirstlane_b32 s2, v161
	v_add_u32_e32 v162, 0xe000, v137
	v_lshl_add_u64 v[158:159], v[210:211], 0, s[26:27]
	s_mov_b32 m0, s2
	v_readfirstlane_b32 s2, v162
	global_load_lds_dwordx4 v[158:159], off
	v_lshl_add_u64 v[158:159], v[210:211], 0, s[36:37]
	s_mov_b32 m0, s2
	s_nop 0
	global_load_lds_dwordx4 v[158:159], off
	s_waitcnt vmcnt(8)
	s_barrier
	s_waitcnt lgkmcnt(0)
	v_mfma_f32_16x16x32_bf16 v[126:129], v[164:167], v[180:183], v[126:129]
	v_mfma_f32_16x16x32_bf16 v[122:125], v[172:175], v[180:183], v[122:125]
	v_mfma_f32_16x16x32_bf16 v[118:121], v[164:167], v[188:191], v[118:121]
	v_mfma_f32_16x16x32_bf16 v[114:117], v[172:175], v[188:191], v[114:117]
	v_mfma_f32_16x16x32_bf16 v[110:113], v[164:167], v[196:199], v[110:113]
	v_mfma_f32_16x16x32_bf16 v[106:109], v[172:175], v[196:199], v[106:109]
	v_mfma_f32_16x16x32_bf16 v[102:105], v[164:167], v[206:209], v[102:105]
	v_mfma_f32_16x16x32_bf16 v[98:101], v[172:175], v[206:209], v[98:101]
	v_mfma_f32_16x16x32_bf16 v[126:129], v[168:171], v[184:187], v[126:129]
	v_mfma_f32_16x16x32_bf16 v[122:125], v[176:179], v[184:187], v[122:125]
	v_mfma_f32_16x16x32_bf16 v[118:121], v[168:171], v[192:195], v[118:121]
	v_mfma_f32_16x16x32_bf16 v[114:117], v[176:179], v[192:195], v[114:117]
	v_mfma_f32_16x16x32_bf16 v[110:113], v[168:171], v[202:205], v[110:113]
	v_mfma_f32_16x16x32_bf16 v[106:109], v[176:179], v[202:205], v[106:109]
	v_mfma_f32_16x16x32_bf16 v[102:105], v[168:171], v[216:219], v[102:105]
	v_mfma_f32_16x16x32_bf16 v[98:101], v[176:179], v[216:219], v[98:101]
	v_mfma_f32_16x16x32_bf16 v[94:97], v[228:231], v[180:183], v[94:97]
	v_mfma_f32_16x16x32_bf16 v[90:93], v[236:239], v[180:183], v[90:93]
	v_mfma_f32_16x16x32_bf16 v[86:89], v[228:231], v[188:191], v[86:89]
	v_mfma_f32_16x16x32_bf16 v[82:85], v[236:239], v[188:191], v[82:85]
	v_mfma_f32_16x16x32_bf16 v[78:81], v[228:231], v[196:199], v[78:81]
	v_mfma_f32_16x16x32_bf16 v[74:77], v[236:239], v[196:199], v[74:77]
	v_mfma_f32_16x16x32_bf16 v[70:73], v[228:231], v[206:209], v[70:73]
	v_mfma_f32_16x16x32_bf16 v[66:69], v[236:239], v[206:209], v[66:69]
	v_mfma_f32_16x16x32_bf16 v[94:97], v[232:235], v[184:187], v[94:97]
	v_mfma_f32_16x16x32_bf16 v[90:93], v[240:243], v[184:187], v[90:93]
	v_mfma_f32_16x16x32_bf16 v[86:89], v[232:235], v[192:195], v[86:89]
	v_mfma_f32_16x16x32_bf16 v[82:85], v[240:243], v[192:195], v[82:85]
	v_mfma_f32_16x16x32_bf16 v[78:81], v[232:235], v[202:205], v[78:81]
	v_mfma_f32_16x16x32_bf16 v[74:77], v[240:243], v[202:205], v[74:77]
	v_mfma_f32_16x16x32_bf16 v[70:73], v[232:235], v[216:219], v[70:73]
	v_mfma_f32_16x16x32_bf16 v[66:69], v[240:243], v[216:219], v[66:69]
	s_barrier
	ds_read_b128 v[180:183], v147 offset:16384
	ds_read_b128 v[184:187], v147 offset:17408
	ds_read_b128 v[188:191], v146 offset:16384
	ds_read_b128 v[192:195], v146 offset:17408
	ds_read_b128 v[196:199], v145 offset:16384
	ds_read_b128 v[202:205], v145 offset:17408
	ds_read_b128 v[206:209], v144 offset:16384
	ds_read_b128 v[216:219], v144 offset:17408
	v_lshl_add_u64 v[212:213], s[12:13], 0, v[130:131]
	s_mov_b64 s[2:3], 0x900100
	v_add_u32_e32 v158, s14, v142
	v_lshl_add_u64 v[222:223], v[212:213], 0, s[2:3]
	v_readfirstlane_b32 s2, v158
	s_mov_b32 m0, s2
	s_mov_b64 s[2:3], 0x920100
	v_add_u32_e32 v159, 0x2000, v158
	global_load_lds_dwordx4 v[222:223], off
	v_lshl_add_u64 v[222:223], v[212:213], 0, s[2:3]
	v_readfirstlane_b32 s2, v159
	s_mov_b32 m0, s2
	s_nop 0
	global_load_lds_dwordx4 v[222:223], off
	v_readfirstlane_b32 s2, v137
	v_lshl_add_u64 v[222:223], v[210:211], 0, s[40:41]
	s_mov_b32 m0, s2
	v_readfirstlane_b32 s2, v136
	global_load_lds_dwordx4 v[222:223], off
	v_lshl_add_u64 v[222:223], v[210:211], 0, s[44:45]
	s_mov_b32 m0, s2
	s_nop 0
	global_load_lds_dwordx4 v[222:223], off
	s_mov_b64 s[2:3], 0x940100
	v_lshl_add_u64 v[244:245], v[212:213], 0, s[2:3]
	v_readfirstlane_b32 s2, v135
	s_mov_b32 m0, s2
	s_mov_b64 s[2:3], 0x960100
	v_add_u32_e32 v160, 0x2000, v135
	global_load_lds_dwordx4 v[244:245], off
	v_lshl_add_u64 v[244:245], v[212:213], 0, s[2:3]
	v_readfirstlane_b32 s2, v160
	s_mov_b32 m0, s2
	s_nop 0
	global_load_lds_dwordx4 v[244:245], off
	s_waitcnt vmcnt(8)
	s_barrier
; #define STAGE_B(P, br, kt) do { const char* _gb = (const char*)(Bt + ((long)(br) * K + (long)(kt) * BK)); \
;     __builtin_amdgcn_global_load_lds((const unsigned*)(_gb + bofl0), (unsigned*)((char*)(P) + gtid_ * 16), 16, 0, 0); \
;     __builtin_amdgcn_global_load_lds((const unsigned*)(_gb + (long)K * 128 + bofl0), (unsigned*)((char*)(P) + gtid_ * 16 + 8192), 16, 0, 0); } while (0)
; #define LDA(dst, b, h) for (int m = 0; m < 4; ++m) for (int k = 0; k < 2; ++k) \
;     dst[m][k] = *reinterpret_cast<const bf16x8*>((char*)SA(b, h) + lds_byte(wr * 64 + m * 16 + fr, k * 32 + fq * 8))
; #define LDB(dst, b, h) for (int n = 0; n < 2; ++n) for (int k = 0; k < 2; ++k) \
;     dst[n][k] = *reinterpret_cast<const bf16x8*>((char*)SB(b, h) + lds_byte(wc * 32 + n * 16 + fr, k * 32 + fq * 8))
; #define MMA(ai, bj, At_, Bt_) do { __builtin_amdgcn_s_setprio(1); \
;     for (int m = 0; m < 4; ++m) for (int n = 0; n < 2; ++n) for (int k = 0; k < 2; ++k) \
;       acc[ai][bj][m][n] = __builtin_amdgcn_mfma_f32_16x16x32_bf16(At_[m][k], Bt_[n][k], acc[ai][bj][m][n], 0, 0, 0); \
;     __builtin_amdgcn_s_setprio(0); } while (0)
; #define WAIT_V(n) asm volatile("s_waitcnt vmcnt(" #n ")" ::: "memory")
; #define WAIT_L(n) asm volatile("s_waitcnt lgkmcnt(" #n ")" ::: "memory")
; #define BAR __builtin_amdgcn_s_barrier()
; #define SCHED __builtin_amdgcn_sched_barrier(0)
; template <int EPI>
; __device__ __forceinline__ void gemm_tile(const GemmArgs& g, int brow, int bcol, int parity, bool first, bool nvalid, int nbrow, int nbcol) {
;     ...
;     WAIT_V(6); BAR; MMA(1, 1, At, B1); BAR; SCHED;
;     LDB(B0, 1, 0); SCHED; LDA(At, 1, 0); STAGE_A(SA(0, 1), brow + HALF, t + 2);
;     WAIT_L(8); BAR; WAIT_L(0); MMA(0, 0, At, B0); BAR; SCHED;
;     LDB(B1, 1, 1); STAGE_B(SB(1, 0), bcol, t + 3);
;     BAR; WAIT_L(0); MMA(0, 1, At, B1); BAR; SCHED;
;     LDA(At, 1, 1); STAGE_A(SA(1, 0), brow, t + 3);
;     BAR; WAIT_L(0); MMA(1, 0, At, B0); BAR; SCHED;
	s_waitcnt lgkmcnt(0)
	v_mfma_f32_16x16x32_bf16 v[62:65], v[164:167], v[180:183], v[62:65]
	v_mfma_f32_16x16x32_bf16 v[58:61], v[172:175], v[180:183], v[58:61]
	v_mfma_f32_16x16x32_bf16 v[54:57], v[164:167], v[188:191], v[54:57]
	v_mfma_f32_16x16x32_bf16 v[50:53], v[172:175], v[188:191], v[50:53]
	v_mfma_f32_16x16x32_bf16 v[46:49], v[164:167], v[196:199], v[46:49]
	v_mfma_f32_16x16x32_bf16 v[42:45], v[172:175], v[196:199], v[42:45]
	v_mfma_f32_16x16x32_bf16 v[38:41], v[164:167], v[206:209], v[38:41]
	v_mfma_f32_16x16x32_bf16 v[34:37], v[172:175], v[206:209], v[34:37]
	v_mfma_f32_16x16x32_bf16 v[62:65], v[168:171], v[184:187], v[62:65]
	v_mfma_f32_16x16x32_bf16 v[58:61], v[176:179], v[184:187], v[58:61]
	v_mfma_f32_16x16x32_bf16 v[54:57], v[168:171], v[192:195], v[54:57]
	v_mfma_f32_16x16x32_bf16 v[50:53], v[176:179], v[192:195], v[50:53]
	v_mfma_f32_16x16x32_bf16 v[46:49], v[168:171], v[202:205], v[46:49]
	v_mfma_f32_16x16x32_bf16 v[42:45], v[176:179], v[202:205], v[42:45]
	v_mfma_f32_16x16x32_bf16 v[38:41], v[168:171], v[216:219], v[38:41]
	v_mfma_f32_16x16x32_bf16 v[34:37], v[176:179], v[216:219], v[34:37]
	v_mfma_f32_16x16x32_bf16 v[30:33], v[228:231], v[180:183], v[30:33]
	v_mfma_f32_16x16x32_bf16 v[26:29], v[236:239], v[180:183], v[26:29]
	v_mfma_f32_16x16x32_bf16 v[22:25], v[228:231], v[188:191], v[22:25]
	v_mfma_f32_16x16x32_bf16 v[18:21], v[236:239], v[188:191], v[18:21]
	v_mfma_f32_16x16x32_bf16 v[14:17], v[228:231], v[196:199], v[14:17]
	v_mfma_f32_16x16x32_bf16 v[10:13], v[236:239], v[196:199], v[10:13]
	v_mfma_f32_16x16x32_bf16 v[6:9], v[228:231], v[206:209], v[6:9]
	v_mfma_f32_16x16x32_bf16 v[2:5], v[236:239], v[206:209], v[2:5]
	v_mfma_f32_16x16x32_bf16 v[30:33], v[232:235], v[184:187], v[30:33]
	v_mfma_f32_16x16x32_bf16 v[26:29], v[240:243], v[184:187], v[26:29]
	v_mfma_f32_16x16x32_bf16 v[22:25], v[232:235], v[192:195], v[22:25]
	v_mfma_f32_16x16x32_bf16 v[18:21], v[240:243], v[192:195], v[18:21]
	v_mfma_f32_16x16x32_bf16 v[14:17], v[232:235], v[202:205], v[14:17]
	v_mfma_f32_16x16x32_bf16 v[10:13], v[240:243], v[202:205], v[10:13]
	v_mfma_f32_16x16x32_bf16 v[6:9], v[232:235], v[216:219], v[6:9]
	v_mfma_f32_16x16x32_bf16 v[2:5], v[240:243], v[216:219], v[2:5]
	s_barrier
	ds_read_b128 v[164:167], v149
	ds_read_b128 v[168:171], v149 offset:1024
	ds_read_b128 v[172:175], v149 offset:2048
	ds_read_b128 v[176:179], v149 offset:3072
	ds_read_b128 v[180:183], v147 offset:32768
	ds_read_b128 v[184:187], v147 offset:33792
	ds_read_b128 v[188:191], v146 offset:32768
	ds_read_b128 v[192:195], v146 offset:33792
	ds_read_b128 v[196:199], v145 offset:32768
	ds_read_b128 v[202:205], v145 offset:33792
	ds_read_b128 v[206:209], v144 offset:32768
	ds_read_b128 v[216:219], v144 offset:33792
	s_waitcnt lgkmcnt(6)
	ds_read_b128 v[228:231], v148
	ds_read_b128 v[232:235], v148 offset:1024
	ds_read_b128 v[236:239], v148 offset:2048
	ds_read_b128 v[240:243], v148 offset:3072
	v_readfirstlane_b32 s2, v134
	v_lshl_add_u64 v[222:223], v[210:211], 0, s[46:47]
	s_mov_b32 m0, s2
	v_readfirstlane_b32 s2, v133
	global_load_lds_dwordx4 v[222:223], off
	v_lshl_add_u64 v[222:223], v[210:211], 0, s[48:49]
	s_mov_b32 m0, s2
	s_nop 0
	global_load_lds_dwordx4 v[222:223], off
	s_waitcnt vmcnt(8)
	s_barrier
	s_waitcnt lgkmcnt(0)
	v_mfma_f32_16x16x32_bf16 v[126:129], v[164:167], v[180:183], v[126:129]
	v_mfma_f32_16x16x32_bf16 v[122:125], v[172:175], v[180:183], v[122:125]
	v_mfma_f32_16x16x32_bf16 v[118:121], v[164:167], v[188:191], v[118:121]
	v_mfma_f32_16x16x32_bf16 v[114:117], v[172:175], v[188:191], v[114:117]
	v_mfma_f32_16x16x32_bf16 v[110:113], v[164:167], v[196:199], v[110:113]
	v_mfma_f32_16x16x32_bf16 v[106:109], v[172:175], v[196:199], v[106:109]
	v_mfma_f32_16x16x32_bf16 v[102:105], v[164:167], v[206:209], v[102:105]
	v_mfma_f32_16x16x32_bf16 v[98:101], v[172:175], v[206:209], v[98:101]
	v_mfma_f32_16x16x32_bf16 v[126:129], v[168:171], v[184:187], v[126:129]
	v_mfma_f32_16x16x32_bf16 v[122:125], v[176:179], v[184:187], v[122:125]
	v_mfma_f32_16x16x32_bf16 v[118:121], v[168:171], v[192:195], v[118:121]
	v_mfma_f32_16x16x32_bf16 v[114:117], v[176:179], v[192:195], v[114:117]
	v_mfma_f32_16x16x32_bf16 v[110:113], v[168:171], v[202:205], v[110:113]
	v_mfma_f32_16x16x32_bf16 v[106:109], v[176:179], v[202:205], v[106:109]
	v_mfma_f32_16x16x32_bf16 v[102:105], v[168:171], v[216:219], v[102:105]
	v_mfma_f32_16x16x32_bf16 v[98:101], v[176:179], v[216:219], v[98:101]
	v_mfma_f32_16x16x32_bf16 v[94:97], v[228:231], v[180:183], v[94:97]
	v_mfma_f32_16x16x32_bf16 v[90:93], v[236:239], v[180:183], v[90:93]
	v_mfma_f32_16x16x32_bf16 v[86:89], v[228:231], v[188:191], v[86:89]
	v_mfma_f32_16x16x32_bf16 v[82:85], v[236:239], v[188:191], v[82:85]
	v_mfma_f32_16x16x32_bf16 v[78:81], v[228:231], v[196:199], v[78:81]
	v_mfma_f32_16x16x32_bf16 v[74:77], v[236:239], v[196:199], v[74:77]
	v_mfma_f32_16x16x32_bf16 v[70:73], v[228:231], v[206:209], v[70:73]
	v_mfma_f32_16x16x32_bf16 v[66:69], v[236:239], v[206:209], v[66:69]
	v_mfma_f32_16x16x32_bf16 v[94:97], v[232:235], v[184:187], v[94:97]
	v_mfma_f32_16x16x32_bf16 v[90:93], v[240:243], v[184:187], v[90:93]
	v_mfma_f32_16x16x32_bf16 v[86:89], v[232:235], v[192:195], v[86:89]
	v_mfma_f32_16x16x32_bf16 v[82:85], v[240:243], v[192:195], v[82:85]
	v_mfma_f32_16x16x32_bf16 v[78:81], v[232:235], v[202:205], v[78:81]
	v_mfma_f32_16x16x32_bf16 v[74:77], v[240:243], v[202:205], v[74:77]
	v_mfma_f32_16x16x32_bf16 v[70:73], v[232:235], v[216:219], v[70:73]
	v_mfma_f32_16x16x32_bf16 v[66:69], v[240:243], v[216:219], v[66:69]
	s_barrier
; #define STAGE_B(P, br, kt) do { const char* _gb = (const char*)(Bt + ((long)(br) * K + (long)(kt) * BK)); \
;     __builtin_amdgcn_global_load_lds((const unsigned*)(_gb + bofl0), (unsigned*)((char*)(P) + gtid_ * 16), 16, 0, 0); \
;     __builtin_amdgcn_global_load_lds((const unsigned*)(_gb + (long)K * 128 + bofl0), (unsigned*)((char*)(P) + gtid_ * 16 + 8192), 16, 0, 0); } while (0)
; #define LDA(dst, b, h) for (int m = 0; m < 4; ++m) for (int k = 0; k < 2; ++k) \
;     dst[m][k] = *reinterpret_cast<const bf16x8*>((char*)SA(b, h) + lds_byte(wr * 64 + m * 16 + fr, k * 32 + fq * 8))
; #define LDB(dst, b, h) for (int n = 0; n < 2; ++n) for (int k = 0; k < 2; ++k) \
;     dst[n][k] = *reinterpret_cast<const bf16x8*>((char*)SB(b, h) + lds_byte(wc * 32 + n * 16 + fr, k * 32 + fq * 8))
; #define MMA(ai, bj, At_, Bt_) do { __builtin_amdgcn_s_setprio(1); \
;     for (int m = 0; m < 4; ++m) for (int n = 0; n < 2; ++n) for (int k = 0; k < 2; ++k) \
;       acc[ai][bj][m][n] = __builtin_amdgcn_mfma_f32_16x16x32_bf16(At_[m][k], Bt_[n][k], acc[ai][bj][m][n], 0, 0, 0); \
;     __builtin_amdgcn_s_setprio(0); } while (0)
; #define WAIT_V(n) asm volatile("s_waitcnt vmcnt(" #n ")" ::: "memory")
; #define WAIT_L(n) asm volatile("s_waitcnt lgkmcnt(" #n ")" ::: "memory")
; #define BAR __builtin_amdgcn_s_barrier()
; #define SCHED __builtin_amdgcn_sched_barrier(0)
; template <int EPI>
; __device__ __forceinline__ void gemm_tile(const GemmArgs& g, int brow, int bcol, int parity, bool first, bool nvalid, int nbrow, int nbcol) {
;     ...
;     BAR; WAIT_L(0); MMA(1, 0, At, B0); BAR; SCHED;
;     STAGE_B(SB(1, 1), bcol + HALF, t + 3);
;     WAIT_V(6); BAR; MMA(1, 1, At, B1); BAR; SCHED;
;   }
;   { LDB(B0, 0, 0); LDA(At, 0, 0); STAGE_A(SA(1, 1), brow + HALF, nt - 1);
;     BAR; WAIT_L(0); MMA(0, 0, At, B0); BAR;
	ds_read_b128 v[180:183], v147 offset:49152
	ds_read_b128 v[184:187], v147 offset:50176
	ds_read_b128 v[188:191], v146 offset:49152
	ds_read_b128 v[192:195], v146 offset:50176
	ds_read_b128 v[196:199], v145 offset:49152
	ds_read_b128 v[202:205], v145 offset:50176
	ds_read_b128 v[206:209], v144 offset:49152
	ds_read_b128 v[216:219], v144 offset:50176
	s_mov_b64 s[2:3], 0x900180
	v_lshl_add_u64 v[222:223], v[212:213], 0, s[2:3]
	v_readfirstlane_b32 s2, v150
	s_mov_b32 m0, s2
	s_mov_b64 s[2:3], 0x920180
	global_load_lds_dwordx4 v[222:223], off
	v_lshl_add_u64 v[222:223], v[212:213], 0, s[2:3]
	v_readfirstlane_b32 s2, v151
	s_mov_b32 m0, s2
	s_nop 0
	global_load_lds_dwordx4 v[222:223], off
	v_readfirstlane_b32 s2, v152
	v_lshl_add_u64 v[222:223], v[210:211], 0, s[50:51]
	s_mov_b32 m0, s2
	v_readfirstlane_b32 s2, v153
	global_load_lds_dwordx4 v[222:223], off
	v_lshl_add_u64 v[210:211], v[210:211], 0, s[52:53]
	s_mov_b32 m0, s2
	s_nop 0
	global_load_lds_dwordx4 v[210:211], off
	s_mov_b64 s[2:3], 0x940180
	v_lshl_add_u64 v[244:245], v[212:213], 0, s[2:3]
	v_readfirstlane_b32 s2, v155
	s_mov_b32 m0, s2
	s_mov_b64 s[2:3], 0x960180
	global_load_lds_dwordx4 v[244:245], off
	v_lshl_add_u64 v[244:245], v[212:213], 0, s[2:3]
	v_readfirstlane_b32 s2, v156
	s_mov_b32 m0, s2
	s_nop 0
	global_load_lds_dwordx4 v[244:245], off
	s_waitcnt vmcnt(8)
	s_barrier
	s_waitcnt lgkmcnt(0)
	v_mfma_f32_16x16x32_bf16 v[62:65], v[164:167], v[180:183], v[62:65]
	v_mfma_f32_16x16x32_bf16 v[58:61], v[172:175], v[180:183], v[58:61]
	v_mfma_f32_16x16x32_bf16 v[54:57], v[164:167], v[188:191], v[54:57]
	v_mfma_f32_16x16x32_bf16 v[50:53], v[172:175], v[188:191], v[50:53]
	v_mfma_f32_16x16x32_bf16 v[46:49], v[164:167], v[196:199], v[46:49]
	v_mfma_f32_16x16x32_bf16 v[42:45], v[172:175], v[196:199], v[42:45]
	v_mfma_f32_16x16x32_bf16 v[38:41], v[164:167], v[206:209], v[38:41]
	v_mfma_f32_16x16x32_bf16 v[34:37], v[172:175], v[206:209], v[34:37]
	v_mfma_f32_16x16x32_bf16 v[62:65], v[168:171], v[184:187], v[62:65]
	v_mfma_f32_16x16x32_bf16 v[58:61], v[176:179], v[184:187], v[58:61]
	v_mfma_f32_16x16x32_bf16 v[54:57], v[168:171], v[192:195], v[54:57]
	v_mfma_f32_16x16x32_bf16 v[50:53], v[176:179], v[192:195], v[50:53]
	v_mfma_f32_16x16x32_bf16 v[46:49], v[168:171], v[202:205], v[46:49]
	v_mfma_f32_16x16x32_bf16 v[42:45], v[176:179], v[202:205], v[42:45]
	v_mfma_f32_16x16x32_bf16 v[38:41], v[168:171], v[216:219], v[38:41]
	v_mfma_f32_16x16x32_bf16 v[34:37], v[176:179], v[216:219], v[34:37]
	v_mfma_f32_16x16x32_bf16 v[30:33], v[228:231], v[180:183], v[30:33]
	v_mfma_f32_16x16x32_bf16 v[26:29], v[236:239], v[180:183], v[26:29]
	v_mfma_f32_16x16x32_bf16 v[22:25], v[228:231], v[188:191], v[22:25]
	v_mfma_f32_16x16x32_bf16 v[18:21], v[236:239], v[188:191], v[18:21]
	v_mfma_f32_16x16x32_bf16 v[14:17], v[228:231], v[196:199], v[14:17]
	v_mfma_f32_16x16x32_bf16 v[10:13], v[236:239], v[196:199], v[10:13]
	v_mfma_f32_16x16x32_bf16 v[6:9], v[228:231], v[206:209], v[6:9]
	v_mfma_f32_16x16x32_bf16 v[2:5], v[236:239], v[206:209], v[2:5]
	v_mfma_f32_16x16x32_bf16 v[30:33], v[232:235], v[184:187], v[30:33]
	v_mfma_f32_16x16x32_bf16 v[26:29], v[240:243], v[184:187], v[26:29]
	v_mfma_f32_16x16x32_bf16 v[22:25], v[232:235], v[192:195], v[22:25]
	v_mfma_f32_16x16x32_bf16 v[18:21], v[240:243], v[192:195], v[18:21]
	v_mfma_f32_16x16x32_bf16 v[14:17], v[232:235], v[202:205], v[14:17]
	v_mfma_f32_16x16x32_bf16 v[10:13], v[240:243], v[202:205], v[10:13]
	v_mfma_f32_16x16x32_bf16 v[6:9], v[232:235], v[216:219], v[6:9]
	v_mfma_f32_16x16x32_bf16 v[2:5], v[240:243], v[216:219], v[2:5]
	s_add_i32 s15, s15, 2
	s_add_u32 s0, s0, 0x100
	s_addc_u32 s1, s1, 0
	s_add_u32 s12, s12, 0x100
	s_addc_u32 s13, s13, 0
	s_cmp_lt_u32 s15, 12
	s_cbranch_scc1 .LBB0_90
	s_barrier
	s_or_b32 s0, s38, 0x80
	s_ashr_i32 s1, s0, 31
	s_lshl_b64 s[0:1], s[0:1], 11
	s_add_u32 s0, s80, s0
	s_addc_u32 s1, s81, s1
	v_lshl_add_u64 v[130:131], s[0:1], 0, v[0:1]
	s_mov_b64 s[0:1], 0x780
	ds_read_b128 v[150:153], v157
	ds_read_b128 v[164:167], v157 offset:1024
	ds_read_b128 v[168:171], v157 offset:2048
	ds_read_b128 v[172:175], v157 offset:3072
	ds_read_b128 v[176:179], v147
	ds_read_b128 v[180:183], v147 offset:1024
	ds_read_b128 v[184:187], v146
	ds_read_b128 v[188:191], v146 offset:1024
	ds_read_b128 v[192:195], v145
	ds_read_b128 v[196:199], v145 offset:1024
	ds_read_b128 v[202:205], v144
	ds_read_b128 v[206:209], v144 offset:1024
	v_lshl_add_u64 v[156:157], v[130:131], 0, s[0:1]
	v_readfirstlane_b32 s0, v161
	s_mov_b32 m0, s0
	s_mov_b64 s[0:1], 0x20780
	v_lshl_add_u64 v[130:131], v[130:131], 0, s[0:1]
	v_readfirstlane_b32 s0, v162
	global_load_lds_dwordx4 v[156:157], off
	s_mov_b32 m0, s0
	s_nop 0
	global_load_lds_dwordx4 v[130:131], off
	s_waitcnt vmcnt(8)
	s_barrier
	s_waitcnt lgkmcnt(0)
	s_setprio 1
	s_waitcnt lgkmcnt(0)
	v_mfma_f32_16x16x32_bf16 v[126:129], v[150:153], v[176:179], v[126:129]
	v_mfma_f32_16x16x32_bf16 v[118:121], v[150:153], v[184:187], v[118:121]
	v_mfma_f32_16x16x32_bf16 v[110:113], v[150:153], v[192:195], v[110:113]
	v_mfma_f32_16x16x32_bf16 v[102:105], v[150:153], v[202:205], v[102:105]
	v_mfma_f32_16x16x32_bf16 v[126:129], v[164:167], v[180:183], v[126:129]
	v_mfma_f32_16x16x32_bf16 v[122:125], v[168:171], v[176:179], v[122:125]
	v_mfma_f32_16x16x32_bf16 v[118:121], v[164:167], v[188:191], v[118:121]
	v_mfma_f32_16x16x32_bf16 v[114:117], v[168:171], v[184:187], v[114:117]
	v_mfma_f32_16x16x32_bf16 v[110:113], v[164:167], v[196:199], v[110:113]
	v_mfma_f32_16x16x32_bf16 v[106:109], v[168:171], v[192:195], v[106:109]
	v_mfma_f32_16x16x32_bf16 v[102:105], v[164:167], v[206:209], v[102:105]
	v_mfma_f32_16x16x32_bf16 v[98:101], v[168:171], v[202:205], v[98:101]
	v_mfma_f32_16x16x32_bf16 v[216:219], v[172:175], v[180:183], v[122:125]
	v_mfma_f32_16x16x32_bf16 v[228:231], v[172:175], v[188:191], v[114:117]
	v_mfma_f32_16x16x32_bf16 v[232:235], v[172:175], v[196:199], v[106:109]
	v_mfma_f32_16x16x32_bf16 v[236:239], v[172:175], v[206:209], v[98:101]
	s_setprio 0
	s_barrier
; #define LDA(dst, b, h) for (int m = 0; m < 4; ++m) for (int k = 0; k < 2; ++k) \
;     dst[m][k] = *reinterpret_cast<const bf16x8*>((char*)SA(b, h) + lds_byte(wr * 64 + m * 16 + fr, k * 32 + fq * 8))
; #define LDB(dst, b, h) for (int n = 0; n < 2; ++n) for (int k = 0; k < 2; ++k) \
;     dst[n][k] = *reinterpret_cast<const bf16x8*>((char*)SB(b, h) + lds_byte(wc * 32 + n * 16 + fr, k * 32 + fq * 8))
; #define MMA(ai, bj, At_, Bt_) do { __builtin_amdgcn_s_setprio(1); \
;     for (int m = 0; m < 4; ++m) for (int n = 0; n < 2; ++n) for (int k = 0; k < 2; ++k) \
;       acc[ai][bj][m][n] = __builtin_amdgcn_mfma_f32_16x16x32_bf16(At_[m][k], Bt_[n][k], acc[ai][bj][m][n], 0, 0, 0); \
;     __builtin_amdgcn_s_setprio(0); } while (0)
; #define WAIT_V(n) asm volatile("s_waitcnt vmcnt(" #n ")" ::: "memory")
; #define WAIT_L(n) asm volatile("s_waitcnt lgkmcnt(" #n ")" ::: "memory")
; #define BAR __builtin_amdgcn_s_barrier()
; #define SCHED __builtin_amdgcn_sched_barrier(0)
; template <int EPI>
; __device__ __forceinline__ void gemm_tile(const GemmArgs& g, int brow, int bcol, int parity, bool first, bool nvalid, int nbrow, int nbcol) {
;     ...
;     BAR; WAIT_L(0); MMA(0, 0, At, B0); BAR;
;     LDB(B1, 0, 1); BAR; WAIT_L(0); MMA(0, 1, At, B1); BAR; SCHED;
;     LDA(At, 0, 1); WAIT_V(4); BAR; WAIT_L(0); MMA(1, 0, At, B0); MMA(1, 1, At, B1); BAR; }
;   { LDB(B0, 1, 0); LDA(At, 1, 0); WAIT_V(2); BAR; WAIT_L(0); MMA(0, 0, At, B0); BAR;
	s_nop 1
	ds_read_b128 v[98:101], v154
	ds_read_b128 v[106:109], v154 offset:1024
	ds_read_b128 v[114:117], v154 offset:2048
	ds_read_b128 v[122:125], v154 offset:3072
	s_barrier
	s_waitcnt lgkmcnt(0)
	s_setprio 1
	s_waitcnt lgkmcnt(0)
	v_mfma_f32_16x16x32_bf16 v[94:97], v[98:101], v[176:179], v[94:97]
	v_mfma_f32_16x16x32_bf16 v[86:89], v[98:101], v[184:187], v[86:89]
	v_mfma_f32_16x16x32_bf16 v[78:81], v[98:101], v[192:195], v[78:81]
	v_mfma_f32_16x16x32_bf16 v[70:73], v[98:101], v[202:205], v[70:73]
	v_mfma_f32_16x16x32_bf16 v[94:97], v[106:109], v[180:183], v[94:97]
	v_mfma_f32_16x16x32_bf16 v[90:93], v[114:117], v[176:179], v[90:93]
	v_mfma_f32_16x16x32_bf16 v[86:89], v[106:109], v[188:191], v[86:89]
	v_mfma_f32_16x16x32_bf16 v[82:85], v[114:117], v[184:187], v[82:85]
	v_mfma_f32_16x16x32_bf16 v[78:81], v[106:109], v[196:199], v[78:81]
	v_mfma_f32_16x16x32_bf16 v[74:77], v[114:117], v[192:195], v[74:77]
	v_mfma_f32_16x16x32_bf16 v[70:73], v[106:109], v[206:209], v[70:73]
	v_mfma_f32_16x16x32_bf16 v[66:69], v[114:117], v[202:205], v[66:69]
	v_mfma_f32_16x16x32_bf16 v[154:157], v[122:125], v[180:183], v[90:93]
	v_mfma_f32_16x16x32_bf16 v[176:179], v[122:125], v[188:191], v[82:85]
	v_mfma_f32_16x16x32_bf16 v[180:183], v[122:125], v[196:199], v[74:77]
	v_mfma_f32_16x16x32_bf16 v[184:187], v[122:125], v[206:209], v[66:69]
	s_setprio 0
	s_barrier
	s_nop 1
	ds_read_b128 v[66:69], v147 offset:16384
	ds_read_b128 v[74:77], v147 offset:17408
	ds_read_b128 v[82:85], v146 offset:16384
	ds_read_b128 v[90:93], v146 offset:17408
	ds_read_b128 v[188:191], v145 offset:16384
	ds_read_b128 v[192:195], v145 offset:17408
	ds_read_b128 v[196:199], v144 offset:16384
	ds_read_b128 v[202:205], v144 offset:17408
	s_waitcnt vmcnt(4)
	s_barrier
	s_waitcnt lgkmcnt(0)
	s_setprio 1
	s_waitcnt lgkmcnt(0)
	v_mfma_f32_16x16x32_bf16 v[62:65], v[150:153], v[66:69], v[62:65]
	v_mfma_f32_16x16x32_bf16 v[54:57], v[150:153], v[82:85], v[54:57]
	v_mfma_f32_16x16x32_bf16 v[46:49], v[150:153], v[188:191], v[46:49]
	v_mfma_f32_16x16x32_bf16 v[38:41], v[150:153], v[196:199], v[38:41]
	v_mfma_f32_16x16x32_bf16 v[62:65], v[164:167], v[74:77], v[62:65]
	v_mfma_f32_16x16x32_bf16 v[58:61], v[168:171], v[66:69], v[58:61]
	v_mfma_f32_16x16x32_bf16 v[54:57], v[164:167], v[90:93], v[54:57]
	v_mfma_f32_16x16x32_bf16 v[50:53], v[168:171], v[82:85], v[50:53]
	v_mfma_f32_16x16x32_bf16 v[46:49], v[164:167], v[192:195], v[46:49]
	v_mfma_f32_16x16x32_bf16 v[42:45], v[168:171], v[188:191], v[42:45]
	v_mfma_f32_16x16x32_bf16 v[38:41], v[164:167], v[202:205], v[38:41]
	v_mfma_f32_16x16x32_bf16 v[34:37], v[168:171], v[196:199], v[34:37]
	v_mfma_f32_16x16x32_bf16 v[206:209], v[172:175], v[74:77], v[58:61]
	v_mfma_f32_16x16x32_bf16 v[240:243], v[172:175], v[90:93], v[50:53]
	v_mfma_f32_16x16x32_bf16 v[244:247], v[172:175], v[192:195], v[42:45]
	v_mfma_f32_16x16x32_bf16 v[150:153], v[172:175], v[202:205], v[34:37]
	s_setprio 0
	s_setprio 1
	v_mfma_f32_16x16x32_bf16 v[30:33], v[98:101], v[66:69], v[30:33]
	v_mfma_f32_16x16x32_bf16 v[22:25], v[98:101], v[82:85], v[22:25]
	v_mfma_f32_16x16x32_bf16 v[14:17], v[98:101], v[188:191], v[14:17]
	v_mfma_f32_16x16x32_bf16 v[6:9], v[98:101], v[196:199], v[6:9]
	v_mfma_f32_16x16x32_bf16 v[30:33], v[106:109], v[74:77], v[30:33]
	v_mfma_f32_16x16x32_bf16 v[26:29], v[114:117], v[66:69], v[26:29]
	v_mfma_f32_16x16x32_bf16 v[22:25], v[106:109], v[90:93], v[22:25]
	v_mfma_f32_16x16x32_bf16 v[18:21], v[114:117], v[82:85], v[18:21]
	v_mfma_f32_16x16x32_bf16 v[14:17], v[106:109], v[192:195], v[14:17]
	v_mfma_f32_16x16x32_bf16 v[10:13], v[114:117], v[188:191], v[10:13]
	v_mfma_f32_16x16x32_bf16 v[6:9], v[106:109], v[202:205], v[6:9]
	v_mfma_f32_16x16x32_bf16 v[2:5], v[114:117], v[196:199], v[2:5]
	v_mfma_f32_16x16x32_bf16 v[162:165], v[122:125], v[74:77], v[26:29]
	v_mfma_f32_16x16x32_bf16 v[166:169], v[122:125], v[90:93], v[18:21]
	v_mfma_f32_16x16x32_bf16 v[170:173], v[122:125], v[192:195], v[10:13]
	v_mfma_f32_16x16x32_bf16 v[188:191], v[122:125], v[202:205], v[2:5]
	s_setprio 0
	s_barrier
	s_nop 1
	ds_read_b128 v[2:5], v149
	ds_read_b128 v[10:13], v149 offset:1024
	ds_read_b128 v[18:21], v149 offset:2048
	ds_read_b128 v[26:29], v149 offset:3072
	ds_read_b128 v[34:37], v147 offset:32768
	ds_read_b128 v[42:45], v147 offset:33792
	ds_read_b128 v[50:53], v146 offset:32768
	ds_read_b128 v[58:61], v146 offset:33792
	ds_read_b128 v[66:69], v145 offset:32768
	ds_read_b128 v[192:195], v145 offset:33792
	ds_read_b128 v[196:199], v144 offset:32768
	ds_read_b128 v[202:205], v144 offset:33792
	s_waitcnt vmcnt(2)
	s_barrier
; #define LDA(dst, b, h) for (int m = 0; m < 4; ++m) for (int k = 0; k < 2; ++k) \
;     dst[m][k] = *reinterpret_cast<const bf16x8*>((char*)SA(b, h) + lds_byte(wr * 64 + m * 16 + fr, k * 32 + fq * 8))
; #define LDB(dst, b, h) for (int n = 0; n < 2; ++n) for (int k = 0; k < 2; ++k) \
;     dst[n][k] = *reinterpret_cast<const bf16x8*>((char*)SB(b, h) + lds_byte(wc * 32 + n * 16 + fr, k * 32 + fq * 8))
; #define MMA(ai, bj, At_, Bt_) do { __builtin_amdgcn_s_setprio(1); \
;     for (int m = 0; m < 4; ++m) for (int n = 0; n < 2; ++n) for (int k = 0; k < 2; ++k) \
;       acc[ai][bj][m][n] = __builtin_amdgcn_mfma_f32_16x16x32_bf16(At_[m][k], Bt_[n][k], acc[ai][bj][m][n], 0, 0, 0); \
;     __builtin_amdgcn_s_setprio(0); } while (0)
; #define WAIT_V(n) asm volatile("s_waitcnt vmcnt(" #n ")" ::: "memory")
; #define WAIT_L(n) asm volatile("s_waitcnt lgkmcnt(" #n ")" ::: "memory")
; #define BAR __builtin_amdgcn_s_barrier()
; #define SCHED __builtin_amdgcn_sched_barrier(0)
; template <int EPI>
; __device__ __forceinline__ void gemm_tile(const GemmArgs& g, int brow, int bcol, int parity, bool first, bool nvalid, int nbrow, int nbcol) {
;     ...
;   { LDB(B0, 1, 0); LDA(At, 1, 0); WAIT_V(2); BAR; WAIT_L(0); MMA(0, 0, At, B0); BAR;
;     LDB(B1, 1, 1); WAIT_V(0); BAR; WAIT_L(0); MMA(0, 1, At, B1); BAR; SCHED;
;     LDA(At, 1, 1); BAR; WAIT_L(0); MMA(1, 0, At, B0); MMA(1, 1, At, B1); BAR; }
;   if (wr == 0) BAR;
	s_waitcnt lgkmcnt(0)
	s_setprio 1
	s_waitcnt lgkmcnt(0)
	v_mfma_f32_16x16x32_bf16 v[74:77], v[2:5], v[34:37], v[126:129]
	v_mfma_f32_16x16x32_bf16 v[122:125], v[10:13], v[42:45], v[74:77]
	v_mfma_f32_16x16x32_bf16 v[74:77], v[18:21], v[34:37], v[216:219]
	v_mfma_f32_16x16x32_bf16 v[126:129], v[26:29], v[42:45], v[74:77]
	v_mfma_f32_16x16x32_bf16 v[74:77], v[2:5], v[50:53], v[118:121]
	v_mfma_f32_16x16x32_bf16 v[114:117], v[10:13], v[58:61], v[74:77]
	v_mfma_f32_16x16x32_bf16 v[74:77], v[18:21], v[50:53], v[228:231]
	v_mfma_f32_16x16x32_bf16 v[118:121], v[26:29], v[58:61], v[74:77]
	v_mfma_f32_16x16x32_bf16 v[74:77], v[2:5], v[66:69], v[110:113]
	v_mfma_f32_16x16x32_bf16 v[106:109], v[10:13], v[192:195], v[74:77]
	v_mfma_f32_16x16x32_bf16 v[74:77], v[18:21], v[66:69], v[232:235]
	v_mfma_f32_16x16x32_bf16 v[110:113], v[26:29], v[192:195], v[74:77]
	v_mfma_f32_16x16x32_bf16 v[74:77], v[2:5], v[196:199], v[102:105]
	v_mfma_f32_16x16x32_bf16 v[98:101], v[10:13], v[202:205], v[74:77]
	v_mfma_f32_16x16x32_bf16 v[74:77], v[18:21], v[196:199], v[236:239]
	v_mfma_f32_16x16x32_bf16 v[102:105], v[26:29], v[202:205], v[74:77]
	s_setprio 0
	s_barrier
	ds_read_b128 v[216:219], v148
	ds_read_b128 v[228:231], v148 offset:1024
	ds_read_b128 v[232:235], v148 offset:2048
	ds_read_b128 v[236:239], v148 offset:3072
	s_waitcnt vmcnt(0)
	s_barrier
	s_waitcnt lgkmcnt(0)
	s_setprio 1
	s_waitcnt lgkmcnt(0)
	v_mfma_f32_16x16x32_bf16 v[74:77], v[216:219], v[34:37], v[94:97]
	v_mfma_f32_16x16x32_bf16 v[34:37], v[232:235], v[34:37], v[154:157]
	v_mfma_f32_16x16x32_bf16 v[94:97], v[236:239], v[42:45], v[34:37]
	v_mfma_f32_16x16x32_bf16 v[34:37], v[216:219], v[50:53], v[86:89]
	v_mfma_f32_16x16x32_bf16 v[82:85], v[228:231], v[58:61], v[34:37]
	v_mfma_f32_16x16x32_bf16 v[34:37], v[232:235], v[50:53], v[176:179]
	v_mfma_f32_16x16x32_bf16 v[86:89], v[236:239], v[58:61], v[34:37]
	v_mfma_f32_16x16x32_bf16 v[34:37], v[216:219], v[66:69], v[78:81]
	v_mfma_f32_16x16x32_bf16 v[90:93], v[228:231], v[42:45], v[74:77]
	v_mfma_f32_16x16x32_bf16 v[74:77], v[228:231], v[192:195], v[34:37]
	v_mfma_f32_16x16x32_bf16 v[34:37], v[232:235], v[66:69], v[180:183]
	v_mfma_f32_16x16x32_bf16 v[78:81], v[236:239], v[192:195], v[34:37]
	v_mfma_f32_16x16x32_bf16 v[34:37], v[216:219], v[196:199], v[70:73]
	v_mfma_f32_16x16x32_bf16 v[66:69], v[228:231], v[202:205], v[34:37]
	v_mfma_f32_16x16x32_bf16 v[34:37], v[232:235], v[196:199], v[184:187]
	v_mfma_f32_16x16x32_bf16 v[70:73], v[236:239], v[202:205], v[34:37]
	s_setprio 0
	s_barrier
	ds_read_b128 v[154:157], v147 offset:49152
	ds_read_b128 v[174:177], v147 offset:50176
	ds_read_b128 v[178:181], v146 offset:49152
	ds_read_b128 v[146:149], v146 offset:50176
	ds_read_b128 v[182:185], v145 offset:49152
	ds_read_b128 v[192:195], v145 offset:50176
	ds_read_b128 v[196:199], v144 offset:49152
	ds_read_b128 v[202:205], v144 offset:50176
	s_barrier
	s_waitcnt lgkmcnt(0)
	s_setprio 1
	s_waitcnt lgkmcnt(0)
	v_mfma_f32_16x16x32_bf16 v[34:37], v[2:5], v[154:157], v[62:65]
	v_mfma_f32_16x16x32_bf16 v[58:61], v[10:13], v[174:177], v[34:37]
	v_mfma_f32_16x16x32_bf16 v[34:37], v[18:21], v[154:157], v[206:209]
	v_mfma_f32_16x16x32_bf16 v[62:65], v[26:29], v[174:177], v[34:37]
	v_mfma_f32_16x16x32_bf16 v[34:37], v[2:5], v[178:181], v[54:57]
	v_mfma_f32_16x16x32_bf16 v[50:53], v[10:13], v[146:149], v[34:37]
	v_mfma_f32_16x16x32_bf16 v[34:37], v[18:21], v[178:181], v[240:243]
	v_mfma_f32_16x16x32_bf16 v[54:57], v[26:29], v[146:149], v[34:37]
	v_mfma_f32_16x16x32_bf16 v[34:37], v[2:5], v[182:185], v[46:49]
	v_mfma_f32_16x16x32_bf16 v[42:45], v[10:13], v[192:195], v[34:37]
	v_mfma_f32_16x16x32_bf16 v[34:37], v[18:21], v[182:185], v[244:247]
	v_mfma_f32_16x16x32_bf16 v[2:5], v[2:5], v[196:199], v[38:41]
	v_mfma_f32_16x16x32_bf16 v[46:49], v[26:29], v[192:195], v[34:37]
	v_mfma_f32_16x16x32_bf16 v[34:37], v[10:13], v[202:205], v[2:5]
	v_mfma_f32_16x16x32_bf16 v[2:5], v[18:21], v[196:199], v[150:153]
	v_mfma_f32_16x16x32_bf16 v[38:41], v[26:29], v[202:205], v[2:5]
	s_setprio 0
	s_setprio 1
	v_mfma_f32_16x16x32_bf16 v[2:5], v[216:219], v[154:157], v[30:33]
	v_mfma_f32_16x16x32_bf16 v[26:29], v[228:231], v[174:177], v[2:5]
	v_mfma_f32_16x16x32_bf16 v[2:5], v[232:235], v[154:157], v[162:165]
	v_mfma_f32_16x16x32_bf16 v[30:33], v[236:239], v[174:177], v[2:5]
	v_mfma_f32_16x16x32_bf16 v[2:5], v[216:219], v[178:181], v[22:25]
	v_mfma_f32_16x16x32_bf16 v[18:21], v[228:231], v[146:149], v[2:5]
	v_mfma_f32_16x16x32_bf16 v[2:5], v[232:235], v[178:181], v[166:169]
	v_mfma_f32_16x16x32_bf16 v[22:25], v[236:239], v[146:149], v[2:5]
	v_mfma_f32_16x16x32_bf16 v[2:5], v[216:219], v[182:185], v[14:17]
	v_mfma_f32_16x16x32_bf16 v[10:13], v[228:231], v[192:195], v[2:5]
	v_mfma_f32_16x16x32_bf16 v[2:5], v[232:235], v[182:185], v[170:173]
	v_mfma_f32_16x16x32_bf16 v[14:17], v[236:239], v[192:195], v[2:5]
	v_mfma_f32_16x16x32_bf16 v[2:5], v[216:219], v[196:199], v[6:9]
	v_mfma_f32_16x16x32_bf16 v[6:9], v[232:235], v[196:199], v[188:191]
	v_mfma_f32_16x16x32_bf16 v[2:5], v[228:231], v[202:205], v[2:5]
	v_mfma_f32_16x16x32_bf16 v[6:9], v[236:239], v[202:205], v[6:9]
	s_setprio 0
	s_movk_i32 s0, 0x100
	v_cmp_gt_u32_e32 vcc, s0, v138
	s_barrier
	s_and_saveexec_b64 s[0:1], vcc
	s_cbranch_execz .LBB0_93
	s_barrier

; #define STAGE_B(P, br, kt) do { const char* _gb = (const char*)(Bt + ((long)(br) * K + (long)(kt) * BK)); \
;     __builtin_amdgcn_global_load_lds((const unsigned*)(_gb + bofl0), (unsigned*)((char*)(P) + gtid_ * 16), 16, 0, 0); \
;     __builtin_amdgcn_global_load_lds((const unsigned*)(_gb + (long)K * 128 + bofl0), (unsigned*)((char*)(P) + gtid_ * 16 + 8192), 16, 0, 0); } while (0)
; #define LDA(dst, b, h) for (int m = 0; m < 4; ++m) for (int k = 0; k < 2; ++k) \
;     dst[m][k] = *reinterpret_cast<const bf16x8*>((char*)SA(b, h) + lds_byte(wr * 64 + m * 16 + fr, k * 32 + fq * 8))
; #define LDB(dst, b, h) for (int n = 0; n < 2; ++n) for (int k = 0; k < 2; ++k) \
;     dst[n][k] = *reinterpret_cast<const bf16x8*>((char*)SB(b, h) + lds_byte(wc * 32 + n * 16 + fr, k * 32 + fq * 8))
; #define MMA(ai, bj, At_, Bt_) do { __builtin_amdgcn_s_setprio(1); \
;     for (int m = 0; m < 4; ++m) for (int n = 0; n < 2; ++n) for (int k = 0; k < 2; ++k) \
;       acc[ai][bj][m][n] = __builtin_amdgcn_mfma_f32_16x16x32_bf16(At_[m][k], Bt_[n][k], acc[ai][bj][m][n], 0, 0, 0); \
;     __builtin_amdgcn_s_setprio(0); } while (0)
; #define WAIT_V(n) asm volatile("s_waitcnt vmcnt(" #n ")" ::: "memory")
; #define WAIT_L(n) asm volatile("s_waitcnt lgkmcnt(" #n ")" ::: "memory")
; #define BAR __builtin_amdgcn_s_barrier()
; #define SCHED __builtin_amdgcn_sched_barrier(0)
; template <int EPI>
; __device__ __forceinline__ void gemm_tile(const GemmArgs& g, int brow, int bcol, int parity, bool first, bool nvalid, int nbrow, int nbcol) {
;     ...
;   for (int t = 0; t < nt - 2; t += 2) {
;     LDB(B0, 0, 0); SCHED; LDA(At, 0, 0); STAGE_A(SA(1, 1), brow + HALF, t + 1);
;     WAIT_L(8); BAR; WAIT_L(0); MMA(0, 0, At, B0); BAR; SCHED;
;     LDB(B1, 0, 1); STAGE_B(SB(0, 0), bcol, t + 2);
;     BAR; WAIT_L(0); MMA(0, 1, At, B1); BAR; SCHED;
;     LDA(At, 0, 1); STAGE_A(SA(0, 0), brow, t + 2);
;     BAR; WAIT_L(0); MMA(1, 0, At, B0); BAR; SCHED;
;     STAGE_B(SB(0, 1), bcol + HALF, t + 2);
;     WAIT_V(6); BAR; MMA(1, 1, At, B1); BAR; SCHED;
;     LDB(B0, 1, 0); SCHED; LDA(At, 1, 0); STAGE_A(SA(0, 1), brow + HALF, t + 2);
;     WAIT_L(8); BAR; WAIT_L(0); MMA(0, 0, At, B0); BAR; SCHED;
.LBB0_133:
	s_barrier
	ds_read_b128 v[164:167], v157
	ds_read_b128 v[168:171], v157 offset:1024
	ds_read_b128 v[172:175], v157 offset:2048
	ds_read_b128 v[176:179], v157 offset:3072
	ds_read_b128 v[180:183], v146
	ds_read_b128 v[184:187], v146 offset:1024
	ds_read_b128 v[188:191], v145
	ds_read_b128 v[192:195], v145 offset:1024
	ds_read_b128 v[196:199], v144
	ds_read_b128 v[202:205], v144 offset:1024
	ds_read_b128 v[206:209], v143
	ds_read_b128 v[216:219], v143 offset:1024
	s_waitcnt lgkmcnt(6)
	ds_read_b128 v[222:225], v154
	ds_read_b128 v[228:231], v154 offset:1024
	ds_read_b128 v[232:235], v154 offset:2048
	ds_read_b128 v[236:239], v154 offset:3072
	v_add_u32_e32 v161, 0xc000, v137
	v_lshl_add_u64 v[210:211], s[12:13], 0, v[130:131]
	v_readfirstlane_b32 s2, v161
	v_add_u32_e32 v162, 0xe000, v137
	v_lshl_add_u64 v[158:159], v[210:211], 0, s[24:25]
	s_mov_b32 m0, s2
	v_readfirstlane_b32 s2, v162
	global_load_lds_dwordx4 v[158:159], off
	v_lshl_add_u64 v[158:159], v[210:211], 0, s[34:35]
	s_mov_b32 m0, s2
	s_nop 0
	global_load_lds_dwordx4 v[158:159], off
	s_waitcnt vmcnt(8)
	s_barrier
	s_waitcnt lgkmcnt(0)
	v_mfma_f32_16x16x32_bf16 v[126:129], v[180:183], v[164:167], v[126:129]
	v_mfma_f32_16x16x32_bf16 v[122:125], v[180:183], v[172:175], v[122:125]
	v_mfma_f32_16x16x32_bf16 v[118:121], v[188:191], v[164:167], v[118:121]
	v_mfma_f32_16x16x32_bf16 v[114:117], v[188:191], v[172:175], v[114:117]
	v_mfma_f32_16x16x32_bf16 v[110:113], v[196:199], v[164:167], v[110:113]
	v_mfma_f32_16x16x32_bf16 v[106:109], v[196:199], v[172:175], v[106:109]
	v_mfma_f32_16x16x32_bf16 v[102:105], v[206:209], v[164:167], v[102:105]
	v_mfma_f32_16x16x32_bf16 v[98:101], v[206:209], v[172:175], v[98:101]
	v_mfma_f32_16x16x32_bf16 v[126:129], v[184:187], v[168:171], v[126:129]
	v_mfma_f32_16x16x32_bf16 v[122:125], v[184:187], v[176:179], v[122:125]
	v_mfma_f32_16x16x32_bf16 v[118:121], v[192:195], v[168:171], v[118:121]
	v_mfma_f32_16x16x32_bf16 v[114:117], v[192:195], v[176:179], v[114:117]
	v_mfma_f32_16x16x32_bf16 v[110:113], v[202:205], v[168:171], v[110:113]
	v_mfma_f32_16x16x32_bf16 v[106:109], v[202:205], v[176:179], v[106:109]
	v_mfma_f32_16x16x32_bf16 v[102:105], v[216:219], v[168:171], v[102:105]
	v_mfma_f32_16x16x32_bf16 v[98:101], v[216:219], v[176:179], v[98:101]
	v_mfma_f32_16x16x32_bf16 v[94:97], v[180:183], v[222:225], v[94:97]
	v_mfma_f32_16x16x32_bf16 v[90:93], v[180:183], v[232:235], v[90:93]
	v_mfma_f32_16x16x32_bf16 v[86:89], v[188:191], v[222:225], v[86:89]
	v_mfma_f32_16x16x32_bf16 v[82:85], v[188:191], v[232:235], v[82:85]
	v_mfma_f32_16x16x32_bf16 v[78:81], v[196:199], v[222:225], v[78:81]
	v_mfma_f32_16x16x32_bf16 v[74:77], v[196:199], v[232:235], v[74:77]
	v_mfma_f32_16x16x32_bf16 v[70:73], v[206:209], v[222:225], v[70:73]
	v_mfma_f32_16x16x32_bf16 v[66:69], v[206:209], v[232:235], v[66:69]
	v_mfma_f32_16x16x32_bf16 v[94:97], v[184:187], v[228:231], v[94:97]
	v_mfma_f32_16x16x32_bf16 v[90:93], v[184:187], v[236:239], v[90:93]
	v_mfma_f32_16x16x32_bf16 v[86:89], v[192:195], v[228:231], v[86:89]
	v_mfma_f32_16x16x32_bf16 v[82:85], v[192:195], v[236:239], v[82:85]
	v_mfma_f32_16x16x32_bf16 v[78:81], v[202:205], v[228:231], v[78:81]
	v_mfma_f32_16x16x32_bf16 v[74:77], v[202:205], v[236:239], v[74:77]
	v_mfma_f32_16x16x32_bf16 v[70:73], v[216:219], v[228:231], v[70:73]
	v_mfma_f32_16x16x32_bf16 v[66:69], v[216:219], v[236:239], v[66:69]
	s_barrier
	ds_read_b128 v[180:183], v146 offset:16384
	ds_read_b128 v[184:187], v146 offset:17408
	ds_read_b128 v[188:191], v145 offset:16384
	ds_read_b128 v[192:195], v145 offset:17408
	ds_read_b128 v[196:199], v144 offset:16384
	ds_read_b128 v[202:205], v144 offset:17408
	ds_read_b128 v[206:209], v143 offset:16384
	ds_read_b128 v[216:219], v143 offset:17408
	v_add_u32_e32 v158, s15, v141
	v_lshl_add_u64 v[212:213], s[0:1], 0, v[130:131]
	v_readfirstlane_b32 s2, v158
	v_add_u32_e32 v159, 0x2000, v158
	v_lshl_add_u64 v[240:241], v[212:213], 0, s[78:79]
	s_mov_b32 m0, s2
	v_readfirstlane_b32 s2, v159
	global_load_lds_dwordx4 v[240:241], off
	v_lshl_add_u64 v[240:241], v[212:213], 0, s[52:53]
	s_mov_b32 m0, s2
	s_nop 0
	global_load_lds_dwordx4 v[240:241], off
	v_readfirstlane_b32 s2, v137
	v_lshl_add_u64 v[240:241], v[210:211], 0, s[36:37]
	s_mov_b32 m0, s2
	v_readfirstlane_b32 s2, v136
	global_load_lds_dwordx4 v[240:241], off
	v_lshl_add_u64 v[240:241], v[210:211], 0, s[42:43]
	s_mov_b32 m0, s2
	s_nop 0
	global_load_lds_dwordx4 v[240:241], off
	v_readfirstlane_b32 s2, v135
	v_add_u32_e32 v160, 0x2000, v135
	v_lshl_add_u64 v[244:245], v[212:213], 0, s[56:57]
	s_mov_b32 m0, s2
	v_readfirstlane_b32 s2, v160
	global_load_lds_dwordx4 v[244:245], off
	v_lshl_add_u64 v[244:245], v[212:213], 0, s[66:67]
	s_mov_b32 m0, s2
	s_nop 0
	global_load_lds_dwordx4 v[244:245], off
	s_waitcnt vmcnt(8)
	s_barrier
; #define STAGE_B(P, br, kt) do { const char* _gb = (const char*)(Bt + ((long)(br) * K + (long)(kt) * BK)); \
;     __builtin_amdgcn_global_load_lds((const unsigned*)(_gb + bofl0), (unsigned*)((char*)(P) + gtid_ * 16), 16, 0, 0); \
;     __builtin_amdgcn_global_load_lds((const unsigned*)(_gb + (long)K * 128 + bofl0), (unsigned*)((char*)(P) + gtid_ * 16 + 8192), 16, 0, 0); } while (0)
; #define LDA(dst, b, h) for (int m = 0; m < 4; ++m) for (int k = 0; k < 2; ++k) \
;     dst[m][k] = *reinterpret_cast<const bf16x8*>((char*)SA(b, h) + lds_byte(wr * 64 + m * 16 + fr, k * 32 + fq * 8))
; #define LDB(dst, b, h) for (int n = 0; n < 2; ++n) for (int k = 0; k < 2; ++k) \
;     dst[n][k] = *reinterpret_cast<const bf16x8*>((char*)SB(b, h) + lds_byte(wc * 32 + n * 16 + fr, k * 32 + fq * 8))
; #define MMA(ai, bj, At_, Bt_) do { __builtin_amdgcn_s_setprio(1); \
;     for (int m = 0; m < 4; ++m) for (int n = 0; n < 2; ++n) for (int k = 0; k < 2; ++k) \
;       acc[ai][bj][m][n] = __builtin_amdgcn_mfma_f32_16x16x32_bf16(At_[m][k], Bt_[n][k], acc[ai][bj][m][n], 0, 0, 0); \
;     __builtin_amdgcn_s_setprio(0); } while (0)
; #define WAIT_V(n) asm volatile("s_waitcnt vmcnt(" #n ")" ::: "memory")
; #define WAIT_L(n) asm volatile("s_waitcnt lgkmcnt(" #n ")" ::: "memory")
; #define BAR __builtin_amdgcn_s_barrier()
; #define SCHED __builtin_amdgcn_sched_barrier(0)
; template <int EPI>
; __device__ __forceinline__ void gemm_tile(const GemmArgs& g, int brow, int bcol, int parity, bool first, bool nvalid, int nbrow, int nbcol) {
;     ...
;     WAIT_V(6); BAR; MMA(1, 1, At, B1); BAR; SCHED;
;     LDB(B0, 1, 0); SCHED; LDA(At, 1, 0); STAGE_A(SA(0, 1), brow + HALF, t + 2);
;     WAIT_L(8); BAR; WAIT_L(0); MMA(0, 0, At, B0); BAR; SCHED;
;     LDB(B1, 1, 1); STAGE_B(SB(1, 0), bcol, t + 3);
;     BAR; WAIT_L(0); MMA(0, 1, At, B1); BAR; SCHED;
;     LDA(At, 1, 1); STAGE_A(SA(1, 0), brow, t + 3);
;     BAR; WAIT_L(0); MMA(1, 0, At, B0); BAR; SCHED;
	s_waitcnt lgkmcnt(0)
	v_mfma_f32_16x16x32_bf16 v[62:65], v[180:183], v[164:167], v[62:65]
	v_mfma_f32_16x16x32_bf16 v[58:61], v[180:183], v[172:175], v[58:61]
	v_mfma_f32_16x16x32_bf16 v[54:57], v[188:191], v[164:167], v[54:57]
	v_mfma_f32_16x16x32_bf16 v[50:53], v[188:191], v[172:175], v[50:53]
	v_mfma_f32_16x16x32_bf16 v[46:49], v[196:199], v[164:167], v[46:49]
	v_mfma_f32_16x16x32_bf16 v[42:45], v[196:199], v[172:175], v[42:45]
	v_mfma_f32_16x16x32_bf16 v[38:41], v[206:209], v[164:167], v[38:41]
	v_mfma_f32_16x16x32_bf16 v[34:37], v[206:209], v[172:175], v[34:37]
	v_mfma_f32_16x16x32_bf16 v[62:65], v[184:187], v[168:171], v[62:65]
	v_mfma_f32_16x16x32_bf16 v[58:61], v[184:187], v[176:179], v[58:61]
	v_mfma_f32_16x16x32_bf16 v[54:57], v[192:195], v[168:171], v[54:57]
	v_mfma_f32_16x16x32_bf16 v[50:53], v[192:195], v[176:179], v[50:53]
	v_mfma_f32_16x16x32_bf16 v[46:49], v[202:205], v[168:171], v[46:49]
	v_mfma_f32_16x16x32_bf16 v[42:45], v[202:205], v[176:179], v[42:45]
	v_mfma_f32_16x16x32_bf16 v[38:41], v[216:219], v[168:171], v[38:41]
	v_mfma_f32_16x16x32_bf16 v[34:37], v[216:219], v[176:179], v[34:37]
	v_mfma_f32_16x16x32_bf16 v[30:33], v[180:183], v[222:225], v[30:33]
	v_mfma_f32_16x16x32_bf16 v[26:29], v[180:183], v[232:235], v[26:29]
	v_mfma_f32_16x16x32_bf16 v[22:25], v[188:191], v[222:225], v[22:25]
	v_mfma_f32_16x16x32_bf16 v[18:21], v[188:191], v[232:235], v[18:21]
	v_mfma_f32_16x16x32_bf16 v[14:17], v[196:199], v[222:225], v[14:17]
	v_mfma_f32_16x16x32_bf16 v[10:13], v[196:199], v[232:235], v[10:13]
	v_mfma_f32_16x16x32_bf16 v[6:9], v[206:209], v[222:225], v[6:9]
	v_mfma_f32_16x16x32_bf16 v[2:5], v[206:209], v[232:235], v[2:5]
	v_mfma_f32_16x16x32_bf16 v[30:33], v[184:187], v[228:231], v[30:33]
	v_mfma_f32_16x16x32_bf16 v[26:29], v[184:187], v[236:239], v[26:29]
	v_mfma_f32_16x16x32_bf16 v[22:25], v[192:195], v[228:231], v[22:25]
	v_mfma_f32_16x16x32_bf16 v[18:21], v[192:195], v[236:239], v[18:21]
	v_mfma_f32_16x16x32_bf16 v[14:17], v[202:205], v[228:231], v[14:17]
	v_mfma_f32_16x16x32_bf16 v[10:13], v[202:205], v[236:239], v[10:13]
	v_mfma_f32_16x16x32_bf16 v[6:9], v[216:219], v[228:231], v[6:9]
	v_mfma_f32_16x16x32_bf16 v[2:5], v[216:219], v[236:239], v[2:5]
	s_barrier
	ds_read_b128 v[164:167], v148
	ds_read_b128 v[168:171], v148 offset:1024
	ds_read_b128 v[172:175], v148 offset:2048
	ds_read_b128 v[176:179], v148 offset:3072
	ds_read_b128 v[180:183], v146 offset:32768
	ds_read_b128 v[184:187], v146 offset:33792
	ds_read_b128 v[188:191], v145 offset:32768
	ds_read_b128 v[192:195], v145 offset:33792
	ds_read_b128 v[196:199], v144 offset:32768
	ds_read_b128 v[202:205], v144 offset:33792
	ds_read_b128 v[206:209], v143 offset:32768
	ds_read_b128 v[216:219], v143 offset:33792
	s_waitcnt lgkmcnt(6)
	ds_read_b128 v[222:225], v147
	ds_read_b128 v[228:231], v147 offset:1024
	ds_read_b128 v[232:235], v147 offset:2048
	ds_read_b128 v[236:239], v147 offset:3072
	v_readfirstlane_b32 s2, v134
	v_lshl_add_u64 v[246:247], v[210:211], 0, s[44:45]
	s_mov_b32 m0, s2
	v_readfirstlane_b32 s2, v133
	global_load_lds_dwordx4 v[246:247], off
	v_lshl_add_u64 v[246:247], v[210:211], 0, s[46:47]
	s_mov_b32 m0, s2
	s_nop 0
	global_load_lds_dwordx4 v[246:247], off
	s_waitcnt vmcnt(8)
	s_barrier
	s_waitcnt lgkmcnt(0)
	v_mfma_f32_16x16x32_bf16 v[126:129], v[180:183], v[164:167], v[126:129]
	v_mfma_f32_16x16x32_bf16 v[122:125], v[180:183], v[172:175], v[122:125]
	v_mfma_f32_16x16x32_bf16 v[118:121], v[188:191], v[164:167], v[118:121]
	v_mfma_f32_16x16x32_bf16 v[114:117], v[188:191], v[172:175], v[114:117]
	v_mfma_f32_16x16x32_bf16 v[110:113], v[196:199], v[164:167], v[110:113]
	v_mfma_f32_16x16x32_bf16 v[106:109], v[196:199], v[172:175], v[106:109]
	v_mfma_f32_16x16x32_bf16 v[102:105], v[206:209], v[164:167], v[102:105]
	v_mfma_f32_16x16x32_bf16 v[98:101], v[206:209], v[172:175], v[98:101]
	v_mfma_f32_16x16x32_bf16 v[126:129], v[184:187], v[168:171], v[126:129]
	v_mfma_f32_16x16x32_bf16 v[122:125], v[184:187], v[176:179], v[122:125]
	v_mfma_f32_16x16x32_bf16 v[118:121], v[192:195], v[168:171], v[118:121]
	v_mfma_f32_16x16x32_bf16 v[114:117], v[192:195], v[176:179], v[114:117]
	v_mfma_f32_16x16x32_bf16 v[110:113], v[202:205], v[168:171], v[110:113]
	v_mfma_f32_16x16x32_bf16 v[106:109], v[202:205], v[176:179], v[106:109]
	v_mfma_f32_16x16x32_bf16 v[102:105], v[216:219], v[168:171], v[102:105]
	v_mfma_f32_16x16x32_bf16 v[98:101], v[216:219], v[176:179], v[98:101]
	v_mfma_f32_16x16x32_bf16 v[94:97], v[180:183], v[222:225], v[94:97]
	v_mfma_f32_16x16x32_bf16 v[90:93], v[180:183], v[232:235], v[90:93]
	v_mfma_f32_16x16x32_bf16 v[86:89], v[188:191], v[222:225], v[86:89]
	v_mfma_f32_16x16x32_bf16 v[82:85], v[188:191], v[232:235], v[82:85]
	v_mfma_f32_16x16x32_bf16 v[78:81], v[196:199], v[222:225], v[78:81]
	v_mfma_f32_16x16x32_bf16 v[74:77], v[196:199], v[232:235], v[74:77]
	v_mfma_f32_16x16x32_bf16 v[70:73], v[206:209], v[222:225], v[70:73]
	v_mfma_f32_16x16x32_bf16 v[66:69], v[206:209], v[232:235], v[66:69]
	v_mfma_f32_16x16x32_bf16 v[94:97], v[184:187], v[228:231], v[94:97]
	v_mfma_f32_16x16x32_bf16 v[90:93], v[184:187], v[236:239], v[90:93]
	v_mfma_f32_16x16x32_bf16 v[86:89], v[192:195], v[228:231], v[86:89]
	v_mfma_f32_16x16x32_bf16 v[82:85], v[192:195], v[236:239], v[82:85]
	v_mfma_f32_16x16x32_bf16 v[78:81], v[202:205], v[228:231], v[78:81]
	v_mfma_f32_16x16x32_bf16 v[74:77], v[202:205], v[236:239], v[74:77]
	v_mfma_f32_16x16x32_bf16 v[70:73], v[216:219], v[228:231], v[70:73]
	v_mfma_f32_16x16x32_bf16 v[66:69], v[216:219], v[236:239], v[66:69]
	s_barrier
; #define STAGE_B(P, br, kt) do { const char* _gb = (const char*)(Bt + ((long)(br) * K + (long)(kt) * BK)); \
;     __builtin_amdgcn_global_load_lds((const unsigned*)(_gb + bofl0), (unsigned*)((char*)(P) + gtid_ * 16), 16, 0, 0); \
;     __builtin_amdgcn_global_load_lds((const unsigned*)(_gb + (long)K * 128 + bofl0), (unsigned*)((char*)(P) + gtid_ * 16 + 8192), 16, 0, 0); } while (0)
; #define LDA(dst, b, h) for (int m = 0; m < 4; ++m) for (int k = 0; k < 2; ++k) \
;     dst[m][k] = *reinterpret_cast<const bf16x8*>((char*)SA(b, h) + lds_byte(wr * 64 + m * 16 + fr, k * 32 + fq * 8))
; #define LDB(dst, b, h) for (int n = 0; n < 2; ++n) for (int k = 0; k < 2; ++k) \
;     dst[n][k] = *reinterpret_cast<const bf16x8*>((char*)SB(b, h) + lds_byte(wc * 32 + n * 16 + fr, k * 32 + fq * 8))
; #define MMA(ai, bj, At_, Bt_) do { __builtin_amdgcn_s_setprio(1); \
;     for (int m = 0; m < 4; ++m) for (int n = 0; n < 2; ++n) for (int k = 0; k < 2; ++k) \
;       acc[ai][bj][m][n] = __builtin_amdgcn_mfma_f32_16x16x32_bf16(At_[m][k], Bt_[n][k], acc[ai][bj][m][n], 0, 0, 0); \
;     __builtin_amdgcn_s_setprio(0); } while (0)
; #define WAIT_V(n) asm volatile("s_waitcnt vmcnt(" #n ")" ::: "memory")
; #define WAIT_L(n) asm volatile("s_waitcnt lgkmcnt(" #n ")" ::: "memory")
; #define BAR __builtin_amdgcn_s_barrier()
; #define SCHED __builtin_amdgcn_sched_barrier(0)
; template <int EPI>
; __device__ __forceinline__ void gemm_tile(const GemmArgs& g, int brow, int bcol, int parity, bool first, bool nvalid, int nbrow, int nbcol) {
;     ...
;     BAR; WAIT_L(0); MMA(1, 0, At, B0); BAR; SCHED;
;     STAGE_B(SB(1, 1), bcol + HALF, t + 3);
;     WAIT_V(6); BAR; MMA(1, 1, At, B1); BAR; SCHED;
;   }
;   { LDB(B0, 0, 0); LDA(At, 0, 0); STAGE_A(SA(1, 1), brow + HALF, nt - 1);
;     BAR; WAIT_L(0); MMA(0, 0, At, B0); BAR;
	ds_read_b128 v[180:183], v146 offset:49152
	ds_read_b128 v[184:187], v146 offset:50176
	ds_read_b128 v[188:191], v145 offset:49152
	ds_read_b128 v[192:195], v145 offset:50176
	ds_read_b128 v[196:199], v144 offset:49152
	ds_read_b128 v[202:205], v144 offset:50176
	ds_read_b128 v[206:209], v143 offset:49152
	ds_read_b128 v[216:219], v143 offset:50176
	v_readfirstlane_b32 s2, v149
	v_lshl_add_u64 v[240:241], v[212:213], 0, s[58:59]
	s_mov_b32 m0, s2
	v_readfirstlane_b32 s2, v151
	global_load_lds_dwordx4 v[240:241], off
	v_lshl_add_u64 v[240:241], v[212:213], 0, s[76:77]
	s_mov_b32 m0, s2
	s_nop 0
	global_load_lds_dwordx4 v[240:241], off
	v_readfirstlane_b32 s2, v152
	v_lshl_add_u64 v[240:241], v[210:211], 0, s[48:49]
	s_mov_b32 m0, s2
	v_readfirstlane_b32 s2, v153
	global_load_lds_dwordx4 v[240:241], off
	v_lshl_add_u64 v[210:211], v[210:211], 0, s[50:51]
	s_mov_b32 m0, s2
	s_nop 0
	global_load_lds_dwordx4 v[210:211], off
	v_readfirstlane_b32 s2, v155
	v_lshl_add_u64 v[244:245], v[212:213], 0, s[96:97]
	s_mov_b32 m0, s2
	v_readfirstlane_b32 s2, v156
	global_load_lds_dwordx4 v[244:245], off
	v_lshl_add_u64 v[244:245], v[212:213], 0, s[60:61]
	s_mov_b32 m0, s2
	s_nop 0
	global_load_lds_dwordx4 v[244:245], off
	s_waitcnt vmcnt(8)
	s_barrier
	s_waitcnt lgkmcnt(0)
	v_mfma_f32_16x16x32_bf16 v[62:65], v[180:183], v[164:167], v[62:65]
	v_mfma_f32_16x16x32_bf16 v[58:61], v[180:183], v[172:175], v[58:61]
	v_mfma_f32_16x16x32_bf16 v[54:57], v[188:191], v[164:167], v[54:57]
	v_mfma_f32_16x16x32_bf16 v[50:53], v[188:191], v[172:175], v[50:53]
	v_mfma_f32_16x16x32_bf16 v[46:49], v[196:199], v[164:167], v[46:49]
	v_mfma_f32_16x16x32_bf16 v[42:45], v[196:199], v[172:175], v[42:45]
	v_mfma_f32_16x16x32_bf16 v[38:41], v[206:209], v[164:167], v[38:41]
	v_mfma_f32_16x16x32_bf16 v[34:37], v[206:209], v[172:175], v[34:37]
	v_mfma_f32_16x16x32_bf16 v[62:65], v[184:187], v[168:171], v[62:65]
	v_mfma_f32_16x16x32_bf16 v[58:61], v[184:187], v[176:179], v[58:61]
	v_mfma_f32_16x16x32_bf16 v[54:57], v[192:195], v[168:171], v[54:57]
	v_mfma_f32_16x16x32_bf16 v[50:53], v[192:195], v[176:179], v[50:53]
	v_mfma_f32_16x16x32_bf16 v[46:49], v[202:205], v[168:171], v[46:49]
	v_mfma_f32_16x16x32_bf16 v[42:45], v[202:205], v[176:179], v[42:45]
	v_mfma_f32_16x16x32_bf16 v[38:41], v[216:219], v[168:171], v[38:41]
	v_mfma_f32_16x16x32_bf16 v[34:37], v[216:219], v[176:179], v[34:37]
	v_mfma_f32_16x16x32_bf16 v[30:33], v[180:183], v[222:225], v[30:33]
	v_mfma_f32_16x16x32_bf16 v[26:29], v[180:183], v[232:235], v[26:29]
	v_mfma_f32_16x16x32_bf16 v[22:25], v[188:191], v[222:225], v[22:25]
	v_mfma_f32_16x16x32_bf16 v[18:21], v[188:191], v[232:235], v[18:21]
	v_mfma_f32_16x16x32_bf16 v[14:17], v[196:199], v[222:225], v[14:17]
	v_mfma_f32_16x16x32_bf16 v[10:13], v[196:199], v[232:235], v[10:13]
	v_mfma_f32_16x16x32_bf16 v[6:9], v[206:209], v[222:225], v[6:9]
	v_mfma_f32_16x16x32_bf16 v[2:5], v[206:209], v[232:235], v[2:5]
	v_mfma_f32_16x16x32_bf16 v[30:33], v[184:187], v[228:231], v[30:33]
	v_mfma_f32_16x16x32_bf16 v[26:29], v[184:187], v[236:239], v[26:29]
	v_mfma_f32_16x16x32_bf16 v[22:25], v[192:195], v[228:231], v[22:25]
	v_mfma_f32_16x16x32_bf16 v[18:21], v[192:195], v[236:239], v[18:21]
	v_mfma_f32_16x16x32_bf16 v[14:17], v[202:205], v[228:231], v[14:17]
	v_mfma_f32_16x16x32_bf16 v[10:13], v[202:205], v[236:239], v[10:13]
	v_mfma_f32_16x16x32_bf16 v[6:9], v[216:219], v[228:231], v[6:9]
	v_mfma_f32_16x16x32_bf16 v[2:5], v[216:219], v[236:239], v[2:5]
	s_add_i32 s22, s22, 2
	s_add_u32 s12, s12, 0x100
	s_addc_u32 s13, s13, 0
	s_add_u32 s0, s0, 0x100
	s_addc_u32 s1, s1, 0
	s_cmp_lt_u32 s22, 12
	s_cbranch_scc1 .LBB0_133
	s_barrier
	s_or_b32 s0, s40, 0x80
	s_ashr_i32 s1, s0, 31
	s_lshl_b64 s[0:1], s[0:1], 11
	s_add_u32 s0, s80, s0
	s_addc_u32 s1, s81, s1
	v_lshl_add_u64 v[130:131], s[0:1], 0, v[0:1]
	s_mov_b64 s[0:1], 0x780
	v_lshl_add_u64 v[152:153], v[130:131], 0, s[0:1]
	v_readfirstlane_b32 s0, v161
	s_mov_b32 m0, s0
	s_mov_b64 s[0:1], 0x20780
	v_lshl_add_u64 v[130:131], v[130:131], 0, s[0:1]
	v_readfirstlane_b32 s0, v162
	ds_read_b128 v[164:167], v157
	ds_read_b128 v[168:171], v157 offset:1024
	ds_read_b128 v[172:175], v157 offset:2048
	ds_read_b128 v[176:179], v157 offset:3072
	ds_read_b128 v[180:183], v146
	ds_read_b128 v[184:187], v146 offset:1024
	ds_read_b128 v[188:191], v145
	ds_read_b128 v[192:195], v145 offset:1024
	ds_read_b128 v[196:199], v144
	ds_read_b128 v[202:205], v144 offset:1024
	ds_read_b128 v[206:209], v143
	ds_read_b128 v[216:219], v143 offset:1024
	global_load_lds_dwordx4 v[152:153], off
	s_mov_b32 m0, s0
	s_nop 0
	global_load_lds_dwordx4 v[130:131], off
	s_waitcnt vmcnt(8)
	s_barrier
	s_waitcnt lgkmcnt(0)
	s_setprio 1
	s_waitcnt lgkmcnt(0)
	v_mfma_f32_16x16x32_bf16 v[126:129], v[180:183], v[164:167], v[126:129]
	v_mfma_f32_16x16x32_bf16 v[122:125], v[180:183], v[172:175], v[122:125]
	v_mfma_f32_16x16x32_bf16 v[110:113], v[196:199], v[164:167], v[110:113]
	v_mfma_f32_16x16x32_bf16 v[106:109], v[196:199], v[172:175], v[106:109]
	v_mfma_f32_16x16x32_bf16 v[126:129], v[184:187], v[168:171], v[126:129]
	v_mfma_f32_16x16x32_bf16 v[122:125], v[184:187], v[176:179], v[122:125]
	v_mfma_f32_16x16x32_bf16 v[118:121], v[188:191], v[164:167], v[118:121]
	v_mfma_f32_16x16x32_bf16 v[114:117], v[188:191], v[172:175], v[114:117]
	v_mfma_f32_16x16x32_bf16 v[110:113], v[202:205], v[168:171], v[110:113]
	v_mfma_f32_16x16x32_bf16 v[106:109], v[202:205], v[176:179], v[106:109]
	v_mfma_f32_16x16x32_bf16 v[102:105], v[206:209], v[164:167], v[102:105]
	v_mfma_f32_16x16x32_bf16 v[98:101], v[206:209], v[172:175], v[98:101]
	v_mfma_f32_16x16x32_bf16 v[222:225], v[192:195], v[168:171], v[118:121]
	v_mfma_f32_16x16x32_bf16 v[228:231], v[192:195], v[176:179], v[114:117]
	v_mfma_f32_16x16x32_bf16 v[232:235], v[216:219], v[168:171], v[102:105]
	v_mfma_f32_16x16x32_bf16 v[236:239], v[216:219], v[176:179], v[98:101]
	s_setprio 0
	s_barrier
; #define LDA(dst, b, h) for (int m = 0; m < 4; ++m) for (int k = 0; k < 2; ++k) \
;     dst[m][k] = *reinterpret_cast<const bf16x8*>((char*)SA(b, h) + lds_byte(wr * 64 + m * 16 + fr, k * 32 + fq * 8))
; #define LDB(dst, b, h) for (int n = 0; n < 2; ++n) for (int k = 0; k < 2; ++k) \
;     dst[n][k] = *reinterpret_cast<const bf16x8*>((char*)SB(b, h) + lds_byte(wc * 32 + n * 16 + fr, k * 32 + fq * 8))
; #define MMA(ai, bj, At_, Bt_) do { __builtin_amdgcn_s_setprio(1); \
;     for (int m = 0; m < 4; ++m) for (int n = 0; n < 2; ++n) for (int k = 0; k < 2; ++k) \
;       acc[ai][bj][m][n] = __builtin_amdgcn_mfma_f32_16x16x32_bf16(At_[m][k], Bt_[n][k], acc[ai][bj][m][n], 0, 0, 0); \
;     __builtin_amdgcn_s_setprio(0); } while (0)
; #define WAIT_V(n) asm volatile("s_waitcnt vmcnt(" #n ")" ::: "memory")
; #define WAIT_L(n) asm volatile("s_waitcnt lgkmcnt(" #n ")" ::: "memory")
; #define BAR __builtin_amdgcn_s_barrier()
; #define SCHED __builtin_amdgcn_sched_barrier(0)
; template <int EPI>
; __device__ __forceinline__ void gemm_tile(const GemmArgs& g, int brow, int bcol, int parity, bool first, bool nvalid, int nbrow, int nbcol) {
;     ...
;     BAR; WAIT_L(0); MMA(0, 0, At, B0); BAR;
;     LDB(B1, 0, 1); BAR; WAIT_L(0); MMA(0, 1, At, B1); BAR; SCHED;
;     LDA(At, 0, 1); WAIT_V(4); BAR; WAIT_L(0); MMA(1, 0, At, B0); MMA(1, 1, At, B1); BAR; }
;   { LDB(B0, 1, 0); LDA(At, 1, 0); WAIT_V(2); BAR; WAIT_L(0); MMA(0, 0, At, B0); BAR;
	s_nop 1
	ds_read_b128 v[98:101], v154
	ds_read_b128 v[102:105], v154 offset:1024
	ds_read_b128 v[114:117], v154 offset:2048
	ds_read_b128 v[118:121], v154 offset:3072
	s_barrier
	s_waitcnt lgkmcnt(0)
	s_setprio 1
	s_waitcnt lgkmcnt(0)
	v_mfma_f32_16x16x32_bf16 v[94:97], v[180:183], v[98:101], v[94:97]
	v_mfma_f32_16x16x32_bf16 v[90:93], v[180:183], v[114:117], v[90:93]
	v_mfma_f32_16x16x32_bf16 v[78:81], v[196:199], v[98:101], v[78:81]
	v_mfma_f32_16x16x32_bf16 v[74:77], v[196:199], v[114:117], v[74:77]
	v_mfma_f32_16x16x32_bf16 v[94:97], v[184:187], v[102:105], v[94:97]
	v_mfma_f32_16x16x32_bf16 v[90:93], v[184:187], v[118:121], v[90:93]
	v_mfma_f32_16x16x32_bf16 v[86:89], v[188:191], v[98:101], v[86:89]
	v_mfma_f32_16x16x32_bf16 v[82:85], v[188:191], v[114:117], v[82:85]
	v_mfma_f32_16x16x32_bf16 v[78:81], v[202:205], v[102:105], v[78:81]
	v_mfma_f32_16x16x32_bf16 v[74:77], v[202:205], v[118:121], v[74:77]
	v_mfma_f32_16x16x32_bf16 v[70:73], v[206:209], v[98:101], v[70:73]
	v_mfma_f32_16x16x32_bf16 v[66:69], v[206:209], v[114:117], v[66:69]
	v_mfma_f32_16x16x32_bf16 v[152:155], v[192:195], v[102:105], v[86:89]
	v_mfma_f32_16x16x32_bf16 v[180:183], v[192:195], v[118:121], v[82:85]
	v_mfma_f32_16x16x32_bf16 v[184:187], v[216:219], v[102:105], v[70:73]
	v_mfma_f32_16x16x32_bf16 v[188:191], v[216:219], v[118:121], v[66:69]
	s_setprio 0
	s_barrier
	s_nop 1
	ds_read_b128 v[66:69], v146 offset:16384
	ds_read_b128 v[70:73], v146 offset:17408
	ds_read_b128 v[82:85], v145 offset:16384
	ds_read_b128 v[86:89], v145 offset:17408
	ds_read_b128 v[192:195], v144 offset:16384
	ds_read_b128 v[196:199], v144 offset:17408
	ds_read_b128 v[202:205], v143 offset:16384
	ds_read_b128 v[206:209], v143 offset:17408
	s_waitcnt vmcnt(4)
	s_barrier
	s_waitcnt lgkmcnt(0)
	s_setprio 1
	s_waitcnt lgkmcnt(0)
	v_mfma_f32_16x16x32_bf16 v[62:65], v[66:69], v[164:167], v[62:65]
	v_mfma_f32_16x16x32_bf16 v[58:61], v[66:69], v[172:175], v[58:61]
	v_mfma_f32_16x16x32_bf16 v[46:49], v[192:195], v[164:167], v[46:49]
	v_mfma_f32_16x16x32_bf16 v[42:45], v[192:195], v[172:175], v[42:45]
	v_mfma_f32_16x16x32_bf16 v[62:65], v[70:73], v[168:171], v[62:65]
	v_mfma_f32_16x16x32_bf16 v[58:61], v[70:73], v[176:179], v[58:61]
	v_mfma_f32_16x16x32_bf16 v[54:57], v[82:85], v[164:167], v[54:57]
	v_mfma_f32_16x16x32_bf16 v[50:53], v[82:85], v[172:175], v[50:53]
	v_mfma_f32_16x16x32_bf16 v[46:49], v[196:199], v[168:171], v[46:49]
	v_mfma_f32_16x16x32_bf16 v[42:45], v[196:199], v[176:179], v[42:45]
	v_mfma_f32_16x16x32_bf16 v[38:41], v[202:205], v[164:167], v[38:41]
	v_mfma_f32_16x16x32_bf16 v[34:37], v[202:205], v[172:175], v[34:37]
	v_mfma_f32_16x16x32_bf16 v[216:219], v[86:89], v[168:171], v[54:57]
	v_mfma_f32_16x16x32_bf16 v[240:243], v[86:89], v[176:179], v[50:53]
	v_mfma_f32_16x16x32_bf16 v[162:165], v[206:209], v[168:171], v[38:41]
	v_mfma_f32_16x16x32_bf16 v[166:169], v[206:209], v[176:179], v[34:37]
	s_setprio 0
	s_setprio 1
	v_mfma_f32_16x16x32_bf16 v[30:33], v[66:69], v[98:101], v[30:33]
	v_mfma_f32_16x16x32_bf16 v[26:29], v[66:69], v[114:117], v[26:29]
	v_mfma_f32_16x16x32_bf16 v[14:17], v[192:195], v[98:101], v[14:17]
	v_mfma_f32_16x16x32_bf16 v[10:13], v[192:195], v[114:117], v[10:13]
	v_mfma_f32_16x16x32_bf16 v[30:33], v[70:73], v[102:105], v[30:33]
	v_mfma_f32_16x16x32_bf16 v[26:29], v[70:73], v[118:121], v[26:29]
	v_mfma_f32_16x16x32_bf16 v[22:25], v[82:85], v[98:101], v[22:25]
	v_mfma_f32_16x16x32_bf16 v[18:21], v[82:85], v[114:117], v[18:21]
	v_mfma_f32_16x16x32_bf16 v[14:17], v[196:199], v[102:105], v[14:17]
	v_mfma_f32_16x16x32_bf16 v[10:13], v[196:199], v[118:121], v[10:13]
	v_mfma_f32_16x16x32_bf16 v[6:9], v[202:205], v[98:101], v[6:9]
	v_mfma_f32_16x16x32_bf16 v[2:5], v[202:205], v[114:117], v[2:5]
	v_mfma_f32_16x16x32_bf16 v[170:173], v[86:89], v[102:105], v[22:25]
	v_mfma_f32_16x16x32_bf16 v[174:177], v[86:89], v[118:121], v[18:21]
	v_mfma_f32_16x16x32_bf16 v[192:195], v[206:209], v[102:105], v[6:9]
	v_mfma_f32_16x16x32_bf16 v[196:199], v[206:209], v[118:121], v[2:5]
	s_setprio 0
	s_barrier
	s_nop 1
	ds_read_b128 v[2:5], v148
	ds_read_b128 v[6:9], v148 offset:1024
	ds_read_b128 v[202:205], v148 offset:2048
	ds_read_b128 v[206:209], v148 offset:3072
	ds_read_b128 v[18:21], v146 offset:32768
	ds_read_b128 v[22:25], v146 offset:33792
	ds_read_b128 v[34:37], v145 offset:32768
	ds_read_b128 v[38:41], v145 offset:33792
	ds_read_b128 v[50:53], v144 offset:32768
	ds_read_b128 v[54:57], v144 offset:33792
	ds_read_b128 v[244:247], v143 offset:32768
	ds_read_b128 v[248:251], v143 offset:33792
	s_waitcnt vmcnt(2)
	s_barrier
; #define LDA(dst, b, h) for (int m = 0; m < 4; ++m) for (int k = 0; k < 2; ++k) \
;     dst[m][k] = *reinterpret_cast<const bf16x8*>((char*)SA(b, h) + lds_byte(wr * 64 + m * 16 + fr, k * 32 + fq * 8))
; #define LDB(dst, b, h) for (int n = 0; n < 2; ++n) for (int k = 0; k < 2; ++k) \
;     dst[n][k] = *reinterpret_cast<const bf16x8*>((char*)SB(b, h) + lds_byte(wc * 32 + n * 16 + fr, k * 32 + fq * 8))
; #define MMA(ai, bj, At_, Bt_) do { __builtin_amdgcn_s_setprio(1); \
;     for (int m = 0; m < 4; ++m) for (int n = 0; n < 2; ++n) for (int k = 0; k < 2; ++k) \
;       acc[ai][bj][m][n] = __builtin_amdgcn_mfma_f32_16x16x32_bf16(At_[m][k], Bt_[n][k], acc[ai][bj][m][n], 0, 0, 0); \
;     __builtin_amdgcn_s_setprio(0); } while (0)
; #define WAIT_V(n) asm volatile("s_waitcnt vmcnt(" #n ")" ::: "memory")
; #define WAIT_L(n) asm volatile("s_waitcnt lgkmcnt(" #n ")" ::: "memory")
; #define BAR __builtin_amdgcn_s_barrier()
; #define SCHED __builtin_amdgcn_sched_barrier(0)
; template <int EPI>
; __device__ __forceinline__ void gemm_tile(const GemmArgs& g, int brow, int bcol, int parity, bool first, bool nvalid, int nbrow, int nbcol) {
;     ...
;   { LDB(B0, 1, 0); LDA(At, 1, 0); WAIT_V(2); BAR; WAIT_L(0); MMA(0, 0, At, B0); BAR;
;     LDB(B1, 1, 1); WAIT_V(0); BAR; WAIT_L(0); MMA(0, 1, At, B1); BAR; SCHED;
;     LDA(At, 1, 1); BAR; WAIT_L(0); MMA(1, 0, At, B0); MMA(1, 1, At, B1); BAR; }
;   if (wr == 0) BAR;
	s_waitcnt lgkmcnt(0)
	s_setprio 1
	s_waitcnt lgkmcnt(0)
	v_mfma_f32_16x16x32_bf16 v[66:69], v[18:21], v[2:5], v[126:129]
	v_mfma_f32_16x16x32_bf16 v[114:117], v[22:25], v[6:9], v[66:69]
	v_mfma_f32_16x16x32_bf16 v[66:69], v[18:21], v[202:205], v[122:125]
	v_mfma_f32_16x16x32_bf16 v[118:121], v[22:25], v[206:209], v[66:69]
	v_mfma_f32_16x16x32_bf16 v[66:69], v[34:37], v[2:5], v[222:225]
	v_mfma_f32_16x16x32_bf16 v[98:101], v[38:41], v[6:9], v[66:69]
	v_mfma_f32_16x16x32_bf16 v[66:69], v[34:37], v[202:205], v[228:231]
	v_mfma_f32_16x16x32_bf16 v[102:105], v[38:41], v[206:209], v[66:69]
	v_mfma_f32_16x16x32_bf16 v[66:69], v[50:53], v[2:5], v[110:113]
	v_mfma_f32_16x16x32_bf16 v[82:85], v[54:57], v[6:9], v[66:69]
	v_mfma_f32_16x16x32_bf16 v[66:69], v[50:53], v[202:205], v[106:109]
	v_mfma_f32_16x16x32_bf16 v[86:89], v[54:57], v[206:209], v[66:69]
	v_mfma_f32_16x16x32_bf16 v[66:69], v[244:247], v[2:5], v[232:235]
	v_mfma_f32_16x16x32_bf16 v[70:73], v[244:247], v[202:205], v[236:239]
	v_mfma_f32_16x16x32_bf16 v[66:69], v[248:251], v[6:9], v[66:69]
	v_mfma_f32_16x16x32_bf16 v[70:73], v[248:251], v[206:209], v[70:73]
	s_setprio 0
	s_barrier
	ds_read_b128 v[222:225], v147
	ds_read_b128 v[228:231], v147 offset:1024
	ds_read_b128 v[232:235], v147 offset:2048
	ds_read_b128 v[236:239], v147 offset:3072
	s_waitcnt vmcnt(0)
	s_barrier
	s_waitcnt lgkmcnt(0)
	s_setprio 1
	s_waitcnt lgkmcnt(0)
	v_mfma_f32_16x16x32_bf16 v[94:97], v[18:21], v[222:225], v[94:97]
	v_mfma_f32_16x16x32_bf16 v[18:21], v[18:21], v[232:235], v[90:93]
	v_mfma_f32_16x16x32_bf16 v[122:125], v[22:25], v[236:239], v[18:21]
	v_mfma_f32_16x16x32_bf16 v[18:21], v[34:37], v[222:225], v[152:155]
	v_mfma_f32_16x16x32_bf16 v[110:113], v[38:41], v[228:231], v[18:21]
	v_mfma_f32_16x16x32_bf16 v[18:21], v[34:37], v[232:235], v[180:183]
	v_mfma_f32_16x16x32_bf16 v[106:109], v[38:41], v[236:239], v[18:21]
	v_mfma_f32_16x16x32_bf16 v[18:21], v[50:53], v[222:225], v[78:81]
	v_mfma_f32_16x16x32_bf16 v[126:129], v[22:25], v[228:231], v[94:97]
	v_mfma_f32_16x16x32_bf16 v[94:97], v[54:57], v[228:231], v[18:21]
	v_mfma_f32_16x16x32_bf16 v[18:21], v[50:53], v[232:235], v[74:77]
	v_mfma_f32_16x16x32_bf16 v[90:93], v[54:57], v[236:239], v[18:21]
	v_mfma_f32_16x16x32_bf16 v[18:21], v[244:247], v[222:225], v[184:187]
	v_mfma_f32_16x16x32_bf16 v[78:81], v[248:251], v[228:231], v[18:21]
	v_mfma_f32_16x16x32_bf16 v[18:21], v[244:247], v[232:235], v[188:191]
	v_mfma_f32_16x16x32_bf16 v[74:77], v[248:251], v[236:239], v[18:21]
	s_setprio 0
	s_barrier
	ds_read_b128 v[152:155], v146 offset:49152
	ds_read_b128 v[146:149], v146 offset:50176
	ds_read_b128 v[178:181], v145 offset:49152
	ds_read_b128 v[182:185], v145 offset:50176
	ds_read_b128 v[186:189], v144 offset:49152
	ds_read_b128 v[244:247], v144 offset:50176
	ds_read_b128 v[248:251], v143 offset:49152
	ds_read_b128 v[210:213], v143 offset:50176
	s_barrier
	s_waitcnt lgkmcnt(0)
	s_setprio 1
	s_waitcnt lgkmcnt(0)
	v_mfma_f32_16x16x32_bf16 v[18:21], v[152:155], v[2:5], v[62:65]
	v_mfma_f32_16x16x32_bf16 v[50:53], v[146:149], v[6:9], v[18:21]
	v_mfma_f32_16x16x32_bf16 v[18:21], v[152:155], v[202:205], v[58:61]
	v_mfma_f32_16x16x32_bf16 v[54:57], v[146:149], v[206:209], v[18:21]
	v_mfma_f32_16x16x32_bf16 v[18:21], v[178:181], v[2:5], v[216:219]
	v_mfma_f32_16x16x32_bf16 v[34:37], v[182:185], v[6:9], v[18:21]
	v_mfma_f32_16x16x32_bf16 v[18:21], v[178:181], v[202:205], v[240:243]
	v_mfma_f32_16x16x32_bf16 v[38:41], v[182:185], v[206:209], v[18:21]
	v_mfma_f32_16x16x32_bf16 v[18:21], v[186:189], v[2:5], v[46:49]
	v_mfma_f32_16x16x32_bf16 v[2:5], v[248:251], v[2:5], v[162:165]
	v_mfma_f32_16x16x32_bf16 v[18:21], v[244:247], v[6:9], v[18:21]
	v_mfma_f32_16x16x32_bf16 v[22:25], v[186:189], v[202:205], v[42:45]
	v_mfma_f32_16x16x32_bf16 v[2:5], v[210:213], v[6:9], v[2:5]
	v_mfma_f32_16x16x32_bf16 v[6:9], v[248:251], v[202:205], v[166:169]
	v_mfma_f32_16x16x32_bf16 v[22:25], v[244:247], v[206:209], v[22:25]
	v_mfma_f32_16x16x32_bf16 v[6:9], v[210:213], v[206:209], v[6:9]
	s_setprio 0
	s_setprio 1
	v_mfma_f32_16x16x32_bf16 v[26:29], v[152:155], v[232:235], v[26:29]
	v_mfma_f32_16x16x32_bf16 v[58:61], v[146:149], v[236:239], v[26:29]
	v_mfma_f32_16x16x32_bf16 v[26:29], v[178:181], v[222:225], v[170:173]
	v_mfma_f32_16x16x32_bf16 v[46:49], v[182:185], v[228:231], v[26:29]
	v_mfma_f32_16x16x32_bf16 v[26:29], v[178:181], v[232:235], v[174:177]
	v_mfma_f32_16x16x32_bf16 v[10:13], v[186:189], v[232:235], v[10:13]
	v_mfma_f32_16x16x32_bf16 v[30:33], v[152:155], v[222:225], v[30:33]
	v_mfma_f32_16x16x32_bf16 v[42:45], v[182:185], v[236:239], v[26:29]
	v_mfma_f32_16x16x32_bf16 v[14:17], v[186:189], v[222:225], v[14:17]
	v_mfma_f32_16x16x32_bf16 v[26:29], v[244:247], v[236:239], v[10:13]
	v_mfma_f32_16x16x32_bf16 v[10:13], v[248:251], v[222:225], v[192:195]
	v_mfma_f32_16x16x32_bf16 v[62:65], v[146:149], v[228:231], v[30:33]
	v_mfma_f32_16x16x32_bf16 v[30:33], v[244:247], v[228:231], v[14:17]
	v_mfma_f32_16x16x32_bf16 v[14:17], v[210:213], v[228:231], v[10:13]
	v_mfma_f32_16x16x32_bf16 v[10:13], v[248:251], v[232:235], v[196:199]
	v_mfma_f32_16x16x32_bf16 v[10:13], v[210:213], v[236:239], v[10:13]
	s_setprio 0
	s_movk_i32 s0, 0x100
	v_cmp_gt_u32_e32 vcc, s0, v138
	s_barrier
	s_and_saveexec_b64 s[0:1], vcc
	s_cbranch_execz .LBB0_136
	s_barrier

; #define STAGE_B(P, br, kt) do { const char* _gb = (const char*)(Bt + ((long)(br) * K + (long)(kt) * BK)); \
;     __builtin_amdgcn_global_load_lds((const unsigned*)(_gb + bofl0), (unsigned*)((char*)(P) + gtid_ * 16), 16, 0, 0); \
;     __builtin_amdgcn_global_load_lds((const unsigned*)(_gb + (long)K * 128 + bofl0), (unsigned*)((char*)(P) + gtid_ * 16 + 8192), 16, 0, 0); } while (0)
; #define LDA(dst, b, h) for (int m = 0; m < 4; ++m) for (int k = 0; k < 2; ++k) \
;     dst[m][k] = *reinterpret_cast<const bf16x8*>((char*)SA(b, h) + lds_byte(wr * 64 + m * 16 + fr, k * 32 + fq * 8))
; #define LDB(dst, b, h) for (int n = 0; n < 2; ++n) for (int k = 0; k < 2; ++k) \
;     dst[n][k] = *reinterpret_cast<const bf16x8*>((char*)SB(b, h) + lds_byte(wc * 32 + n * 16 + fr, k * 32 + fq * 8))
; #define MMA(ai, bj, At_, Bt_) do { __builtin_amdgcn_s_setprio(1); \
;     for (int m = 0; m < 4; ++m) for (int n = 0; n < 2; ++n) for (int k = 0; k < 2; ++k) \
;       acc[ai][bj][m][n] = __builtin_amdgcn_mfma_f32_16x16x32_bf16(At_[m][k], Bt_[n][k], acc[ai][bj][m][n], 0, 0, 0); \
;     __builtin_amdgcn_s_setprio(0); } while (0)
; #define WAIT_V(n) asm volatile("s_waitcnt vmcnt(" #n ")" ::: "memory")
; #define WAIT_L(n) asm volatile("s_waitcnt lgkmcnt(" #n ")" ::: "memory")
; #define BAR __builtin_amdgcn_s_barrier()
; #define SCHED __builtin_amdgcn_sched_barrier(0)
; template <int EPI>
; __device__ __forceinline__ void gemm_tile(const GemmArgs& g, int brow, int bcol, int parity, bool first, bool nvalid, int nbrow, int nbcol) {
;     ...
;   for (int t = 0; t < nt - 2; t += 2) {
;     LDB(B0, 0, 0); SCHED; LDA(At, 0, 0); STAGE_A(SA(1, 1), brow + HALF, t + 1);
;     WAIT_L(8); BAR; WAIT_L(0); MMA(0, 0, At, B0); BAR; SCHED;
;     LDB(B1, 0, 1); STAGE_B(SB(0, 0), bcol, t + 2);
;     BAR; WAIT_L(0); MMA(0, 1, At, B1); BAR; SCHED;
;     LDA(At, 0, 1); STAGE_A(SA(0, 0), brow, t + 2);
;     BAR; WAIT_L(0); MMA(1, 0, At, B0); BAR; SCHED;
;     STAGE_B(SB(0, 1), bcol + HALF, t + 2);
;     WAIT_V(6); BAR; MMA(1, 1, At, B1); BAR; SCHED;
;     LDB(B0, 1, 0); SCHED; LDA(At, 1, 0); STAGE_A(SA(0, 1), brow + HALF, t + 2);
;     WAIT_L(8); BAR; WAIT_L(0); MMA(0, 0, At, B0); BAR; SCHED;
.LBB0_166:
	s_barrier
	ds_read_b128 v[164:167], v157
	ds_read_b128 v[168:171], v157 offset:1024
	ds_read_b128 v[172:175], v157 offset:2048
	ds_read_b128 v[176:179], v157 offset:3072
	ds_read_b128 v[180:183], v147
	ds_read_b128 v[184:187], v147 offset:1024
	ds_read_b128 v[188:191], v146
	ds_read_b128 v[192:195], v146 offset:1024
	ds_read_b128 v[196:199], v145
	ds_read_b128 v[202:205], v145 offset:1024
	ds_read_b128 v[206:209], v144
	ds_read_b128 v[216:219], v144 offset:1024
	s_waitcnt lgkmcnt(6)
	ds_read_b128 v[222:225], v154
	ds_read_b128 v[228:231], v154 offset:1024
	ds_read_b128 v[232:235], v154 offset:2048
	ds_read_b128 v[236:239], v154 offset:3072
	v_add_u32_e32 v161, 0xc000, v137
	v_lshl_add_u64 v[210:211], s[0:1], 0, v[130:131]
	v_readfirstlane_b32 s2, v161
	v_add_u32_e32 v162, 0xe000, v137
	v_lshl_add_u64 v[158:159], v[210:211], 0, s[26:27]
	s_mov_b32 m0, s2
	v_readfirstlane_b32 s2, v162
	global_load_lds_dwordx4 v[158:159], off
	v_lshl_add_u64 v[158:159], v[210:211], 0, s[42:43]
	s_mov_b32 m0, s2
	s_nop 0
	global_load_lds_dwordx4 v[158:159], off
	s_waitcnt vmcnt(8)
	s_barrier
	s_waitcnt lgkmcnt(0)
	v_mfma_f32_16x16x32_bf16 v[126:129], v[164:167], v[180:183], v[126:129]
	v_mfma_f32_16x16x32_bf16 v[122:125], v[172:175], v[180:183], v[122:125]
	v_mfma_f32_16x16x32_bf16 v[118:121], v[164:167], v[188:191], v[118:121]
	v_mfma_f32_16x16x32_bf16 v[114:117], v[172:175], v[188:191], v[114:117]
	v_mfma_f32_16x16x32_bf16 v[110:113], v[164:167], v[196:199], v[110:113]
	v_mfma_f32_16x16x32_bf16 v[106:109], v[172:175], v[196:199], v[106:109]
	v_mfma_f32_16x16x32_bf16 v[102:105], v[164:167], v[206:209], v[102:105]
	v_mfma_f32_16x16x32_bf16 v[98:101], v[172:175], v[206:209], v[98:101]
	v_mfma_f32_16x16x32_bf16 v[126:129], v[168:171], v[184:187], v[126:129]
	v_mfma_f32_16x16x32_bf16 v[122:125], v[176:179], v[184:187], v[122:125]
	v_mfma_f32_16x16x32_bf16 v[118:121], v[168:171], v[192:195], v[118:121]
	v_mfma_f32_16x16x32_bf16 v[114:117], v[176:179], v[192:195], v[114:117]
	v_mfma_f32_16x16x32_bf16 v[110:113], v[168:171], v[202:205], v[110:113]
	v_mfma_f32_16x16x32_bf16 v[106:109], v[176:179], v[202:205], v[106:109]
	v_mfma_f32_16x16x32_bf16 v[102:105], v[168:171], v[216:219], v[102:105]
	v_mfma_f32_16x16x32_bf16 v[98:101], v[176:179], v[216:219], v[98:101]
	v_mfma_f32_16x16x32_bf16 v[94:97], v[222:225], v[180:183], v[94:97]
	v_mfma_f32_16x16x32_bf16 v[90:93], v[232:235], v[180:183], v[90:93]
	v_mfma_f32_16x16x32_bf16 v[86:89], v[222:225], v[188:191], v[86:89]
	v_mfma_f32_16x16x32_bf16 v[82:85], v[232:235], v[188:191], v[82:85]
	v_mfma_f32_16x16x32_bf16 v[78:81], v[222:225], v[196:199], v[78:81]
	v_mfma_f32_16x16x32_bf16 v[74:77], v[232:235], v[196:199], v[74:77]
	v_mfma_f32_16x16x32_bf16 v[70:73], v[222:225], v[206:209], v[70:73]
	v_mfma_f32_16x16x32_bf16 v[66:69], v[232:235], v[206:209], v[66:69]
	v_mfma_f32_16x16x32_bf16 v[94:97], v[228:231], v[184:187], v[94:97]
	v_mfma_f32_16x16x32_bf16 v[90:93], v[236:239], v[184:187], v[90:93]
	v_mfma_f32_16x16x32_bf16 v[86:89], v[228:231], v[192:195], v[86:89]
	v_mfma_f32_16x16x32_bf16 v[82:85], v[236:239], v[192:195], v[82:85]
	v_mfma_f32_16x16x32_bf16 v[78:81], v[228:231], v[202:205], v[78:81]
	v_mfma_f32_16x16x32_bf16 v[74:77], v[236:239], v[202:205], v[74:77]
	v_mfma_f32_16x16x32_bf16 v[70:73], v[228:231], v[216:219], v[70:73]
	v_mfma_f32_16x16x32_bf16 v[66:69], v[236:239], v[216:219], v[66:69]
	s_barrier
	ds_read_b128 v[180:183], v147 offset:16384
	ds_read_b128 v[184:187], v147 offset:17408
	ds_read_b128 v[188:191], v146 offset:16384
	ds_read_b128 v[192:195], v146 offset:17408
	ds_read_b128 v[196:199], v145 offset:16384
	ds_read_b128 v[202:205], v145 offset:17408
	ds_read_b128 v[206:209], v144 offset:16384
	ds_read_b128 v[216:219], v144 offset:17408
	v_add_u32_e32 v158, s15, v142
	v_lshl_add_u64 v[212:213], s[12:13], 0, v[130:131]
	v_readfirstlane_b32 s2, v158
	v_add_u32_e32 v159, 0x2000, v158
	v_lshl_add_u64 v[240:241], v[212:213], 0, s[78:79]
	s_mov_b32 m0, s2
	v_readfirstlane_b32 s2, v159
	global_load_lds_dwordx4 v[240:241], off
	v_lshl_add_u64 v[240:241], v[212:213], 0, s[66:67]
	s_mov_b32 m0, s2
	s_nop 0
	global_load_lds_dwordx4 v[240:241], off
	v_readfirstlane_b32 s2, v137
	v_lshl_add_u64 v[240:241], v[210:211], 0, s[44:45]
	s_mov_b32 m0, s2
	v_readfirstlane_b32 s2, v136
	global_load_lds_dwordx4 v[240:241], off
	v_lshl_add_u64 v[240:241], v[210:211], 0, s[46:47]
	s_mov_b32 m0, s2
	s_nop 0
	global_load_lds_dwordx4 v[240:241], off
	v_readfirstlane_b32 s2, v135
	v_add_u32_e32 v160, 0x2000, v135
	v_lshl_add_u64 v[244:245], v[212:213], 0, s[76:77]
	s_mov_b32 m0, s2
	v_readfirstlane_b32 s2, v160
	global_load_lds_dwordx4 v[244:245], off
	v_lshl_add_u64 v[244:245], v[212:213], 0, s[96:97]
	s_mov_b32 m0, s2
	s_nop 0
	global_load_lds_dwordx4 v[244:245], off
	s_waitcnt vmcnt(8)
	s_barrier
; #define STAGE_B(P, br, kt) do { const char* _gb = (const char*)(Bt + ((long)(br) * K + (long)(kt) * BK)); \
;     __builtin_amdgcn_global_load_lds((const unsigned*)(_gb + bofl0), (unsigned*)((char*)(P) + gtid_ * 16), 16, 0, 0); \
;     __builtin_amdgcn_global_load_lds((const unsigned*)(_gb + (long)K * 128 + bofl0), (unsigned*)((char*)(P) + gtid_ * 16 + 8192), 16, 0, 0); } while (0)
; #define LDA(dst, b, h) for (int m = 0; m < 4; ++m) for (int k = 0; k < 2; ++k) \
;     dst[m][k] = *reinterpret_cast<const bf16x8*>((char*)SA(b, h) + lds_byte(wr * 64 + m * 16 + fr, k * 32 + fq * 8))
; #define LDB(dst, b, h) for (int n = 0; n < 2; ++n) for (int k = 0; k < 2; ++k) \
;     dst[n][k] = *reinterpret_cast<const bf16x8*>((char*)SB(b, h) + lds_byte(wc * 32 + n * 16 + fr, k * 32 + fq * 8))
; #define MMA(ai, bj, At_, Bt_) do { __builtin_amdgcn_s_setprio(1); \
;     for (int m = 0; m < 4; ++m) for (int n = 0; n < 2; ++n) for (int k = 0; k < 2; ++k) \
;       acc[ai][bj][m][n] = __builtin_amdgcn_mfma_f32_16x16x32_bf16(At_[m][k], Bt_[n][k], acc[ai][bj][m][n], 0, 0, 0); \
;     __builtin_amdgcn_s_setprio(0); } while (0)
; #define WAIT_V(n) asm volatile("s_waitcnt vmcnt(" #n ")" ::: "memory")
; #define WAIT_L(n) asm volatile("s_waitcnt lgkmcnt(" #n ")" ::: "memory")
; #define BAR __builtin_amdgcn_s_barrier()
; #define SCHED __builtin_amdgcn_sched_barrier(0)
; template <int EPI>
; __device__ __forceinline__ void gemm_tile(const GemmArgs& g, int brow, int bcol, int parity, bool first, bool nvalid, int nbrow, int nbcol) {
;     ...
;     WAIT_V(6); BAR; MMA(1, 1, At, B1); BAR; SCHED;
;     LDB(B0, 1, 0); SCHED; LDA(At, 1, 0); STAGE_A(SA(0, 1), brow + HALF, t + 2);
;     WAIT_L(8); BAR; WAIT_L(0); MMA(0, 0, At, B0); BAR; SCHED;
;     LDB(B1, 1, 1); STAGE_B(SB(1, 0), bcol, t + 3);
;     BAR; WAIT_L(0); MMA(0, 1, At, B1); BAR; SCHED;
;     LDA(At, 1, 1); STAGE_A(SA(1, 0), brow, t + 3);
;     BAR; WAIT_L(0); MMA(1, 0, At, B0); BAR; SCHED;
	s_waitcnt lgkmcnt(0)
	v_mfma_f32_16x16x32_bf16 v[62:65], v[164:167], v[180:183], v[62:65]
	v_mfma_f32_16x16x32_bf16 v[58:61], v[172:175], v[180:183], v[58:61]
	v_mfma_f32_16x16x32_bf16 v[54:57], v[164:167], v[188:191], v[54:57]
	v_mfma_f32_16x16x32_bf16 v[50:53], v[172:175], v[188:191], v[50:53]
	v_mfma_f32_16x16x32_bf16 v[46:49], v[164:167], v[196:199], v[46:49]
	v_mfma_f32_16x16x32_bf16 v[42:45], v[172:175], v[196:199], v[42:45]
	v_mfma_f32_16x16x32_bf16 v[38:41], v[164:167], v[206:209], v[38:41]
	v_mfma_f32_16x16x32_bf16 v[34:37], v[172:175], v[206:209], v[34:37]
	v_mfma_f32_16x16x32_bf16 v[62:65], v[168:171], v[184:187], v[62:65]
	v_mfma_f32_16x16x32_bf16 v[58:61], v[176:179], v[184:187], v[58:61]
	v_mfma_f32_16x16x32_bf16 v[54:57], v[168:171], v[192:195], v[54:57]
	v_mfma_f32_16x16x32_bf16 v[50:53], v[176:179], v[192:195], v[50:53]
	v_mfma_f32_16x16x32_bf16 v[46:49], v[168:171], v[202:205], v[46:49]
	v_mfma_f32_16x16x32_bf16 v[42:45], v[176:179], v[202:205], v[42:45]
	v_mfma_f32_16x16x32_bf16 v[38:41], v[168:171], v[216:219], v[38:41]
	v_mfma_f32_16x16x32_bf16 v[34:37], v[176:179], v[216:219], v[34:37]
	v_mfma_f32_16x16x32_bf16 v[30:33], v[222:225], v[180:183], v[30:33]
	v_mfma_f32_16x16x32_bf16 v[26:29], v[232:235], v[180:183], v[26:29]
	v_mfma_f32_16x16x32_bf16 v[22:25], v[222:225], v[188:191], v[22:25]
	v_mfma_f32_16x16x32_bf16 v[18:21], v[232:235], v[188:191], v[18:21]
	v_mfma_f32_16x16x32_bf16 v[14:17], v[222:225], v[196:199], v[14:17]
	v_mfma_f32_16x16x32_bf16 v[10:13], v[232:235], v[196:199], v[10:13]
	v_mfma_f32_16x16x32_bf16 v[6:9], v[222:225], v[206:209], v[6:9]
	v_mfma_f32_16x16x32_bf16 v[2:5], v[232:235], v[206:209], v[2:5]
	v_mfma_f32_16x16x32_bf16 v[30:33], v[228:231], v[184:187], v[30:33]
	v_mfma_f32_16x16x32_bf16 v[26:29], v[236:239], v[184:187], v[26:29]
	v_mfma_f32_16x16x32_bf16 v[22:25], v[228:231], v[192:195], v[22:25]
	v_mfma_f32_16x16x32_bf16 v[18:21], v[236:239], v[192:195], v[18:21]
	v_mfma_f32_16x16x32_bf16 v[14:17], v[228:231], v[202:205], v[14:17]
	v_mfma_f32_16x16x32_bf16 v[10:13], v[236:239], v[202:205], v[10:13]
	v_mfma_f32_16x16x32_bf16 v[6:9], v[228:231], v[216:219], v[6:9]
	v_mfma_f32_16x16x32_bf16 v[2:5], v[236:239], v[216:219], v[2:5]
	s_barrier
	ds_read_b128 v[164:167], v149
	ds_read_b128 v[168:171], v149 offset:1024
	ds_read_b128 v[172:175], v149 offset:2048
	ds_read_b128 v[176:179], v149 offset:3072
	ds_read_b128 v[180:183], v147 offset:32768
	ds_read_b128 v[184:187], v147 offset:33792
	ds_read_b128 v[188:191], v146 offset:32768
	ds_read_b128 v[192:195], v146 offset:33792
	ds_read_b128 v[196:199], v145 offset:32768
	ds_read_b128 v[202:205], v145 offset:33792
	ds_read_b128 v[206:209], v144 offset:32768
	ds_read_b128 v[216:219], v144 offset:33792
	s_waitcnt lgkmcnt(6)
	ds_read_b128 v[222:225], v148
	ds_read_b128 v[228:231], v148 offset:1024
	ds_read_b128 v[232:235], v148 offset:2048
	ds_read_b128 v[236:239], v148 offset:3072
	v_readfirstlane_b32 s2, v134
	v_lshl_add_u64 v[246:247], v[210:211], 0, s[48:49]
	s_mov_b32 m0, s2
	v_readfirstlane_b32 s2, v133
	global_load_lds_dwordx4 v[246:247], off
	v_lshl_add_u64 v[246:247], v[210:211], 0, s[50:51]
	s_mov_b32 m0, s2
	s_nop 0
	global_load_lds_dwordx4 v[246:247], off
	s_waitcnt vmcnt(8)
	s_barrier
	s_waitcnt lgkmcnt(0)
	v_mfma_f32_16x16x32_bf16 v[126:129], v[164:167], v[180:183], v[126:129]
	v_mfma_f32_16x16x32_bf16 v[122:125], v[172:175], v[180:183], v[122:125]
	v_mfma_f32_16x16x32_bf16 v[118:121], v[164:167], v[188:191], v[118:121]
	v_mfma_f32_16x16x32_bf16 v[114:117], v[172:175], v[188:191], v[114:117]
	v_mfma_f32_16x16x32_bf16 v[110:113], v[164:167], v[196:199], v[110:113]
	v_mfma_f32_16x16x32_bf16 v[106:109], v[172:175], v[196:199], v[106:109]
	v_mfma_f32_16x16x32_bf16 v[102:105], v[164:167], v[206:209], v[102:105]
	v_mfma_f32_16x16x32_bf16 v[98:101], v[172:175], v[206:209], v[98:101]
	v_mfma_f32_16x16x32_bf16 v[126:129], v[168:171], v[184:187], v[126:129]
	v_mfma_f32_16x16x32_bf16 v[122:125], v[176:179], v[184:187], v[122:125]
	v_mfma_f32_16x16x32_bf16 v[118:121], v[168:171], v[192:195], v[118:121]
	v_mfma_f32_16x16x32_bf16 v[114:117], v[176:179], v[192:195], v[114:117]
	v_mfma_f32_16x16x32_bf16 v[110:113], v[168:171], v[202:205], v[110:113]
	v_mfma_f32_16x16x32_bf16 v[106:109], v[176:179], v[202:205], v[106:109]
	v_mfma_f32_16x16x32_bf16 v[102:105], v[168:171], v[216:219], v[102:105]
	v_mfma_f32_16x16x32_bf16 v[98:101], v[176:179], v[216:219], v[98:101]
	v_mfma_f32_16x16x32_bf16 v[94:97], v[222:225], v[180:183], v[94:97]
	v_mfma_f32_16x16x32_bf16 v[90:93], v[232:235], v[180:183], v[90:93]
	v_mfma_f32_16x16x32_bf16 v[86:89], v[222:225], v[188:191], v[86:89]
	v_mfma_f32_16x16x32_bf16 v[82:85], v[232:235], v[188:191], v[82:85]
	v_mfma_f32_16x16x32_bf16 v[78:81], v[222:225], v[196:199], v[78:81]
	v_mfma_f32_16x16x32_bf16 v[74:77], v[232:235], v[196:199], v[74:77]
	v_mfma_f32_16x16x32_bf16 v[70:73], v[222:225], v[206:209], v[70:73]
	v_mfma_f32_16x16x32_bf16 v[66:69], v[232:235], v[206:209], v[66:69]
	v_mfma_f32_16x16x32_bf16 v[94:97], v[228:231], v[184:187], v[94:97]
	v_mfma_f32_16x16x32_bf16 v[90:93], v[236:239], v[184:187], v[90:93]
	v_mfma_f32_16x16x32_bf16 v[86:89], v[228:231], v[192:195], v[86:89]
	v_mfma_f32_16x16x32_bf16 v[82:85], v[236:239], v[192:195], v[82:85]
	v_mfma_f32_16x16x32_bf16 v[78:81], v[228:231], v[202:205], v[78:81]
	v_mfma_f32_16x16x32_bf16 v[74:77], v[236:239], v[202:205], v[74:77]
	v_mfma_f32_16x16x32_bf16 v[70:73], v[228:231], v[216:219], v[70:73]
	v_mfma_f32_16x16x32_bf16 v[66:69], v[236:239], v[216:219], v[66:69]
	s_barrier
; #define STAGE_B(P, br, kt) do { const char* _gb = (const char*)(Bt + ((long)(br) * K + (long)(kt) * BK)); \
;     __builtin_amdgcn_global_load_lds((const unsigned*)(_gb + bofl0), (unsigned*)((char*)(P) + gtid_ * 16), 16, 0, 0); \
;     __builtin_amdgcn_global_load_lds((const unsigned*)(_gb + (long)K * 128 + bofl0), (unsigned*)((char*)(P) + gtid_ * 16 + 8192), 16, 0, 0); } while (0)
; #define LDA(dst, b, h) for (int m = 0; m < 4; ++m) for (int k = 0; k < 2; ++k) \
;     dst[m][k] = *reinterpret_cast<const bf16x8*>((char*)SA(b, h) + lds_byte(wr * 64 + m * 16 + fr, k * 32 + fq * 8))
; #define LDB(dst, b, h) for (int n = 0; n < 2; ++n) for (int k = 0; k < 2; ++k) \
;     dst[n][k] = *reinterpret_cast<const bf16x8*>((char*)SB(b, h) + lds_byte(wc * 32 + n * 16 + fr, k * 32 + fq * 8))
; #define MMA(ai, bj, At_, Bt_) do { __builtin_amdgcn_s_setprio(1); \
;     for (int m = 0; m < 4; ++m) for (int n = 0; n < 2; ++n) for (int k = 0; k < 2; ++k) \
;       acc[ai][bj][m][n] = __builtin_amdgcn_mfma_f32_16x16x32_bf16(At_[m][k], Bt_[n][k], acc[ai][bj][m][n], 0, 0, 0); \
;     __builtin_amdgcn_s_setprio(0); } while (0)
; #define WAIT_V(n) asm volatile("s_waitcnt vmcnt(" #n ")" ::: "memory")
; #define WAIT_L(n) asm volatile("s_waitcnt lgkmcnt(" #n ")" ::: "memory")
; #define BAR __builtin_amdgcn_s_barrier()
; #define SCHED __builtin_amdgcn_sched_barrier(0)
; template <int EPI>
; __device__ __forceinline__ void gemm_tile(const GemmArgs& g, int brow, int bcol, int parity, bool first, bool nvalid, int nbrow, int nbcol) {
;     ...
;     BAR; WAIT_L(0); MMA(1, 0, At, B0); BAR; SCHED;
;     STAGE_B(SB(1, 1), bcol + HALF, t + 3);
;     WAIT_V(6); BAR; MMA(1, 1, At, B1); BAR; SCHED;
;   }
;   { LDB(B0, 0, 0); LDA(At, 0, 0); STAGE_A(SA(1, 1), brow + HALF, nt - 1);
;     BAR; WAIT_L(0); MMA(0, 0, At, B0); BAR;
	ds_read_b128 v[180:183], v147 offset:49152
	ds_read_b128 v[184:187], v147 offset:50176
	ds_read_b128 v[188:191], v146 offset:49152
	ds_read_b128 v[192:195], v146 offset:50176
	ds_read_b128 v[196:199], v145 offset:49152
	ds_read_b128 v[202:205], v145 offset:50176
	ds_read_b128 v[206:209], v144 offset:49152
	ds_read_b128 v[216:219], v144 offset:50176
	v_readfirstlane_b32 s2, v150
	v_lshl_add_u64 v[240:241], v[212:213], 0, s[58:59]
	s_mov_b32 m0, s2
	v_readfirstlane_b32 s2, v151
	global_load_lds_dwordx4 v[240:241], off
	v_lshl_add_u64 v[240:241], v[212:213], 0, vcc
	s_mov_b32 m0, s2
	s_nop 0
	global_load_lds_dwordx4 v[240:241], off
	v_readfirstlane_b32 s2, v152
	v_lshl_add_u64 v[240:241], v[210:211], 0, s[52:53]
	s_mov_b32 m0, s2
	v_readfirstlane_b32 s2, v153
	global_load_lds_dwordx4 v[240:241], off
	v_lshl_add_u64 v[210:211], v[210:211], 0, s[56:57]
	s_mov_b32 m0, s2
	s_nop 0
	global_load_lds_dwordx4 v[210:211], off
	v_readfirstlane_b32 s2, v155
	v_lshl_add_u64 v[244:245], v[212:213], 0, s[60:61]
	s_mov_b32 m0, s2
	v_readfirstlane_b32 s2, v156
	global_load_lds_dwordx4 v[244:245], off
	v_lshl_add_u64 v[244:245], v[212:213], 0, s[94:95]
	s_mov_b32 m0, s2
	s_nop 0
	global_load_lds_dwordx4 v[244:245], off
	s_waitcnt vmcnt(8)
	s_barrier
	s_waitcnt lgkmcnt(0)
	v_mfma_f32_16x16x32_bf16 v[62:65], v[164:167], v[180:183], v[62:65]
	v_mfma_f32_16x16x32_bf16 v[58:61], v[172:175], v[180:183], v[58:61]
	v_mfma_f32_16x16x32_bf16 v[54:57], v[164:167], v[188:191], v[54:57]
	v_mfma_f32_16x16x32_bf16 v[50:53], v[172:175], v[188:191], v[50:53]
	v_mfma_f32_16x16x32_bf16 v[46:49], v[164:167], v[196:199], v[46:49]
	v_mfma_f32_16x16x32_bf16 v[42:45], v[172:175], v[196:199], v[42:45]
	v_mfma_f32_16x16x32_bf16 v[38:41], v[164:167], v[206:209], v[38:41]
	v_mfma_f32_16x16x32_bf16 v[34:37], v[172:175], v[206:209], v[34:37]
	v_mfma_f32_16x16x32_bf16 v[62:65], v[168:171], v[184:187], v[62:65]
	v_mfma_f32_16x16x32_bf16 v[58:61], v[176:179], v[184:187], v[58:61]
	v_mfma_f32_16x16x32_bf16 v[54:57], v[168:171], v[192:195], v[54:57]
	v_mfma_f32_16x16x32_bf16 v[50:53], v[176:179], v[192:195], v[50:53]
	v_mfma_f32_16x16x32_bf16 v[46:49], v[168:171], v[202:205], v[46:49]
	v_mfma_f32_16x16x32_bf16 v[42:45], v[176:179], v[202:205], v[42:45]
	v_mfma_f32_16x16x32_bf16 v[38:41], v[168:171], v[216:219], v[38:41]
	v_mfma_f32_16x16x32_bf16 v[34:37], v[176:179], v[216:219], v[34:37]
	v_mfma_f32_16x16x32_bf16 v[30:33], v[222:225], v[180:183], v[30:33]
	v_mfma_f32_16x16x32_bf16 v[26:29], v[232:235], v[180:183], v[26:29]
	v_mfma_f32_16x16x32_bf16 v[22:25], v[222:225], v[188:191], v[22:25]
	v_mfma_f32_16x16x32_bf16 v[18:21], v[232:235], v[188:191], v[18:21]
	v_mfma_f32_16x16x32_bf16 v[14:17], v[222:225], v[196:199], v[14:17]
	v_mfma_f32_16x16x32_bf16 v[10:13], v[232:235], v[196:199], v[10:13]
	v_mfma_f32_16x16x32_bf16 v[6:9], v[222:225], v[206:209], v[6:9]
	v_mfma_f32_16x16x32_bf16 v[2:5], v[232:235], v[206:209], v[2:5]
	v_mfma_f32_16x16x32_bf16 v[30:33], v[228:231], v[184:187], v[30:33]
	v_mfma_f32_16x16x32_bf16 v[26:29], v[236:239], v[184:187], v[26:29]
	v_mfma_f32_16x16x32_bf16 v[22:25], v[228:231], v[192:195], v[22:25]
	v_mfma_f32_16x16x32_bf16 v[18:21], v[236:239], v[192:195], v[18:21]
	v_mfma_f32_16x16x32_bf16 v[14:17], v[228:231], v[202:205], v[14:17]
	v_mfma_f32_16x16x32_bf16 v[10:13], v[236:239], v[202:205], v[10:13]
	v_mfma_f32_16x16x32_bf16 v[6:9], v[228:231], v[216:219], v[6:9]
	v_mfma_f32_16x16x32_bf16 v[2:5], v[236:239], v[216:219], v[2:5]
	s_add_i32 s25, s25, 2
	s_add_u32 s0, s0, 0x100
	s_addc_u32 s1, s1, 0
	s_add_u32 s12, s12, 0x100
	s_addc_u32 s13, s13, 0
	s_cmp_lt_u32 s25, 12
	s_cbranch_scc1 .LBB0_166
	s_barrier
	s_or_b32 s0, s38, 0x80
	s_ashr_i32 s1, s0, 31
	s_lshl_b64 s[0:1], s[0:1], 11
	s_add_u32 s0, s80, s0
	s_addc_u32 s1, s81, s1
	v_lshl_add_u64 v[130:131], s[0:1], 0, v[0:1]
	s_mov_b64 s[0:1], 0x780
	ds_read_b128 v[150:153], v157
	ds_read_b128 v[164:167], v157 offset:1024
	ds_read_b128 v[168:171], v157 offset:2048
	ds_read_b128 v[172:175], v157 offset:3072
	ds_read_b128 v[176:179], v147
	ds_read_b128 v[180:183], v147 offset:1024
	ds_read_b128 v[184:187], v146
	ds_read_b128 v[188:191], v146 offset:1024
	ds_read_b128 v[192:195], v145
	ds_read_b128 v[196:199], v145 offset:1024
	ds_read_b128 v[202:205], v144
	ds_read_b128 v[206:209], v144 offset:1024
	v_lshl_add_u64 v[156:157], v[130:131], 0, s[0:1]
	v_readfirstlane_b32 s0, v161
	s_mov_b32 m0, s0
	s_mov_b64 s[0:1], 0x20780
	v_lshl_add_u64 v[130:131], v[130:131], 0, s[0:1]
	v_readfirstlane_b32 s0, v162
	global_load_lds_dwordx4 v[156:157], off
	s_mov_b32 m0, s0
	s_nop 0
	global_load_lds_dwordx4 v[130:131], off
	s_waitcnt vmcnt(8)
	s_barrier
	s_waitcnt lgkmcnt(0)
	s_setprio 1
	s_waitcnt lgkmcnt(0)
	v_mfma_f32_16x16x32_bf16 v[126:129], v[150:153], v[176:179], v[126:129]
	v_mfma_f32_16x16x32_bf16 v[118:121], v[150:153], v[184:187], v[118:121]
	v_mfma_f32_16x16x32_bf16 v[110:113], v[150:153], v[192:195], v[110:113]
	v_mfma_f32_16x16x32_bf16 v[102:105], v[150:153], v[202:205], v[102:105]
	v_mfma_f32_16x16x32_bf16 v[126:129], v[164:167], v[180:183], v[126:129]
	v_mfma_f32_16x16x32_bf16 v[122:125], v[168:171], v[176:179], v[122:125]
	v_mfma_f32_16x16x32_bf16 v[118:121], v[164:167], v[188:191], v[118:121]
	v_mfma_f32_16x16x32_bf16 v[114:117], v[168:171], v[184:187], v[114:117]
	v_mfma_f32_16x16x32_bf16 v[110:113], v[164:167], v[196:199], v[110:113]
	v_mfma_f32_16x16x32_bf16 v[106:109], v[168:171], v[192:195], v[106:109]
	v_mfma_f32_16x16x32_bf16 v[102:105], v[164:167], v[206:209], v[102:105]
	v_mfma_f32_16x16x32_bf16 v[98:101], v[168:171], v[202:205], v[98:101]
	v_mfma_f32_16x16x32_bf16 v[216:219], v[172:175], v[180:183], v[122:125]
	v_mfma_f32_16x16x32_bf16 v[222:225], v[172:175], v[188:191], v[114:117]
	v_mfma_f32_16x16x32_bf16 v[228:231], v[172:175], v[196:199], v[106:109]
	v_mfma_f32_16x16x32_bf16 v[232:235], v[172:175], v[206:209], v[98:101]
	s_setprio 0
	s_barrier
; #define LDA(dst, b, h) for (int m = 0; m < 4; ++m) for (int k = 0; k < 2; ++k) \
;     dst[m][k] = *reinterpret_cast<const bf16x8*>((char*)SA(b, h) + lds_byte(wr * 64 + m * 16 + fr, k * 32 + fq * 8))
; #define LDB(dst, b, h) for (int n = 0; n < 2; ++n) for (int k = 0; k < 2; ++k) \
;     dst[n][k] = *reinterpret_cast<const bf16x8*>((char*)SB(b, h) + lds_byte(wc * 32 + n * 16 + fr, k * 32 + fq * 8))
; #define MMA(ai, bj, At_, Bt_) do { __builtin_amdgcn_s_setprio(1); \
;     for (int m = 0; m < 4; ++m) for (int n = 0; n < 2; ++n) for (int k = 0; k < 2; ++k) \
;       acc[ai][bj][m][n] = __builtin_amdgcn_mfma_f32_16x16x32_bf16(At_[m][k], Bt_[n][k], acc[ai][bj][m][n], 0, 0, 0); \
;     __builtin_amdgcn_s_setprio(0); } while (0)
; #define WAIT_V(n) asm volatile("s_waitcnt vmcnt(" #n ")" ::: "memory")
; #define WAIT_L(n) asm volatile("s_waitcnt lgkmcnt(" #n ")" ::: "memory")
; #define BAR __builtin_amdgcn_s_barrier()
; #define SCHED __builtin_amdgcn_sched_barrier(0)
; template <int EPI>
; __device__ __forceinline__ void gemm_tile(const GemmArgs& g, int brow, int bcol, int parity, bool first, bool nvalid, int nbrow, int nbcol) {
;     ...
;     BAR; WAIT_L(0); MMA(0, 0, At, B0); BAR;
;     LDB(B1, 0, 1); BAR; WAIT_L(0); MMA(0, 1, At, B1); BAR; SCHED;
;     LDA(At, 0, 1); WAIT_V(4); BAR; WAIT_L(0); MMA(1, 0, At, B0); MMA(1, 1, At, B1); BAR; }
;   { LDB(B0, 1, 0); LDA(At, 1, 0); WAIT_V(2); BAR; WAIT_L(0); MMA(0, 0, At, B0); BAR;
	s_nop 1
	ds_read_b128 v[98:101], v154
	ds_read_b128 v[106:109], v154 offset:1024
	ds_read_b128 v[114:117], v154 offset:2048
	ds_read_b128 v[122:125], v154 offset:3072
	s_barrier
	s_waitcnt lgkmcnt(0)
	s_setprio 1
	s_waitcnt lgkmcnt(0)
	v_mfma_f32_16x16x32_bf16 v[94:97], v[98:101], v[176:179], v[94:97]
	v_mfma_f32_16x16x32_bf16 v[86:89], v[98:101], v[184:187], v[86:89]
	v_mfma_f32_16x16x32_bf16 v[78:81], v[98:101], v[192:195], v[78:81]
	v_mfma_f32_16x16x32_bf16 v[74:77], v[114:117], v[192:195], v[74:77]
	v_mfma_f32_16x16x32_bf16 v[94:97], v[106:109], v[180:183], v[94:97]
	v_mfma_f32_16x16x32_bf16 v[90:93], v[114:117], v[176:179], v[90:93]
	v_mfma_f32_16x16x32_bf16 v[86:89], v[106:109], v[188:191], v[86:89]
	v_mfma_f32_16x16x32_bf16 v[82:85], v[114:117], v[184:187], v[82:85]
	v_mfma_f32_16x16x32_bf16 v[78:81], v[106:109], v[196:199], v[78:81]
	v_mfma_f32_16x16x32_bf16 v[74:77], v[122:125], v[196:199], v[74:77]
	v_mfma_f32_16x16x32_bf16 v[70:73], v[98:101], v[202:205], v[70:73]
	v_mfma_f32_16x16x32_bf16 v[66:69], v[114:117], v[202:205], v[66:69]
	v_mfma_f32_16x16x32_bf16 v[154:157], v[122:125], v[180:183], v[90:93]
	v_mfma_f32_16x16x32_bf16 v[176:179], v[122:125], v[188:191], v[82:85]
	v_mfma_f32_16x16x32_bf16 v[180:183], v[106:109], v[206:209], v[70:73]
	v_mfma_f32_16x16x32_bf16 v[184:187], v[122:125], v[206:209], v[66:69]
	s_setprio 0
	s_barrier
	s_nop 1
	ds_read_b128 v[66:69], v147 offset:16384
	ds_read_b128 v[70:73], v147 offset:17408
	ds_read_b128 v[82:85], v146 offset:16384
	ds_read_b128 v[90:93], v146 offset:17408
	ds_read_b128 v[188:191], v145 offset:16384
	ds_read_b128 v[192:195], v145 offset:17408
	ds_read_b128 v[196:199], v144 offset:16384
	ds_read_b128 v[202:205], v144 offset:17408
	s_waitcnt vmcnt(4)
	s_barrier
	s_waitcnt lgkmcnt(0)
	s_setprio 1
	s_waitcnt lgkmcnt(0)
	v_mfma_f32_16x16x32_bf16 v[62:65], v[150:153], v[66:69], v[62:65]
	v_mfma_f32_16x16x32_bf16 v[54:57], v[150:153], v[82:85], v[54:57]
	v_mfma_f32_16x16x32_bf16 v[46:49], v[150:153], v[188:191], v[46:49]
	v_mfma_f32_16x16x32_bf16 v[38:41], v[150:153], v[196:199], v[38:41]
	v_mfma_f32_16x16x32_bf16 v[62:65], v[164:167], v[70:73], v[62:65]
	v_mfma_f32_16x16x32_bf16 v[58:61], v[168:171], v[66:69], v[58:61]
	v_mfma_f32_16x16x32_bf16 v[54:57], v[164:167], v[90:93], v[54:57]
	v_mfma_f32_16x16x32_bf16 v[50:53], v[168:171], v[82:85], v[50:53]
	v_mfma_f32_16x16x32_bf16 v[46:49], v[164:167], v[192:195], v[46:49]
	v_mfma_f32_16x16x32_bf16 v[42:45], v[168:171], v[188:191], v[42:45]
	v_mfma_f32_16x16x32_bf16 v[38:41], v[164:167], v[202:205], v[38:41]
	v_mfma_f32_16x16x32_bf16 v[34:37], v[168:171], v[196:199], v[34:37]
	v_mfma_f32_16x16x32_bf16 v[206:209], v[172:175], v[70:73], v[58:61]
	v_mfma_f32_16x16x32_bf16 v[236:239], v[172:175], v[90:93], v[50:53]
	v_mfma_f32_16x16x32_bf16 v[240:243], v[172:175], v[192:195], v[42:45]
	v_mfma_f32_16x16x32_bf16 v[150:153], v[172:175], v[202:205], v[34:37]
	s_setprio 0
	s_setprio 1
	v_mfma_f32_16x16x32_bf16 v[30:33], v[98:101], v[66:69], v[30:33]
	v_mfma_f32_16x16x32_bf16 v[22:25], v[98:101], v[82:85], v[22:25]
	v_mfma_f32_16x16x32_bf16 v[14:17], v[98:101], v[188:191], v[14:17]
	v_mfma_f32_16x16x32_bf16 v[10:13], v[114:117], v[188:191], v[10:13]
	v_mfma_f32_16x16x32_bf16 v[30:33], v[106:109], v[70:73], v[30:33]
	v_mfma_f32_16x16x32_bf16 v[26:29], v[114:117], v[66:69], v[26:29]
	v_mfma_f32_16x16x32_bf16 v[22:25], v[106:109], v[90:93], v[22:25]
	v_mfma_f32_16x16x32_bf16 v[18:21], v[114:117], v[82:85], v[18:21]
	v_mfma_f32_16x16x32_bf16 v[14:17], v[106:109], v[192:195], v[14:17]
	v_mfma_f32_16x16x32_bf16 v[10:13], v[122:125], v[192:195], v[10:13]
	v_mfma_f32_16x16x32_bf16 v[6:9], v[98:101], v[196:199], v[6:9]
	v_mfma_f32_16x16x32_bf16 v[2:5], v[114:117], v[196:199], v[2:5]
	v_mfma_f32_16x16x32_bf16 v[162:165], v[122:125], v[70:73], v[26:29]
	v_mfma_f32_16x16x32_bf16 v[166:169], v[122:125], v[90:93], v[18:21]
	v_mfma_f32_16x16x32_bf16 v[170:173], v[106:109], v[202:205], v[6:9]
	v_mfma_f32_16x16x32_bf16 v[188:191], v[122:125], v[202:205], v[2:5]
	s_setprio 0
	s_barrier
	s_nop 1
	ds_read_b128 v[2:5], v149
	ds_read_b128 v[6:9], v149 offset:1024
	ds_read_b128 v[192:195], v149 offset:2048
	ds_read_b128 v[196:199], v149 offset:3072
	ds_read_b128 v[18:21], v147 offset:32768
	ds_read_b128 v[26:29], v147 offset:33792
	ds_read_b128 v[34:37], v146 offset:32768
	ds_read_b128 v[42:45], v146 offset:33792
	ds_read_b128 v[50:53], v145 offset:32768
	ds_read_b128 v[58:61], v145 offset:33792
	ds_read_b128 v[202:205], v144 offset:32768
	ds_read_b128 v[244:247], v144 offset:33792
	s_waitcnt vmcnt(2)
	s_barrier
; #define LDA(dst, b, h) for (int m = 0; m < 4; ++m) for (int k = 0; k < 2; ++k) \
;     dst[m][k] = *reinterpret_cast<const bf16x8*>((char*)SA(b, h) + lds_byte(wr * 64 + m * 16 + fr, k * 32 + fq * 8))
; #define LDB(dst, b, h) for (int n = 0; n < 2; ++n) for (int k = 0; k < 2; ++k) \
;     dst[n][k] = *reinterpret_cast<const bf16x8*>((char*)SB(b, h) + lds_byte(wc * 32 + n * 16 + fr, k * 32 + fq * 8))
; #define MMA(ai, bj, At_, Bt_) do { __builtin_amdgcn_s_setprio(1); \
;     for (int m = 0; m < 4; ++m) for (int n = 0; n < 2; ++n) for (int k = 0; k < 2; ++k) \
;       acc[ai][bj][m][n] = __builtin_amdgcn_mfma_f32_16x16x32_bf16(At_[m][k], Bt_[n][k], acc[ai][bj][m][n], 0, 0, 0); \
;     __builtin_amdgcn_s_setprio(0); } while (0)
; #define WAIT_V(n) asm volatile("s_waitcnt vmcnt(" #n ")" ::: "memory")
; #define WAIT_L(n) asm volatile("s_waitcnt lgkmcnt(" #n ")" ::: "memory")
; #define BAR __builtin_amdgcn_s_barrier()
; #define SCHED __builtin_amdgcn_sched_barrier(0)
; template <int EPI>
; __device__ __forceinline__ void gemm_tile(const GemmArgs& g, int brow, int bcol, int parity, bool first, bool nvalid, int nbrow, int nbcol) {
;     ...
;   { LDB(B0, 1, 0); LDA(At, 1, 0); WAIT_V(2); BAR; WAIT_L(0); MMA(0, 0, At, B0); BAR;
;     LDB(B1, 1, 1); WAIT_V(0); BAR; WAIT_L(0); MMA(0, 1, At, B1); BAR; SCHED;
;     LDA(At, 1, 1); BAR; WAIT_L(0); MMA(1, 0, At, B0); MMA(1, 1, At, B1); BAR; }
;   if (wr == 0) BAR;
	s_waitcnt lgkmcnt(0)
	s_setprio 1
	s_waitcnt lgkmcnt(0)
	v_mfma_f32_16x16x32_bf16 v[66:69], v[2:5], v[18:21], v[126:129]
	v_mfma_f32_16x16x32_bf16 v[122:125], v[6:9], v[26:29], v[66:69]
	v_mfma_f32_16x16x32_bf16 v[66:69], v[192:195], v[18:21], v[216:219]
	v_mfma_f32_16x16x32_bf16 v[114:117], v[196:199], v[26:29], v[66:69]
	v_mfma_f32_16x16x32_bf16 v[66:69], v[2:5], v[34:37], v[118:121]
	v_mfma_f32_16x16x32_bf16 v[106:109], v[6:9], v[42:45], v[66:69]
	v_mfma_f32_16x16x32_bf16 v[66:69], v[192:195], v[34:37], v[222:225]
	v_mfma_f32_16x16x32_bf16 v[98:101], v[196:199], v[42:45], v[66:69]
	v_mfma_f32_16x16x32_bf16 v[66:69], v[2:5], v[50:53], v[110:113]
	v_mfma_f32_16x16x32_bf16 v[90:93], v[6:9], v[58:61], v[66:69]
	v_mfma_f32_16x16x32_bf16 v[66:69], v[192:195], v[50:53], v[228:231]
	v_mfma_f32_16x16x32_bf16 v[82:85], v[196:199], v[58:61], v[66:69]
	v_mfma_f32_16x16x32_bf16 v[66:69], v[2:5], v[202:205], v[102:105]
	v_mfma_f32_16x16x32_bf16 v[70:73], v[6:9], v[244:247], v[66:69]
	v_mfma_f32_16x16x32_bf16 v[66:69], v[192:195], v[202:205], v[232:235]
	v_mfma_f32_16x16x32_bf16 v[66:69], v[196:199], v[244:247], v[66:69]
	s_setprio 0
	s_barrier
	ds_read_b128 v[216:219], v148
	ds_read_b128 v[222:225], v148 offset:1024
	ds_read_b128 v[228:231], v148 offset:2048
	ds_read_b128 v[232:235], v148 offset:3072
	s_waitcnt vmcnt(0)
	s_barrier
	s_waitcnt lgkmcnt(0)
	s_setprio 1
	s_waitcnt lgkmcnt(0)
	v_mfma_f32_16x16x32_bf16 v[94:97], v[216:219], v[18:21], v[94:97]
	v_mfma_f32_16x16x32_bf16 v[18:21], v[228:231], v[18:21], v[154:157]
	v_mfma_f32_16x16x32_bf16 v[118:121], v[232:235], v[26:29], v[18:21]
	v_mfma_f32_16x16x32_bf16 v[18:21], v[216:219], v[34:37], v[86:89]
	v_mfma_f32_16x16x32_bf16 v[110:113], v[222:225], v[42:45], v[18:21]
	v_mfma_f32_16x16x32_bf16 v[18:21], v[228:231], v[34:37], v[176:179]
	v_mfma_f32_16x16x32_bf16 v[102:105], v[232:235], v[42:45], v[18:21]
	v_mfma_f32_16x16x32_bf16 v[18:21], v[216:219], v[50:53], v[78:81]
	v_mfma_f32_16x16x32_bf16 v[126:129], v[222:225], v[26:29], v[94:97]
	v_mfma_f32_16x16x32_bf16 v[94:97], v[222:225], v[58:61], v[18:21]
	v_mfma_f32_16x16x32_bf16 v[18:21], v[228:231], v[50:53], v[74:77]
	v_mfma_f32_16x16x32_bf16 v[86:89], v[232:235], v[58:61], v[18:21]
	v_mfma_f32_16x16x32_bf16 v[18:21], v[216:219], v[202:205], v[180:183]
	v_mfma_f32_16x16x32_bf16 v[78:81], v[222:225], v[244:247], v[18:21]
	v_mfma_f32_16x16x32_bf16 v[18:21], v[228:231], v[202:205], v[184:187]
	v_mfma_f32_16x16x32_bf16 v[74:77], v[232:235], v[244:247], v[18:21]
	s_setprio 0
	s_barrier
	ds_read_b128 v[154:157], v147 offset:49152
	ds_read_b128 v[174:177], v147 offset:50176
	ds_read_b128 v[178:181], v146 offset:49152
	ds_read_b128 v[146:149], v146 offset:50176
	ds_read_b128 v[182:185], v145 offset:49152
	ds_read_b128 v[202:205], v145 offset:50176
	ds_read_b128 v[244:247], v144 offset:49152
	ds_read_b128 v[248:251], v144 offset:50176
	s_barrier
	s_waitcnt lgkmcnt(0)
	s_setprio 1
	s_waitcnt lgkmcnt(0)
	v_mfma_f32_16x16x32_bf16 v[18:21], v[2:5], v[154:157], v[62:65]
	v_mfma_f32_16x16x32_bf16 v[58:61], v[6:9], v[174:177], v[18:21]
	v_mfma_f32_16x16x32_bf16 v[18:21], v[192:195], v[154:157], v[206:209]
	v_mfma_f32_16x16x32_bf16 v[50:53], v[196:199], v[174:177], v[18:21]
	v_mfma_f32_16x16x32_bf16 v[18:21], v[2:5], v[178:181], v[54:57]
	v_mfma_f32_16x16x32_bf16 v[42:45], v[6:9], v[146:149], v[18:21]
	v_mfma_f32_16x16x32_bf16 v[18:21], v[192:195], v[178:181], v[236:239]
	v_mfma_f32_16x16x32_bf16 v[34:37], v[196:199], v[146:149], v[18:21]
	v_mfma_f32_16x16x32_bf16 v[18:21], v[2:5], v[182:185], v[46:49]
	v_mfma_f32_16x16x32_bf16 v[2:5], v[2:5], v[244:247], v[38:41]
	v_mfma_f32_16x16x32_bf16 v[26:29], v[6:9], v[202:205], v[18:21]
	v_mfma_f32_16x16x32_bf16 v[18:21], v[192:195], v[182:185], v[240:243]
	v_mfma_f32_16x16x32_bf16 v[6:9], v[6:9], v[248:251], v[2:5]
	v_mfma_f32_16x16x32_bf16 v[2:5], v[192:195], v[244:247], v[150:153]
	v_mfma_f32_16x16x32_bf16 v[18:21], v[196:199], v[202:205], v[18:21]
	v_mfma_f32_16x16x32_bf16 v[2:5], v[196:199], v[248:251], v[2:5]
	s_setprio 0
	s_setprio 1
	v_mfma_f32_16x16x32_bf16 v[22:25], v[216:219], v[178:181], v[22:25]
	v_mfma_f32_16x16x32_bf16 v[30:33], v[216:219], v[154:157], v[30:33]
	v_mfma_f32_16x16x32_bf16 v[46:49], v[222:225], v[146:149], v[22:25]
	v_mfma_f32_16x16x32_bf16 v[22:25], v[228:231], v[178:181], v[166:169]
	v_mfma_f32_16x16x32_bf16 v[10:13], v[228:231], v[182:185], v[10:13]
	v_mfma_f32_16x16x32_bf16 v[62:65], v[222:225], v[174:177], v[30:33]
	v_mfma_f32_16x16x32_bf16 v[30:33], v[228:231], v[154:157], v[162:165]
	v_mfma_f32_16x16x32_bf16 v[38:41], v[232:235], v[146:149], v[22:25]
	v_mfma_f32_16x16x32_bf16 v[14:17], v[216:219], v[182:185], v[14:17]
	v_mfma_f32_16x16x32_bf16 v[22:25], v[232:235], v[202:205], v[10:13]
	v_mfma_f32_16x16x32_bf16 v[10:13], v[216:219], v[244:247], v[170:173]
	v_mfma_f32_16x16x32_bf16 v[54:57], v[232:235], v[174:177], v[30:33]
	v_mfma_f32_16x16x32_bf16 v[30:33], v[222:225], v[202:205], v[14:17]
	v_mfma_f32_16x16x32_bf16 v[14:17], v[222:225], v[248:251], v[10:13]
	v_mfma_f32_16x16x32_bf16 v[10:13], v[228:231], v[244:247], v[188:191]
	v_mfma_f32_16x16x32_bf16 v[10:13], v[232:235], v[248:251], v[10:13]
	s_setprio 0
	s_movk_i32 s0, 0x100
	v_cmp_gt_u32_e32 vcc, s0, v138
	s_barrier
	s_and_saveexec_b64 s[0:1], vcc
	s_cbranch_execz .LBB0_169
	s_barrier

; #define STAGE_B(P, br, kt) do { const char* _gb = (const char*)(Bt + ((long)(br) * K + (long)(kt) * BK)); \
;     __builtin_amdgcn_global_load_lds((const unsigned*)(_gb + bofl0), (unsigned*)((char*)(P) + gtid_ * 16), 16, 0, 0); \
;     __builtin_amdgcn_global_load_lds((const unsigned*)(_gb + (long)K * 128 + bofl0), (unsigned*)((char*)(P) + gtid_ * 16 + 8192), 16, 0, 0); } while (0)
; #define LDA(dst, b, h) for (int m = 0; m < 4; ++m) for (int k = 0; k < 2; ++k) \
;     dst[m][k] = *reinterpret_cast<const bf16x8*>((char*)SA(b, h) + lds_byte(wr * 64 + m * 16 + fr, k * 32 + fq * 8))
; #define LDB(dst, b, h) for (int n = 0; n < 2; ++n) for (int k = 0; k < 2; ++k) \
;     dst[n][k] = *reinterpret_cast<const bf16x8*>((char*)SB(b, h) + lds_byte(wc * 32 + n * 16 + fr, k * 32 + fq * 8))
; #define MMA(ai, bj, At_, Bt_) do { __builtin_amdgcn_s_setprio(1); \
;     for (int m = 0; m < 4; ++m) for (int n = 0; n < 2; ++n) for (int k = 0; k < 2; ++k) \
;       acc[ai][bj][m][n] = __builtin_amdgcn_mfma_f32_16x16x32_bf16(At_[m][k], Bt_[n][k], acc[ai][bj][m][n], 0, 0, 0); \
;     __builtin_amdgcn_s_setprio(0); } while (0)
; #define WAIT_V(n) asm volatile("s_waitcnt vmcnt(" #n ")" ::: "memory")
; #define WAIT_L(n) asm volatile("s_waitcnt lgkmcnt(" #n ")" ::: "memory")
; #define BAR __builtin_amdgcn_s_barrier()
; #define SCHED __builtin_amdgcn_sched_barrier(0)
; template <int EPI>
; __device__ __forceinline__ void gemm_tile(const GemmArgs& g, int brow, int bcol, int parity, bool first, bool nvalid, int nbrow, int nbcol) {
;     ...
;   for (int t = 0; t < nt - 2; t += 2) {
;     LDB(B0, 0, 0); SCHED; LDA(At, 0, 0); STAGE_A(SA(1, 1), brow + HALF, t + 1);
;     WAIT_L(8); BAR; WAIT_L(0); MMA(0, 0, At, B0); BAR; SCHED;
;     LDB(B1, 0, 1); STAGE_B(SB(0, 0), bcol, t + 2);
;     BAR; WAIT_L(0); MMA(0, 1, At, B1); BAR; SCHED;
;     LDA(At, 0, 1); STAGE_A(SA(0, 0), brow, t + 2);
;     BAR; WAIT_L(0); MMA(1, 0, At, B0); BAR; SCHED;
;     STAGE_B(SB(0, 1), bcol + HALF, t + 2);
;     WAIT_V(6); BAR; MMA(1, 1, At, B1); BAR; SCHED;
;     LDB(B0, 1, 0); SCHED; LDA(At, 1, 0); STAGE_A(SA(0, 1), brow + HALF, t + 2);
;     WAIT_L(8); BAR; WAIT_L(0); MMA(0, 0, At, B0); BAR; SCHED;
.LBB0_191:
	s_barrier
	ds_read_b128 v[166:169], v160
	ds_read_b128 v[170:173], v160 offset:1024
	ds_read_b128 v[174:177], v160 offset:2048
	ds_read_b128 v[178:181], v160 offset:3072
	ds_read_b128 v[182:185], v150
	ds_read_b128 v[186:189], v150 offset:1024
	ds_read_b128 v[190:193], v149
	ds_read_b128 v[194:197], v149 offset:1024
	ds_read_b128 v[202:205], v148
	ds_read_b128 v[206:209], v148 offset:1024
	ds_read_b128 v[216:219], v147
	ds_read_b128 v[222:225], v147 offset:1024
	s_waitcnt lgkmcnt(6)
	ds_read_b128 v[228:231], v159
	ds_read_b128 v[232:235], v159 offset:1024
	ds_read_b128 v[236:239], v159 offset:2048
	ds_read_b128 v[240:243], v159 offset:3072
	s_add_i32 s2, s61, 0xffffff80
	s_cmp_lt_u32 s2, s35
	s_cselect_b32 s3, s36, s57
	s_add_i32 s2, s2, s3
	s_ashr_i32 s3, s2, 31
	s_lshl_b64 s[2:3], s[2:3], 1
	s_add_u32 s2, s41, s2
	s_addc_u32 s3, s44, s3
	v_add_u32_e32 v165, 0xc000, v140
	v_lshl_add_u64 v[162:163], s[2:3], 0, v[130:131]
	v_readfirstlane_b32 s26, v165
	s_add_u32 s2, s2, s53
	s_mov_b32 m0, s26
	s_addc_u32 s3, s3, 0
	v_add_u32_e32 v164, 0xe000, v140
	global_load_lds_dwordx4 v[162:163], off
	v_lshl_add_u64 v[162:163], s[2:3], 0, v[130:131]
	v_readfirstlane_b32 s2, v164
	s_mov_b32 m0, s2
	s_nop 0
	global_load_lds_dwordx4 v[162:163], off
	s_waitcnt vmcnt(8)
	s_barrier
	s_waitcnt lgkmcnt(0)
	v_mfma_f32_16x16x32_bf16 v[126:129], v[166:169], v[182:185], v[126:129]
	v_mfma_f32_16x16x32_bf16 v[122:125], v[174:177], v[182:185], v[122:125]
	v_mfma_f32_16x16x32_bf16 v[118:121], v[166:169], v[190:193], v[118:121]
	v_mfma_f32_16x16x32_bf16 v[114:117], v[174:177], v[190:193], v[114:117]
	v_mfma_f32_16x16x32_bf16 v[110:113], v[166:169], v[202:205], v[110:113]
	v_mfma_f32_16x16x32_bf16 v[106:109], v[174:177], v[202:205], v[106:109]
	v_mfma_f32_16x16x32_bf16 v[102:105], v[166:169], v[216:219], v[102:105]
	v_mfma_f32_16x16x32_bf16 v[98:101], v[174:177], v[216:219], v[98:101]
	v_mfma_f32_16x16x32_bf16 v[126:129], v[170:173], v[186:189], v[126:129]
	v_mfma_f32_16x16x32_bf16 v[122:125], v[178:181], v[186:189], v[122:125]
	v_mfma_f32_16x16x32_bf16 v[118:121], v[170:173], v[194:197], v[118:121]
	v_mfma_f32_16x16x32_bf16 v[114:117], v[178:181], v[194:197], v[114:117]
	v_mfma_f32_16x16x32_bf16 v[110:113], v[170:173], v[206:209], v[110:113]
	v_mfma_f32_16x16x32_bf16 v[106:109], v[178:181], v[206:209], v[106:109]
	v_mfma_f32_16x16x32_bf16 v[102:105], v[170:173], v[222:225], v[102:105]
	v_mfma_f32_16x16x32_bf16 v[98:101], v[178:181], v[222:225], v[98:101]
	v_mfma_f32_16x16x32_bf16 v[94:97], v[228:231], v[182:185], v[94:97]
	v_mfma_f32_16x16x32_bf16 v[90:93], v[236:239], v[182:185], v[90:93]
	v_mfma_f32_16x16x32_bf16 v[86:89], v[228:231], v[190:193], v[86:89]
	v_mfma_f32_16x16x32_bf16 v[82:85], v[236:239], v[190:193], v[82:85]
	v_mfma_f32_16x16x32_bf16 v[78:81], v[228:231], v[202:205], v[78:81]
	v_mfma_f32_16x16x32_bf16 v[74:77], v[236:239], v[202:205], v[74:77]
	v_mfma_f32_16x16x32_bf16 v[70:73], v[228:231], v[216:219], v[70:73]
	v_mfma_f32_16x16x32_bf16 v[66:69], v[236:239], v[216:219], v[66:69]
	v_mfma_f32_16x16x32_bf16 v[94:97], v[232:235], v[186:189], v[94:97]
	v_mfma_f32_16x16x32_bf16 v[90:93], v[240:243], v[186:189], v[90:93]
	v_mfma_f32_16x16x32_bf16 v[86:89], v[232:235], v[194:197], v[86:89]
	v_mfma_f32_16x16x32_bf16 v[82:85], v[240:243], v[194:197], v[82:85]
	v_mfma_f32_16x16x32_bf16 v[78:81], v[232:235], v[206:209], v[78:81]
	v_mfma_f32_16x16x32_bf16 v[74:77], v[240:243], v[206:209], v[74:77]
	v_mfma_f32_16x16x32_bf16 v[70:73], v[232:235], v[222:225], v[70:73]
	v_mfma_f32_16x16x32_bf16 v[66:69], v[240:243], v[222:225], v[66:69]
	s_barrier
	ds_read_b128 v[182:185], v150 offset:16384
	ds_read_b128 v[186:189], v150 offset:17408
	ds_read_b128 v[190:193], v149 offset:16384
	ds_read_b128 v[194:197], v149 offset:17408
	ds_read_b128 v[202:205], v148 offset:16384
	ds_read_b128 v[206:209], v148 offset:17408
	ds_read_b128 v[216:219], v147 offset:16384
	ds_read_b128 v[222:225], v147 offset:17408
	v_add_u32_e32 v162, s40, v146
	v_lshl_add_u64 v[198:199], s[14:15], 0, v[132:133]
	v_readfirstlane_b32 s2, v162
	v_lshl_add_u64 v[210:211], v[198:199], 0, s[78:79]
	s_mov_b32 m0, s2
	v_add_u32_e32 v161, 0x2000, v162
	global_load_lds_dwordx4 v[210:211], off
	v_lshl_add_u64 v[210:211], s[18:19], 0, v[132:133]
	v_readfirstlane_b32 s2, v161
	v_lshl_add_u64 v[212:213], v[210:211], 0, s[78:79]
	s_mov_b32 m0, s2
	s_add_i32 s45, s45, 2
	global_load_lds_dwordx4 v[212:213], off
	s_sub_i32 s2, s61, 64
	s_cmp_lt_u32 s2, s35
	s_cselect_b32 s3, s36, s57
	s_add_i32 s2, s2, s3
	s_ashr_i32 s3, s2, 31
	s_lshl_b64 s[2:3], s[2:3], 1
	s_add_u32 s26, s25, s2
	s_addc_u32 s27, s39, s3
	v_lshl_add_u64 v[212:213], s[26:27], 0, v[130:131]
	v_readfirstlane_b32 s63, v140
	s_add_u32 s26, s26, s53
	s_mov_b32 m0, s63
	s_addc_u32 s27, s27, 0
	global_load_lds_dwordx4 v[212:213], off
	v_lshl_add_u64 v[212:213], s[26:27], 0, v[130:131]
	v_readfirstlane_b32 s26, v139
	s_mov_b32 m0, s26
	s_nop 0
	global_load_lds_dwordx4 v[212:213], off
	v_lshl_add_u64 v[212:213], s[20:21], 0, v[132:133]
	v_readfirstlane_b32 s26, v136
	v_add_u32_e32 v163, 0x2000, v136
	v_lshl_add_u64 v[246:247], v[212:213], 0, s[78:79]
	s_mov_b32 m0, s26
	v_lshl_add_u64 v[244:245], s[22:23], 0, v[132:133]
	v_readfirstlane_b32 s26, v163
	global_load_lds_dwordx4 v[246:247], off
	v_lshl_add_u64 v[246:247], v[244:245], 0, s[78:79]
	s_mov_b32 m0, s26
	s_nop 0
	global_load_lds_dwordx4 v[246:247], off
	s_waitcnt vmcnt(8)
	s_barrier
; #define STAGE_B(P, br, kt) do { const char* _gb = (const char*)(Bt + ((long)(br) * K + (long)(kt) * BK)); \
;     __builtin_amdgcn_global_load_lds((const unsigned*)(_gb + bofl0), (unsigned*)((char*)(P) + gtid_ * 16), 16, 0, 0); \
;     __builtin_amdgcn_global_load_lds((const unsigned*)(_gb + (long)K * 128 + bofl0), (unsigned*)((char*)(P) + gtid_ * 16 + 8192), 16, 0, 0); } while (0)
; #define LDA(dst, b, h) for (int m = 0; m < 4; ++m) for (int k = 0; k < 2; ++k) \
;     dst[m][k] = *reinterpret_cast<const bf16x8*>((char*)SA(b, h) + lds_byte(wr * 64 + m * 16 + fr, k * 32 + fq * 8))
; #define LDB(dst, b, h) for (int n = 0; n < 2; ++n) for (int k = 0; k < 2; ++k) \
;     dst[n][k] = *reinterpret_cast<const bf16x8*>((char*)SB(b, h) + lds_byte(wc * 32 + n * 16 + fr, k * 32 + fq * 8))
; #define MMA(ai, bj, At_, Bt_) do { __builtin_amdgcn_s_setprio(1); \
;     for (int m = 0; m < 4; ++m) for (int n = 0; n < 2; ++n) for (int k = 0; k < 2; ++k) \
;       acc[ai][bj][m][n] = __builtin_amdgcn_mfma_f32_16x16x32_bf16(At_[m][k], Bt_[n][k], acc[ai][bj][m][n], 0, 0, 0); \
;     __builtin_amdgcn_s_setprio(0); } while (0)
; #define WAIT_V(n) asm volatile("s_waitcnt vmcnt(" #n ")" ::: "memory")
; #define WAIT_L(n) asm volatile("s_waitcnt lgkmcnt(" #n ")" ::: "memory")
; #define BAR __builtin_amdgcn_s_barrier()
; #define SCHED __builtin_amdgcn_sched_barrier(0)
; template <int EPI>
; __device__ __forceinline__ void gemm_tile(const GemmArgs& g, int brow, int bcol, int parity, bool first, bool nvalid, int nbrow, int nbcol) {
;     ...
;     WAIT_V(6); BAR; MMA(1, 1, At, B1); BAR; SCHED;
;     LDB(B0, 1, 0); SCHED; LDA(At, 1, 0); STAGE_A(SA(0, 1), brow + HALF, t + 2);
;     WAIT_L(8); BAR; WAIT_L(0); MMA(0, 0, At, B0); BAR; SCHED;
;     LDB(B1, 1, 1); STAGE_B(SB(1, 0), bcol, t + 3);
;     BAR; WAIT_L(0); MMA(0, 1, At, B1); BAR; SCHED;
;     LDA(At, 1, 1); STAGE_A(SA(1, 0), brow, t + 3);
;     BAR; WAIT_L(0); MMA(1, 0, At, B0); BAR; SCHED;
	s_waitcnt lgkmcnt(0)
	v_mfma_f32_16x16x32_bf16 v[62:65], v[166:169], v[182:185], v[62:65]
	v_mfma_f32_16x16x32_bf16 v[58:61], v[174:177], v[182:185], v[58:61]
	v_mfma_f32_16x16x32_bf16 v[54:57], v[166:169], v[190:193], v[54:57]
	v_mfma_f32_16x16x32_bf16 v[50:53], v[174:177], v[190:193], v[50:53]
	v_mfma_f32_16x16x32_bf16 v[46:49], v[166:169], v[202:205], v[46:49]
	v_mfma_f32_16x16x32_bf16 v[42:45], v[174:177], v[202:205], v[42:45]
	v_mfma_f32_16x16x32_bf16 v[38:41], v[166:169], v[216:219], v[38:41]
	v_mfma_f32_16x16x32_bf16 v[34:37], v[174:177], v[216:219], v[34:37]
	v_mfma_f32_16x16x32_bf16 v[62:65], v[170:173], v[186:189], v[62:65]
	v_mfma_f32_16x16x32_bf16 v[58:61], v[178:181], v[186:189], v[58:61]
	v_mfma_f32_16x16x32_bf16 v[54:57], v[170:173], v[194:197], v[54:57]
	v_mfma_f32_16x16x32_bf16 v[50:53], v[178:181], v[194:197], v[50:53]
	v_mfma_f32_16x16x32_bf16 v[46:49], v[170:173], v[206:209], v[46:49]
	v_mfma_f32_16x16x32_bf16 v[42:45], v[178:181], v[206:209], v[42:45]
	v_mfma_f32_16x16x32_bf16 v[38:41], v[170:173], v[222:225], v[38:41]
	v_mfma_f32_16x16x32_bf16 v[34:37], v[178:181], v[222:225], v[34:37]
	v_mfma_f32_16x16x32_bf16 v[30:33], v[228:231], v[182:185], v[30:33]
	v_mfma_f32_16x16x32_bf16 v[26:29], v[236:239], v[182:185], v[26:29]
	v_mfma_f32_16x16x32_bf16 v[22:25], v[228:231], v[190:193], v[22:25]
	v_mfma_f32_16x16x32_bf16 v[18:21], v[236:239], v[190:193], v[18:21]
	v_mfma_f32_16x16x32_bf16 v[14:17], v[228:231], v[202:205], v[14:17]
	v_mfma_f32_16x16x32_bf16 v[10:13], v[236:239], v[202:205], v[10:13]
	v_mfma_f32_16x16x32_bf16 v[6:9], v[228:231], v[216:219], v[6:9]
	v_mfma_f32_16x16x32_bf16 v[2:5], v[236:239], v[216:219], v[2:5]
	v_mfma_f32_16x16x32_bf16 v[30:33], v[232:235], v[186:189], v[30:33]
	v_mfma_f32_16x16x32_bf16 v[26:29], v[240:243], v[186:189], v[26:29]
	v_mfma_f32_16x16x32_bf16 v[22:25], v[232:235], v[194:197], v[22:25]
	v_mfma_f32_16x16x32_bf16 v[18:21], v[240:243], v[194:197], v[18:21]
	v_mfma_f32_16x16x32_bf16 v[14:17], v[232:235], v[206:209], v[14:17]
	v_mfma_f32_16x16x32_bf16 v[10:13], v[240:243], v[206:209], v[10:13]
	v_mfma_f32_16x16x32_bf16 v[6:9], v[232:235], v[222:225], v[6:9]
	v_mfma_f32_16x16x32_bf16 v[2:5], v[240:243], v[222:225], v[2:5]
	s_barrier
	ds_read_b128 v[166:169], v154
	ds_read_b128 v[170:173], v154 offset:1024
	ds_read_b128 v[174:177], v154 offset:2048
	ds_read_b128 v[178:181], v154 offset:3072
	ds_read_b128 v[182:185], v150 offset:32768
	ds_read_b128 v[186:189], v150 offset:33792
	ds_read_b128 v[190:193], v149 offset:32768
	ds_read_b128 v[194:197], v149 offset:33792
	ds_read_b128 v[202:205], v148 offset:32768
	ds_read_b128 v[206:209], v148 offset:33792
	ds_read_b128 v[216:219], v147 offset:32768
	ds_read_b128 v[222:225], v147 offset:33792
	s_waitcnt lgkmcnt(6)
	ds_read_b128 v[228:231], v151
	ds_read_b128 v[232:235], v151 offset:1024
	ds_read_b128 v[236:239], v151 offset:2048
	ds_read_b128 v[240:243], v151 offset:3072
	s_add_u32 s2, s41, s2
	s_addc_u32 s3, s44, s3
	v_lshl_add_u64 v[248:249], s[2:3], 0, v[130:131]
	v_readfirstlane_b32 s26, v135
	s_add_u32 s2, s2, s53
	s_mov_b32 m0, s26
	s_addc_u32 s3, s3, 0
	global_load_lds_dwordx4 v[248:249], off
	v_lshl_add_u64 v[248:249], s[2:3], 0, v[130:131]
	v_readfirstlane_b32 s2, v134
	s_mov_b32 m0, s2
	s_nop 0
	global_load_lds_dwordx4 v[248:249], off
	s_waitcnt vmcnt(8)
	s_barrier
	s_waitcnt lgkmcnt(0)
	v_mfma_f32_16x16x32_bf16 v[126:129], v[166:169], v[182:185], v[126:129]
	v_mfma_f32_16x16x32_bf16 v[122:125], v[174:177], v[182:185], v[122:125]
	v_mfma_f32_16x16x32_bf16 v[118:121], v[166:169], v[190:193], v[118:121]
	v_mfma_f32_16x16x32_bf16 v[114:117], v[174:177], v[190:193], v[114:117]
	v_mfma_f32_16x16x32_bf16 v[110:113], v[166:169], v[202:205], v[110:113]
	v_mfma_f32_16x16x32_bf16 v[106:109], v[174:177], v[202:205], v[106:109]
	v_mfma_f32_16x16x32_bf16 v[102:105], v[166:169], v[216:219], v[102:105]
	v_mfma_f32_16x16x32_bf16 v[98:101], v[174:177], v[216:219], v[98:101]
	v_mfma_f32_16x16x32_bf16 v[126:129], v[170:173], v[186:189], v[126:129]
	v_mfma_f32_16x16x32_bf16 v[122:125], v[178:181], v[186:189], v[122:125]
	v_mfma_f32_16x16x32_bf16 v[118:121], v[170:173], v[194:197], v[118:121]
	v_mfma_f32_16x16x32_bf16 v[114:117], v[178:181], v[194:197], v[114:117]
	v_mfma_f32_16x16x32_bf16 v[110:113], v[170:173], v[206:209], v[110:113]
	v_mfma_f32_16x16x32_bf16 v[106:109], v[178:181], v[206:209], v[106:109]
	v_mfma_f32_16x16x32_bf16 v[102:105], v[170:173], v[222:225], v[102:105]
	v_mfma_f32_16x16x32_bf16 v[98:101], v[178:181], v[222:225], v[98:101]
	v_mfma_f32_16x16x32_bf16 v[94:97], v[228:231], v[182:185], v[94:97]
	v_mfma_f32_16x16x32_bf16 v[90:93], v[236:239], v[182:185], v[90:93]
	v_mfma_f32_16x16x32_bf16 v[86:89], v[228:231], v[190:193], v[86:89]
	v_mfma_f32_16x16x32_bf16 v[82:85], v[236:239], v[190:193], v[82:85]
	v_mfma_f32_16x16x32_bf16 v[78:81], v[228:231], v[202:205], v[78:81]
	v_mfma_f32_16x16x32_bf16 v[74:77], v[236:239], v[202:205], v[74:77]
	v_mfma_f32_16x16x32_bf16 v[70:73], v[228:231], v[216:219], v[70:73]
	v_mfma_f32_16x16x32_bf16 v[66:69], v[236:239], v[216:219], v[66:69]
	v_mfma_f32_16x16x32_bf16 v[94:97], v[232:235], v[186:189], v[94:97]
	v_mfma_f32_16x16x32_bf16 v[90:93], v[240:243], v[186:189], v[90:93]
	v_mfma_f32_16x16x32_bf16 v[86:89], v[232:235], v[194:197], v[86:89]
	v_mfma_f32_16x16x32_bf16 v[82:85], v[240:243], v[194:197], v[82:85]
	v_mfma_f32_16x16x32_bf16 v[78:81], v[232:235], v[206:209], v[78:81]
	v_mfma_f32_16x16x32_bf16 v[74:77], v[240:243], v[206:209], v[74:77]
	v_mfma_f32_16x16x32_bf16 v[70:73], v[232:235], v[222:225], v[70:73]
	v_mfma_f32_16x16x32_bf16 v[66:69], v[240:243], v[222:225], v[66:69]
	s_barrier
; #define STAGE_B(P, br, kt) do { const char* _gb = (const char*)(Bt + ((long)(br) * K + (long)(kt) * BK)); \
;     __builtin_amdgcn_global_load_lds((const unsigned*)(_gb + bofl0), (unsigned*)((char*)(P) + gtid_ * 16), 16, 0, 0); \
;     __builtin_amdgcn_global_load_lds((const unsigned*)(_gb + (long)K * 128 + bofl0), (unsigned*)((char*)(P) + gtid_ * 16 + 8192), 16, 0, 0); } while (0)
; #define LDA(dst, b, h) for (int m = 0; m < 4; ++m) for (int k = 0; k < 2; ++k) \
;     dst[m][k] = *reinterpret_cast<const bf16x8*>((char*)SA(b, h) + lds_byte(wr * 64 + m * 16 + fr, k * 32 + fq * 8))
; #define LDB(dst, b, h) for (int n = 0; n < 2; ++n) for (int k = 0; k < 2; ++k) \
;     dst[n][k] = *reinterpret_cast<const bf16x8*>((char*)SB(b, h) + lds_byte(wc * 32 + n * 16 + fr, k * 32 + fq * 8))
; #define MMA(ai, bj, At_, Bt_) do { __builtin_amdgcn_s_setprio(1); \
;     for (int m = 0; m < 4; ++m) for (int n = 0; n < 2; ++n) for (int k = 0; k < 2; ++k) \
;       acc[ai][bj][m][n] = __builtin_amdgcn_mfma_f32_16x16x32_bf16(At_[m][k], Bt_[n][k], acc[ai][bj][m][n], 0, 0, 0); \
;     __builtin_amdgcn_s_setprio(0); } while (0)
; #define WAIT_V(n) asm volatile("s_waitcnt vmcnt(" #n ")" ::: "memory")
; #define WAIT_L(n) asm volatile("s_waitcnt lgkmcnt(" #n ")" ::: "memory")
; #define BAR __builtin_amdgcn_s_barrier()
; #define SCHED __builtin_amdgcn_sched_barrier(0)
; template <int EPI>
; __device__ __forceinline__ void gemm_tile(const GemmArgs& g, int brow, int bcol, int parity, bool first, bool nvalid, int nbrow, int nbcol) {
;     ...
;     LDB(B1, 1, 1); STAGE_B(SB(1, 0), bcol, t + 3);
;     BAR; WAIT_L(0); MMA(0, 1, At, B1); BAR; SCHED;
;     LDA(At, 1, 1); STAGE_A(SA(1, 0), brow, t + 3);
;     BAR; WAIT_L(0); MMA(1, 0, At, B0); BAR; SCHED;
;     STAGE_B(SB(1, 1), bcol + HALF, t + 3);
;     WAIT_V(6); BAR; MMA(1, 1, At, B1); BAR; SCHED;
;   }
;   { LDB(B0, 0, 0); LDA(At, 0, 0); STAGE_A(SA(1, 1), brow + HALF, nt - 1);
;     BAR; WAIT_L(0); MMA(0, 0, At, B0); BAR;
	ds_read_b128 v[182:185], v150 offset:49152
	ds_read_b128 v[186:189], v150 offset:50176
	ds_read_b128 v[190:193], v149 offset:49152
	ds_read_b128 v[194:197], v149 offset:50176
	ds_read_b128 v[202:205], v148 offset:49152
	ds_read_b128 v[206:209], v148 offset:50176
	ds_read_b128 v[216:219], v147 offset:49152
	ds_read_b128 v[222:225], v147 offset:50176
	v_readfirstlane_b32 s2, v152
	v_lshl_add_u64 v[198:199], v[198:199], 0, s[58:59]
	s_mov_b32 m0, s2
	v_readfirstlane_b32 s2, v153
	global_load_lds_dwordx4 v[198:199], off
	v_lshl_add_u64 v[198:199], v[210:211], 0, s[58:59]
	s_mov_b32 m0, s2
	s_nop 0
	global_load_lds_dwordx4 v[198:199], off
	s_cmp_lt_u32 s61, s35
	s_cselect_b32 s2, s36, s57
	s_add_i32 s2, s2, s61
	s_ashr_i32 s3, s2, 31
	s_lshl_b64 s[2:3], s[2:3], 1
	s_add_u32 s2, s25, s2
	s_addc_u32 s3, s39, s3
	v_lshl_add_u64 v[198:199], s[2:3], 0, v[130:131]
	v_readfirstlane_b32 s26, v155
	s_add_u32 s2, s2, s53
	s_mov_b32 m0, s26
	s_addc_u32 s3, s3, 0
	global_load_lds_dwordx4 v[198:199], off
	v_lshl_add_u64 v[198:199], s[2:3], 0, v[130:131]
	v_readfirstlane_b32 s2, v156
	s_mov_b32 m0, s2
	s_nop 0
	global_load_lds_dwordx4 v[198:199], off
	v_readfirstlane_b32 s2, v157
	v_lshl_add_u64 v[246:247], v[212:213], 0, s[58:59]
	s_mov_b32 m0, s2
	v_readfirstlane_b32 s2, v158
	global_load_lds_dwordx4 v[246:247], off
	v_lshl_add_u64 v[246:247], v[244:245], 0, s[58:59]
	s_mov_b32 m0, s2
	s_nop 0
	global_load_lds_dwordx4 v[246:247], off
	s_waitcnt vmcnt(8)
	s_barrier
	s_waitcnt lgkmcnt(0)
	v_mfma_f32_16x16x32_bf16 v[62:65], v[166:169], v[182:185], v[62:65]
	v_mfma_f32_16x16x32_bf16 v[58:61], v[174:177], v[182:185], v[58:61]
	v_mfma_f32_16x16x32_bf16 v[54:57], v[166:169], v[190:193], v[54:57]
	v_mfma_f32_16x16x32_bf16 v[50:53], v[174:177], v[190:193], v[50:53]
	v_mfma_f32_16x16x32_bf16 v[46:49], v[166:169], v[202:205], v[46:49]
	v_mfma_f32_16x16x32_bf16 v[42:45], v[174:177], v[202:205], v[42:45]
	v_mfma_f32_16x16x32_bf16 v[38:41], v[166:169], v[216:219], v[38:41]
	v_mfma_f32_16x16x32_bf16 v[34:37], v[174:177], v[216:219], v[34:37]
	v_mfma_f32_16x16x32_bf16 v[62:65], v[170:173], v[186:189], v[62:65]
	v_mfma_f32_16x16x32_bf16 v[58:61], v[178:181], v[186:189], v[58:61]
	v_mfma_f32_16x16x32_bf16 v[54:57], v[170:173], v[194:197], v[54:57]
	v_mfma_f32_16x16x32_bf16 v[50:53], v[178:181], v[194:197], v[50:53]
	v_mfma_f32_16x16x32_bf16 v[46:49], v[170:173], v[206:209], v[46:49]
	v_mfma_f32_16x16x32_bf16 v[42:45], v[178:181], v[206:209], v[42:45]
	v_mfma_f32_16x16x32_bf16 v[38:41], v[170:173], v[222:225], v[38:41]
	v_mfma_f32_16x16x32_bf16 v[34:37], v[178:181], v[222:225], v[34:37]
	v_mfma_f32_16x16x32_bf16 v[30:33], v[228:231], v[182:185], v[30:33]
	v_mfma_f32_16x16x32_bf16 v[26:29], v[236:239], v[182:185], v[26:29]
	v_mfma_f32_16x16x32_bf16 v[22:25], v[228:231], v[190:193], v[22:25]
	v_mfma_f32_16x16x32_bf16 v[18:21], v[236:239], v[190:193], v[18:21]
	v_mfma_f32_16x16x32_bf16 v[14:17], v[228:231], v[202:205], v[14:17]
	v_mfma_f32_16x16x32_bf16 v[10:13], v[236:239], v[202:205], v[10:13]
	v_mfma_f32_16x16x32_bf16 v[6:9], v[228:231], v[216:219], v[6:9]
	v_mfma_f32_16x16x32_bf16 v[2:5], v[236:239], v[216:219], v[2:5]
	v_mfma_f32_16x16x32_bf16 v[30:33], v[232:235], v[186:189], v[30:33]
	v_mfma_f32_16x16x32_bf16 v[26:29], v[240:243], v[186:189], v[26:29]
	v_mfma_f32_16x16x32_bf16 v[22:25], v[232:235], v[194:197], v[22:25]
	v_mfma_f32_16x16x32_bf16 v[18:21], v[240:243], v[194:197], v[18:21]
	v_mfma_f32_16x16x32_bf16 v[14:17], v[232:235], v[206:209], v[14:17]
	v_mfma_f32_16x16x32_bf16 v[10:13], v[240:243], v[206:209], v[10:13]
	v_mfma_f32_16x16x32_bf16 v[6:9], v[232:235], v[222:225], v[6:9]
	v_mfma_f32_16x16x32_bf16 v[2:5], v[240:243], v[222:225], v[2:5]
	s_addk_i32 s61, 0x80
	s_add_u32 s14, s14, 0x100
	s_addc_u32 s15, s15, 0
	s_add_u32 s18, s18, 0x100
	s_addc_u32 s19, s19, 0
	s_add_u32 s20, s20, 0x100
	s_addc_u32 s21, s21, 0
	s_add_u32 s22, s22, 0x100
	s_addc_u32 s23, s23, 0
	s_cmp_lt_i32 s45, s56
	s_cbranch_scc1 .LBB0_191
	s_barrier
	s_add_u32 s2, s76, s12
	s_addc_u32 s3, s77, s13
	s_movk_i32 s14, 0xff80
	v_lshl_add_u64 v[132:133], s[2:3], 0, v[130:131]
	s_mov_b32 s15, -1
	v_readfirstlane_b32 s12, v165
	s_add_u32 s2, s2, s53
	v_lshl_add_u64 v[132:133], v[132:133], 0, s[14:15]
	s_mov_b32 m0, s12
	s_addc_u32 s3, s3, 0
	ds_read_b128 v[166:169], v160
	ds_read_b128 v[170:173], v160 offset:1024
	ds_read_b128 v[174:177], v160 offset:2048
	ds_read_b128 v[178:181], v160 offset:3072
	ds_read_b128 v[182:185], v150
	ds_read_b128 v[186:189], v150 offset:1024
	ds_read_b128 v[190:193], v149
	ds_read_b128 v[194:197], v149 offset:1024
	ds_read_b128 v[202:205], v148
	ds_read_b128 v[206:209], v148 offset:1024
	ds_read_b128 v[216:219], v147
	ds_read_b128 v[222:225], v147 offset:1024
	global_load_lds_dwordx4 v[132:133], off
	v_lshl_add_u64 v[132:133], s[2:3], 0, v[130:131]
	v_readfirstlane_b32 s2, v164
	v_lshl_add_u64 v[132:133], v[132:133], 0, s[14:15]
	s_mov_b32 m0, s2
	s_nop 0
	global_load_lds_dwordx4 v[132:133], off
	s_waitcnt vmcnt(8)
	s_barrier
	s_waitcnt lgkmcnt(0)
	s_setprio 1
	s_waitcnt lgkmcnt(0)
	v_mfma_f32_16x16x32_bf16 v[126:129], v[166:169], v[182:185], v[126:129]
	v_mfma_f32_16x16x32_bf16 v[122:125], v[174:177], v[182:185], v[122:125]
	v_mfma_f32_16x16x32_bf16 v[118:121], v[166:169], v[190:193], v[118:121]
	v_mfma_f32_16x16x32_bf16 v[106:109], v[174:177], v[202:205], v[106:109]
	v_mfma_f32_16x16x32_bf16 v[126:129], v[170:173], v[186:189], v[126:129]
	v_mfma_f32_16x16x32_bf16 v[122:125], v[178:181], v[186:189], v[122:125]
	v_mfma_f32_16x16x32_bf16 v[118:121], v[170:173], v[194:197], v[118:121]
	v_mfma_f32_16x16x32_bf16 v[114:117], v[174:177], v[190:193], v[114:117]
	v_mfma_f32_16x16x32_bf16 v[110:113], v[166:169], v[202:205], v[110:113]
	v_mfma_f32_16x16x32_bf16 v[106:109], v[178:181], v[206:209], v[106:109]
	v_mfma_f32_16x16x32_bf16 v[102:105], v[166:169], v[216:219], v[102:105]
	v_mfma_f32_16x16x32_bf16 v[98:101], v[174:177], v[216:219], v[98:101]
	v_mfma_f32_16x16x32_bf16 v[228:231], v[178:181], v[194:197], v[114:117]
	v_mfma_f32_16x16x32_bf16 v[232:235], v[170:173], v[206:209], v[110:113]
	v_mfma_f32_16x16x32_bf16 v[236:239], v[170:173], v[222:225], v[102:105]
	v_mfma_f32_16x16x32_bf16 v[240:243], v[178:181], v[222:225], v[98:101]
	s_setprio 0
	s_barrier
; #define LDA(dst, b, h) for (int m = 0; m < 4; ++m) for (int k = 0; k < 2; ++k) \
;     dst[m][k] = *reinterpret_cast<const bf16x8*>((char*)SA(b, h) + lds_byte(wr * 64 + m * 16 + fr, k * 32 + fq * 8))
; #define LDB(dst, b, h) for (int n = 0; n < 2; ++n) for (int k = 0; k < 2; ++k) \
;     dst[n][k] = *reinterpret_cast<const bf16x8*>((char*)SB(b, h) + lds_byte(wc * 32 + n * 16 + fr, k * 32 + fq * 8))
; #define MMA(ai, bj, At_, Bt_) do { __builtin_amdgcn_s_setprio(1); \
;     for (int m = 0; m < 4; ++m) for (int n = 0; n < 2; ++n) for (int k = 0; k < 2; ++k) \
;       acc[ai][bj][m][n] = __builtin_amdgcn_mfma_f32_16x16x32_bf16(At_[m][k], Bt_[n][k], acc[ai][bj][m][n], 0, 0, 0); \
;     __builtin_amdgcn_s_setprio(0); } while (0)
; #define WAIT_V(n) asm volatile("s_waitcnt vmcnt(" #n ")" ::: "memory")
; #define WAIT_L(n) asm volatile("s_waitcnt lgkmcnt(" #n ")" ::: "memory")
; #define BAR __builtin_amdgcn_s_barrier()
; #define SCHED __builtin_amdgcn_sched_barrier(0)
; template <int EPI>
; __device__ __forceinline__ void gemm_tile(const GemmArgs& g, int brow, int bcol, int parity, bool first, bool nvalid, int nbrow, int nbcol) {
;     ...
;     BAR; WAIT_L(0); MMA(0, 0, At, B0); BAR;
;     LDB(B1, 0, 1); BAR; WAIT_L(0); MMA(0, 1, At, B1); BAR; SCHED;
;     LDA(At, 0, 1); WAIT_V(4); BAR; WAIT_L(0); MMA(1, 0, At, B0); MMA(1, 1, At, B1); BAR; }
;   { LDB(B0, 1, 0); LDA(At, 1, 0); WAIT_V(2); BAR; WAIT_L(0); MMA(0, 0, At, B0); BAR;
	s_nop 1
	ds_read_b128 v[98:101], v159
	ds_read_b128 v[102:105], v159 offset:1024
	ds_read_b128 v[110:113], v159 offset:2048
	ds_read_b128 v[114:117], v159 offset:3072
	s_barrier
	s_waitcnt lgkmcnt(0)
	s_setprio 1
	s_waitcnt lgkmcnt(0)
	v_mfma_f32_16x16x32_bf16 v[94:97], v[98:101], v[182:185], v[94:97]
	v_mfma_f32_16x16x32_bf16 v[90:93], v[110:113], v[182:185], v[90:93]
	v_mfma_f32_16x16x32_bf16 v[86:89], v[98:101], v[190:193], v[86:89]
	v_mfma_f32_16x16x32_bf16 v[78:81], v[98:101], v[202:205], v[78:81]
	v_mfma_f32_16x16x32_bf16 v[94:97], v[102:105], v[186:189], v[94:97]
	v_mfma_f32_16x16x32_bf16 v[90:93], v[114:117], v[186:189], v[90:93]
	v_mfma_f32_16x16x32_bf16 v[86:89], v[102:105], v[194:197], v[86:89]
	v_mfma_f32_16x16x32_bf16 v[82:85], v[110:113], v[190:193], v[82:85]
	v_mfma_f32_16x16x32_bf16 v[78:81], v[102:105], v[206:209], v[78:81]
	v_mfma_f32_16x16x32_bf16 v[74:77], v[110:113], v[202:205], v[74:77]
	v_mfma_f32_16x16x32_bf16 v[70:73], v[98:101], v[216:219], v[70:73]
	v_mfma_f32_16x16x32_bf16 v[66:69], v[110:113], v[216:219], v[66:69]
	v_mfma_f32_16x16x32_bf16 v[156:159], v[114:117], v[194:197], v[82:85]
	v_mfma_f32_16x16x32_bf16 v[182:185], v[114:117], v[206:209], v[74:77]
	v_mfma_f32_16x16x32_bf16 v[186:189], v[102:105], v[222:225], v[70:73]
	v_mfma_f32_16x16x32_bf16 v[190:193], v[114:117], v[222:225], v[66:69]
	s_setprio 0
	s_barrier
	s_nop 1
	ds_read_b128 v[66:69], v150 offset:16384
	ds_read_b128 v[70:73], v150 offset:17408
	ds_read_b128 v[74:77], v149 offset:16384
	ds_read_b128 v[82:85], v149 offset:17408
	ds_read_b128 v[194:197], v148 offset:16384
	ds_read_b128 v[202:205], v148 offset:17408
	ds_read_b128 v[206:209], v147 offset:16384
	ds_read_b128 v[216:219], v147 offset:17408
	s_waitcnt vmcnt(4)
	s_barrier
	s_waitcnt lgkmcnt(0)
	s_setprio 1
	s_waitcnt lgkmcnt(0)
	v_mfma_f32_16x16x32_bf16 v[62:65], v[166:169], v[66:69], v[62:65]
	v_mfma_f32_16x16x32_bf16 v[58:61], v[174:177], v[66:69], v[58:61]
	v_mfma_f32_16x16x32_bf16 v[54:57], v[166:169], v[74:77], v[54:57]
	v_mfma_f32_16x16x32_bf16 v[46:49], v[166:169], v[194:197], v[46:49]
	v_mfma_f32_16x16x32_bf16 v[62:65], v[170:173], v[70:73], v[62:65]
	v_mfma_f32_16x16x32_bf16 v[58:61], v[178:181], v[70:73], v[58:61]
	v_mfma_f32_16x16x32_bf16 v[54:57], v[170:173], v[82:85], v[54:57]
	v_mfma_f32_16x16x32_bf16 v[50:53], v[174:177], v[74:77], v[50:53]
	v_mfma_f32_16x16x32_bf16 v[46:49], v[170:173], v[202:205], v[46:49]
	v_mfma_f32_16x16x32_bf16 v[42:45], v[174:177], v[194:197], v[42:45]
	v_mfma_f32_16x16x32_bf16 v[38:41], v[166:169], v[206:209], v[38:41]
	v_mfma_f32_16x16x32_bf16 v[34:37], v[174:177], v[206:209], v[34:37]
	v_mfma_f32_16x16x32_bf16 v[222:225], v[178:181], v[82:85], v[50:53]
	v_mfma_f32_16x16x32_bf16 v[244:247], v[178:181], v[202:205], v[42:45]
	v_mfma_f32_16x16x32_bf16 v[164:167], v[170:173], v[216:219], v[38:41]
	v_mfma_f32_16x16x32_bf16 v[168:171], v[178:181], v[216:219], v[34:37]
	s_setprio 0
	s_setprio 1
	v_mfma_f32_16x16x32_bf16 v[30:33], v[98:101], v[66:69], v[30:33]
	v_mfma_f32_16x16x32_bf16 v[26:29], v[110:113], v[66:69], v[26:29]
	v_mfma_f32_16x16x32_bf16 v[22:25], v[98:101], v[74:77], v[22:25]
	v_mfma_f32_16x16x32_bf16 v[14:17], v[98:101], v[194:197], v[14:17]
	v_mfma_f32_16x16x32_bf16 v[30:33], v[102:105], v[70:73], v[30:33]
	v_mfma_f32_16x16x32_bf16 v[26:29], v[114:117], v[70:73], v[26:29]
	v_mfma_f32_16x16x32_bf16 v[22:25], v[102:105], v[82:85], v[22:25]
	v_mfma_f32_16x16x32_bf16 v[18:21], v[110:113], v[74:77], v[18:21]
	v_mfma_f32_16x16x32_bf16 v[14:17], v[102:105], v[202:205], v[14:17]
	v_mfma_f32_16x16x32_bf16 v[10:13], v[110:113], v[194:197], v[10:13]
	v_mfma_f32_16x16x32_bf16 v[6:9], v[98:101], v[206:209], v[6:9]
	v_mfma_f32_16x16x32_bf16 v[2:5], v[110:113], v[206:209], v[2:5]
	v_mfma_f32_16x16x32_bf16 v[172:175], v[114:117], v[82:85], v[18:21]
	v_mfma_f32_16x16x32_bf16 v[176:179], v[114:117], v[202:205], v[10:13]
	v_mfma_f32_16x16x32_bf16 v[194:197], v[102:105], v[216:219], v[6:9]
	v_mfma_f32_16x16x32_bf16 v[202:205], v[114:117], v[216:219], v[2:5]
	s_setprio 0
	s_barrier
	s_nop 1
	ds_read_b128 v[2:5], v154
	ds_read_b128 v[6:9], v154 offset:1024
	ds_read_b128 v[10:13], v154 offset:2048
	ds_read_b128 v[18:21], v154 offset:3072
	ds_read_b128 v[34:37], v150 offset:32768
	ds_read_b128 v[38:41], v150 offset:33792
	ds_read_b128 v[42:45], v149 offset:32768
	ds_read_b128 v[50:53], v149 offset:33792
	ds_read_b128 v[152:155], v148 offset:32768
	ds_read_b128 v[206:209], v148 offset:33792
	ds_read_b128 v[216:219], v147 offset:32768
	ds_read_b128 v[248:251], v147 offset:33792
	s_waitcnt vmcnt(2)
	s_barrier
; #define LDA(dst, b, h) for (int m = 0; m < 4; ++m) for (int k = 0; k < 2; ++k) \
;     dst[m][k] = *reinterpret_cast<const bf16x8*>((char*)SA(b, h) + lds_byte(wr * 64 + m * 16 + fr, k * 32 + fq * 8))
; #define LDB(dst, b, h) for (int n = 0; n < 2; ++n) for (int k = 0; k < 2; ++k) \
;     dst[n][k] = *reinterpret_cast<const bf16x8*>((char*)SB(b, h) + lds_byte(wc * 32 + n * 16 + fr, k * 32 + fq * 8))
; #define MMA(ai, bj, At_, Bt_) do { __builtin_amdgcn_s_setprio(1); \
;     for (int m = 0; m < 4; ++m) for (int n = 0; n < 2; ++n) for (int k = 0; k < 2; ++k) \
;       acc[ai][bj][m][n] = __builtin_amdgcn_mfma_f32_16x16x32_bf16(At_[m][k], Bt_[n][k], acc[ai][bj][m][n], 0, 0, 0); \
;     __builtin_amdgcn_s_setprio(0); } while (0)
; #define WAIT_V(n) asm volatile("s_waitcnt vmcnt(" #n ")" ::: "memory")
; #define WAIT_L(n) asm volatile("s_waitcnt lgkmcnt(" #n ")" ::: "memory")
; #define BAR __builtin_amdgcn_s_barrier()
; #define SCHED __builtin_amdgcn_sched_barrier(0)
; template <int EPI>
; __device__ __forceinline__ void gemm_tile(const GemmArgs& g, int brow, int bcol, int parity, bool first, bool nvalid, int nbrow, int nbcol) {
;     ...
;   { LDB(B0, 1, 0); LDA(At, 1, 0); WAIT_V(2); BAR; WAIT_L(0); MMA(0, 0, At, B0); BAR;
;     LDB(B1, 1, 1); WAIT_V(0); BAR; WAIT_L(0); MMA(0, 1, At, B1); BAR; SCHED;
;     LDA(At, 1, 1); BAR; WAIT_L(0); MMA(1, 0, At, B0); MMA(1, 1, At, B1); BAR; }
;   if (wr == 0) BAR;
	s_waitcnt lgkmcnt(0)
	s_setprio 1
	s_waitcnt lgkmcnt(0)
	v_mfma_f32_16x16x32_bf16 v[66:69], v[2:5], v[34:37], v[126:129]
	v_mfma_f32_16x16x32_bf16 v[114:117], v[6:9], v[38:41], v[66:69]
	v_mfma_f32_16x16x32_bf16 v[66:69], v[10:13], v[34:37], v[122:125]
	v_mfma_f32_16x16x32_bf16 v[126:129], v[18:21], v[38:41], v[66:69]
	v_mfma_f32_16x16x32_bf16 v[66:69], v[2:5], v[42:45], v[118:121]
	v_mfma_f32_16x16x32_bf16 v[110:113], v[6:9], v[50:53], v[66:69]
	v_mfma_f32_16x16x32_bf16 v[66:69], v[10:13], v[42:45], v[228:231]
	v_mfma_f32_16x16x32_bf16 v[122:125], v[18:21], v[50:53], v[66:69]
	v_mfma_f32_16x16x32_bf16 v[66:69], v[2:5], v[152:155], v[232:235]
	v_mfma_f32_16x16x32_bf16 v[102:105], v[6:9], v[206:209], v[66:69]
	v_mfma_f32_16x16x32_bf16 v[66:69], v[10:13], v[152:155], v[106:109]
	v_mfma_f32_16x16x32_bf16 v[118:121], v[18:21], v[206:209], v[66:69]
	v_mfma_f32_16x16x32_bf16 v[66:69], v[2:5], v[216:219], v[236:239]
	v_mfma_f32_16x16x32_bf16 v[98:101], v[6:9], v[248:251], v[66:69]
	v_mfma_f32_16x16x32_bf16 v[66:69], v[10:13], v[216:219], v[240:243]
	v_mfma_f32_16x16x32_bf16 v[106:109], v[18:21], v[248:251], v[66:69]
	s_setprio 0
	s_barrier
	ds_read_b128 v[228:231], v151
	ds_read_b128 v[232:235], v151 offset:1024
	ds_read_b128 v[236:239], v151 offset:2048
	ds_read_b128 v[240:243], v151 offset:3072
	s_waitcnt vmcnt(0)
	s_barrier
	s_waitcnt lgkmcnt(0)
	s_setprio 1
	s_waitcnt lgkmcnt(0)
	v_mfma_f32_16x16x32_bf16 v[66:69], v[228:231], v[34:37], v[94:97]
	v_mfma_f32_16x16x32_bf16 v[34:37], v[236:239], v[34:37], v[90:93]
	v_mfma_f32_16x16x32_bf16 v[82:85], v[240:243], v[38:41], v[34:37]
	v_mfma_f32_16x16x32_bf16 v[34:37], v[228:231], v[42:45], v[86:89]
	v_mfma_f32_16x16x32_bf16 v[70:73], v[232:235], v[50:53], v[34:37]
	v_mfma_f32_16x16x32_bf16 v[34:37], v[236:239], v[42:45], v[156:159]
	v_mfma_f32_16x16x32_bf16 v[86:89], v[240:243], v[50:53], v[34:37]
	v_mfma_f32_16x16x32_bf16 v[34:37], v[228:231], v[152:155], v[78:81]
	v_mfma_f32_16x16x32_bf16 v[74:77], v[232:235], v[206:209], v[34:37]
	v_mfma_f32_16x16x32_bf16 v[34:37], v[236:239], v[152:155], v[182:185]
	v_mfma_f32_16x16x32_bf16 v[90:93], v[240:243], v[206:209], v[34:37]
	v_mfma_f32_16x16x32_bf16 v[34:37], v[228:231], v[216:219], v[186:189]
	v_mfma_f32_16x16x32_bf16 v[78:81], v[232:235], v[248:251], v[34:37]
	v_mfma_f32_16x16x32_bf16 v[34:37], v[236:239], v[216:219], v[190:193]
	v_mfma_f32_16x16x32_bf16 v[66:69], v[232:235], v[38:41], v[66:69]
	v_mfma_f32_16x16x32_bf16 v[94:97], v[240:243], v[248:251], v[34:37]
	s_setprio 0
	s_barrier
	ds_read_b128 v[152:155], v150 offset:49152
	ds_read_b128 v[156:159], v150 offset:50176
	ds_read_b128 v[180:183], v149 offset:49152
	ds_read_b128 v[184:187], v149 offset:50176
	ds_read_b128 v[188:191], v148 offset:49152
	ds_read_b128 v[148:151], v148 offset:50176
	ds_read_b128 v[206:209], v147 offset:49152
	ds_read_b128 v[216:219], v147 offset:50176
	s_barrier
	s_waitcnt lgkmcnt(0)
	s_setprio 1
	s_waitcnt lgkmcnt(0)
	v_mfma_f32_16x16x32_bf16 v[38:41], v[10:13], v[152:155], v[58:61]
	v_mfma_f32_16x16x32_bf16 v[42:45], v[10:13], v[180:183], v[222:225]
	v_mfma_f32_16x16x32_bf16 v[34:37], v[2:5], v[152:155], v[62:65]
	v_mfma_f32_16x16x32_bf16 v[50:53], v[18:21], v[156:159], v[38:41]
	v_mfma_f32_16x16x32_bf16 v[38:41], v[2:5], v[180:183], v[54:57]
	v_mfma_f32_16x16x32_bf16 v[54:57], v[18:21], v[184:187], v[42:45]
	v_mfma_f32_16x16x32_bf16 v[42:45], v[2:5], v[188:191], v[46:49]
	v_mfma_f32_16x16x32_bf16 v[46:49], v[10:13], v[188:191], v[244:247]
	v_mfma_f32_16x16x32_bf16 v[2:5], v[2:5], v[206:209], v[164:167]
	v_mfma_f32_16x16x32_bf16 v[58:61], v[18:21], v[148:151], v[46:49]
	v_mfma_f32_16x16x32_bf16 v[46:49], v[6:9], v[216:219], v[2:5]
	v_mfma_f32_16x16x32_bf16 v[2:5], v[10:13], v[206:209], v[168:171]
	v_mfma_f32_16x16x32_bf16 v[34:37], v[6:9], v[156:159], v[34:37]
	v_mfma_f32_16x16x32_bf16 v[38:41], v[6:9], v[184:187], v[38:41]
	v_mfma_f32_16x16x32_bf16 v[42:45], v[6:9], v[148:151], v[42:45]
	v_mfma_f32_16x16x32_bf16 v[62:65], v[18:21], v[216:219], v[2:5]
	s_setprio 0
	s_setprio 1
	v_mfma_f32_16x16x32_bf16 v[6:9], v[236:239], v[152:155], v[26:29]
	v_mfma_f32_16x16x32_bf16 v[10:13], v[236:239], v[180:183], v[172:175]
	v_mfma_f32_16x16x32_bf16 v[18:21], v[240:243], v[156:159], v[6:9]
	v_mfma_f32_16x16x32_bf16 v[6:9], v[228:231], v[180:183], v[22:25]
	v_mfma_f32_16x16x32_bf16 v[22:25], v[240:243], v[184:187], v[10:13]
	v_mfma_f32_16x16x32_bf16 v[10:13], v[228:231], v[188:191], v[14:17]
	v_mfma_f32_16x16x32_bf16 v[14:17], v[236:239], v[188:191], v[176:179]
	v_mfma_f32_16x16x32_bf16 v[2:5], v[228:231], v[152:155], v[30:33]
	v_mfma_f32_16x16x32_bf16 v[26:29], v[240:243], v[148:151], v[14:17]
	v_mfma_f32_16x16x32_bf16 v[14:17], v[228:231], v[206:209], v[194:197]
	v_mfma_f32_16x16x32_bf16 v[30:33], v[236:239], v[206:209], v[202:205]
	v_mfma_f32_16x16x32_bf16 v[2:5], v[232:235], v[156:159], v[2:5]
	v_mfma_f32_16x16x32_bf16 v[6:9], v[232:235], v[184:187], v[6:9]
	v_mfma_f32_16x16x32_bf16 v[10:13], v[232:235], v[148:151], v[10:13]
	v_mfma_f32_16x16x32_bf16 v[14:17], v[232:235], v[216:219], v[14:17]
	v_mfma_f32_16x16x32_bf16 v[30:33], v[240:243], v[216:219], v[30:33]
	s_setprio 0
	s_movk_i32 s2, 0x100
	v_cmp_gt_u32_e32 vcc, s2, v141
	s_barrier
	s_and_saveexec_b64 s[12:13], vcc
	s_cbranch_execz .LBB0_194
	s_barrier

; #define STAGE_B(P, br, kt) do { const char* _gb = (const char*)(Bt + ((long)(br) * K + (long)(kt) * BK)); \
;     __builtin_amdgcn_global_load_lds((const unsigned*)(_gb + bofl0), (unsigned*)((char*)(P) + gtid_ * 16), 16, 0, 0); \
;     __builtin_amdgcn_global_load_lds((const unsigned*)(_gb + (long)K * 128 + bofl0), (unsigned*)((char*)(P) + gtid_ * 16 + 8192), 16, 0, 0); } while (0)
; #define LDA(dst, b, h) for (int m = 0; m < 4; ++m) for (int k = 0; k < 2; ++k) \
;     dst[m][k] = *reinterpret_cast<const bf16x8*>((char*)SA(b, h) + lds_byte(wr * 64 + m * 16 + fr, k * 32 + fq * 8))
; #define LDB(dst, b, h) for (int n = 0; n < 2; ++n) for (int k = 0; k < 2; ++k) \
;     dst[n][k] = *reinterpret_cast<const bf16x8*>((char*)SB(b, h) + lds_byte(wc * 32 + n * 16 + fr, k * 32 + fq * 8))
; #define MMA(ai, bj, At_, Bt_) do { __builtin_amdgcn_s_setprio(1); \
;     for (int m = 0; m < 4; ++m) for (int n = 0; n < 2; ++n) for (int k = 0; k < 2; ++k) \
;       acc[ai][bj][m][n] = __builtin_amdgcn_mfma_f32_16x16x32_bf16(At_[m][k], Bt_[n][k], acc[ai][bj][m][n], 0, 0, 0); \
;     __builtin_amdgcn_s_setprio(0); } while (0)
; #define WAIT_V(n) asm volatile("s_waitcnt vmcnt(" #n ")" ::: "memory")
; #define WAIT_L(n) asm volatile("s_waitcnt lgkmcnt(" #n ")" ::: "memory")
; #define BAR __builtin_amdgcn_s_barrier()
; #define SCHED __builtin_amdgcn_sched_barrier(0)
; template <int EPI>
; __device__ __forceinline__ void gemm_tile(const GemmArgs& g, int brow, int bcol, int parity, bool first, bool nvalid, int nbrow, int nbcol) {
;     ...
;     LDB(B0, 0, 0); SCHED; LDA(At, 0, 0); STAGE_A(SA(1, 1), brow + HALF, t + 1);
;     WAIT_L(8); BAR; WAIT_L(0); MMA(0, 0, At, B0); BAR; SCHED;
;     LDB(B1, 0, 1); STAGE_B(SB(0, 0), bcol, t + 2);
;     BAR; WAIT_L(0); MMA(0, 1, At, B1); BAR; SCHED;
;     LDA(At, 0, 1); STAGE_A(SA(0, 0), brow, t + 2);
;     BAR; WAIT_L(0); MMA(1, 0, At, B0); BAR; SCHED;
;     STAGE_B(SB(0, 1), bcol + HALF, t + 2);
;     WAIT_V(6); BAR; MMA(1, 1, At, B1); BAR; SCHED;
.LBB0_640:
	s_barrier
	ds_read_b128 v[164:167], v157
	ds_read_b128 v[168:171], v157 offset:1024
	ds_read_b128 v[172:175], v157 offset:2048
	ds_read_b128 v[176:179], v157 offset:3072
	ds_read_b128 v[180:183], v147
	ds_read_b128 v[184:187], v147 offset:1024
	ds_read_b128 v[188:191], v146
	ds_read_b128 v[192:195], v146 offset:1024
	ds_read_b128 v[196:199], v145
	ds_read_b128 v[202:205], v145 offset:1024
	ds_read_b128 v[206:209], v144
	ds_read_b128 v[216:219], v144 offset:1024
	s_waitcnt lgkmcnt(6)
	ds_read_b128 v[228:231], v154
	ds_read_b128 v[232:235], v154 offset:1024
	ds_read_b128 v[236:239], v154 offset:2048
	ds_read_b128 v[240:243], v154 offset:3072
	v_add_u32_e32 v161, 0xc000, v137
	v_lshl_add_u64 v[210:211], s[12:13], 0, v[130:131]
	v_readfirstlane_b32 s2, v161
	v_add_u32_e32 v162, 0xe000, v137
	v_lshl_add_u64 v[158:159], v[210:211], 0, s[24:25]
	s_mov_b32 m0, s2
	v_readfirstlane_b32 s2, v162
	global_load_lds_dwordx4 v[158:159], off
	v_lshl_add_u64 v[158:159], v[210:211], 0, s[36:37]
	s_mov_b32 m0, s2
	s_nop 0
	global_load_lds_dwordx4 v[158:159], off
	s_waitcnt vmcnt(8)
	s_barrier
	s_waitcnt lgkmcnt(0)
	v_mfma_f32_16x16x32_bf16 v[126:129], v[164:167], v[180:183], v[126:129]
	v_mfma_f32_16x16x32_bf16 v[122:125], v[172:175], v[180:183], v[122:125]
	v_mfma_f32_16x16x32_bf16 v[118:121], v[164:167], v[188:191], v[118:121]
	v_mfma_f32_16x16x32_bf16 v[114:117], v[172:175], v[188:191], v[114:117]
	v_mfma_f32_16x16x32_bf16 v[110:113], v[164:167], v[196:199], v[110:113]
	v_mfma_f32_16x16x32_bf16 v[106:109], v[172:175], v[196:199], v[106:109]
	v_mfma_f32_16x16x32_bf16 v[102:105], v[164:167], v[206:209], v[102:105]
	v_mfma_f32_16x16x32_bf16 v[98:101], v[172:175], v[206:209], v[98:101]
	v_mfma_f32_16x16x32_bf16 v[126:129], v[168:171], v[184:187], v[126:129]
	v_mfma_f32_16x16x32_bf16 v[122:125], v[176:179], v[184:187], v[122:125]
	v_mfma_f32_16x16x32_bf16 v[118:121], v[168:171], v[192:195], v[118:121]
	v_mfma_f32_16x16x32_bf16 v[114:117], v[176:179], v[192:195], v[114:117]
	v_mfma_f32_16x16x32_bf16 v[110:113], v[168:171], v[202:205], v[110:113]
	v_mfma_f32_16x16x32_bf16 v[106:109], v[176:179], v[202:205], v[106:109]
	v_mfma_f32_16x16x32_bf16 v[102:105], v[168:171], v[216:219], v[102:105]
	v_mfma_f32_16x16x32_bf16 v[98:101], v[176:179], v[216:219], v[98:101]
	v_mfma_f32_16x16x32_bf16 v[94:97], v[228:231], v[180:183], v[94:97]
	v_mfma_f32_16x16x32_bf16 v[90:93], v[236:239], v[180:183], v[90:93]
	v_mfma_f32_16x16x32_bf16 v[86:89], v[228:231], v[188:191], v[86:89]
	v_mfma_f32_16x16x32_bf16 v[82:85], v[236:239], v[188:191], v[82:85]
	v_mfma_f32_16x16x32_bf16 v[78:81], v[228:231], v[196:199], v[78:81]
	v_mfma_f32_16x16x32_bf16 v[74:77], v[236:239], v[196:199], v[74:77]
	v_mfma_f32_16x16x32_bf16 v[70:73], v[228:231], v[206:209], v[70:73]
	v_mfma_f32_16x16x32_bf16 v[66:69], v[236:239], v[206:209], v[66:69]
	v_mfma_f32_16x16x32_bf16 v[94:97], v[232:235], v[184:187], v[94:97]
	v_mfma_f32_16x16x32_bf16 v[90:93], v[240:243], v[184:187], v[90:93]
	v_mfma_f32_16x16x32_bf16 v[86:89], v[232:235], v[192:195], v[86:89]
	v_mfma_f32_16x16x32_bf16 v[82:85], v[240:243], v[192:195], v[82:85]
	v_mfma_f32_16x16x32_bf16 v[78:81], v[232:235], v[202:205], v[78:81]
	v_mfma_f32_16x16x32_bf16 v[74:77], v[240:243], v[202:205], v[74:77]
	v_mfma_f32_16x16x32_bf16 v[70:73], v[232:235], v[216:219], v[70:73]
	v_mfma_f32_16x16x32_bf16 v[66:69], v[240:243], v[216:219], v[66:69]
	s_barrier
	ds_read_b128 v[180:183], v147 offset:16384
	ds_read_b128 v[184:187], v147 offset:17408
	ds_read_b128 v[188:191], v146 offset:16384
	ds_read_b128 v[192:195], v146 offset:17408
	ds_read_b128 v[196:199], v145 offset:16384
	ds_read_b128 v[202:205], v145 offset:17408
	ds_read_b128 v[206:209], v144 offset:16384
	ds_read_b128 v[216:219], v144 offset:17408
	v_add_u32_e32 v158, s15, v142
	v_lshl_add_u64 v[212:213], s[0:1], 0, v[130:131]
	v_readfirstlane_b32 s2, v158
	v_add_u32_e32 v159, 0x2000, v158
	v_lshl_add_u64 v[222:223], v[212:213], 0, s[78:79]
	s_mov_b32 m0, s2
	v_readfirstlane_b32 s2, v159
	global_load_lds_dwordx4 v[222:223], off
	v_lshl_add_u64 v[222:223], v[212:213], 0, s[66:67]
	s_mov_b32 m0, s2
	s_nop 0
	global_load_lds_dwordx4 v[222:223], off
	v_readfirstlane_b32 s2, v137
	v_lshl_add_u64 v[222:223], v[210:211], 0, s[38:39]
	s_mov_b32 m0, s2
	v_readfirstlane_b32 s2, v136
	global_load_lds_dwordx4 v[222:223], off
	v_lshl_add_u64 v[222:223], v[210:211], 0, s[42:43]
	s_mov_b32 m0, s2
	s_nop 0
	global_load_lds_dwordx4 v[222:223], off
	v_readfirstlane_b32 s2, v135
	v_add_u32_e32 v160, 0x2000, v135
	v_lshl_add_u64 v[244:245], v[212:213], 0, s[76:77]
	s_mov_b32 m0, s2
	v_readfirstlane_b32 s2, v160
	global_load_lds_dwordx4 v[244:245], off
	v_lshl_add_u64 v[244:245], v[212:213], 0, s[96:97]
	s_mov_b32 m0, s2
	s_nop 0
	global_load_lds_dwordx4 v[244:245], off
	s_waitcnt vmcnt(8)
	s_barrier
; #define LDA(dst, b, h) for (int m = 0; m < 4; ++m) for (int k = 0; k < 2; ++k) \
;     dst[m][k] = *reinterpret_cast<const bf16x8*>((char*)SA(b, h) + lds_byte(wr * 64 + m * 16 + fr, k * 32 + fq * 8))
; #define LDB(dst, b, h) for (int n = 0; n < 2; ++n) for (int k = 0; k < 2; ++k) \
;     dst[n][k] = *reinterpret_cast<const bf16x8*>((char*)SB(b, h) + lds_byte(wc * 32 + n * 16 + fr, k * 32 + fq * 8))
; #define MMA(ai, bj, At_, Bt_) do { __builtin_amdgcn_s_setprio(1); \
;     for (int m = 0; m < 4; ++m) for (int n = 0; n < 2; ++n) for (int k = 0; k < 2; ++k) \
;       acc[ai][bj][m][n] = __builtin_amdgcn_mfma_f32_16x16x32_bf16(At_[m][k], Bt_[n][k], acc[ai][bj][m][n], 0, 0, 0); \
;     __builtin_amdgcn_s_setprio(0); } while (0)
; #define WAIT_V(n) asm volatile("s_waitcnt vmcnt(" #n ")" ::: "memory")
; #define WAIT_L(n) asm volatile("s_waitcnt lgkmcnt(" #n ")" ::: "memory")
; #define BAR __builtin_amdgcn_s_barrier()
; #define SCHED __builtin_amdgcn_sched_barrier(0)
; template <int EPI>
; __device__ __forceinline__ void gemm_tile(const GemmArgs& g, int brow, int bcol, int parity, bool first, bool nvalid, int nbrow, int nbcol) {
;     ...
;     WAIT_V(6); BAR; MMA(1, 1, At, B1); BAR; SCHED;
;     LDB(B0, 1, 0); SCHED; LDA(At, 1, 0); STAGE_A(SA(0, 1), brow + HALF, t + 2);
;     WAIT_L(8); BAR; WAIT_L(0); MMA(0, 0, At, B0); BAR; SCHED;
	s_waitcnt lgkmcnt(0)
	v_mfma_f32_16x16x32_bf16 v[62:65], v[164:167], v[180:183], v[62:65]
	v_mfma_f32_16x16x32_bf16 v[58:61], v[172:175], v[180:183], v[58:61]
	v_mfma_f32_16x16x32_bf16 v[54:57], v[164:167], v[188:191], v[54:57]
	v_mfma_f32_16x16x32_bf16 v[50:53], v[172:175], v[188:191], v[50:53]
	v_mfma_f32_16x16x32_bf16 v[46:49], v[164:167], v[196:199], v[46:49]
	v_mfma_f32_16x16x32_bf16 v[42:45], v[172:175], v[196:199], v[42:45]
	v_mfma_f32_16x16x32_bf16 v[38:41], v[164:167], v[206:209], v[38:41]
	v_mfma_f32_16x16x32_bf16 v[34:37], v[172:175], v[206:209], v[34:37]
	v_mfma_f32_16x16x32_bf16 v[62:65], v[168:171], v[184:187], v[62:65]
	v_mfma_f32_16x16x32_bf16 v[58:61], v[176:179], v[184:187], v[58:61]
	v_mfma_f32_16x16x32_bf16 v[54:57], v[168:171], v[192:195], v[54:57]
	v_mfma_f32_16x16x32_bf16 v[50:53], v[176:179], v[192:195], v[50:53]
	v_mfma_f32_16x16x32_bf16 v[46:49], v[168:171], v[202:205], v[46:49]
	v_mfma_f32_16x16x32_bf16 v[42:45], v[176:179], v[202:205], v[42:45]
	v_mfma_f32_16x16x32_bf16 v[38:41], v[168:171], v[216:219], v[38:41]
	v_mfma_f32_16x16x32_bf16 v[34:37], v[176:179], v[216:219], v[34:37]
	v_mfma_f32_16x16x32_bf16 v[30:33], v[228:231], v[180:183], v[30:33]
	v_mfma_f32_16x16x32_bf16 v[26:29], v[236:239], v[180:183], v[26:29]
	v_mfma_f32_16x16x32_bf16 v[22:25], v[228:231], v[188:191], v[22:25]
	v_mfma_f32_16x16x32_bf16 v[18:21], v[236:239], v[188:191], v[18:21]
	v_mfma_f32_16x16x32_bf16 v[14:17], v[228:231], v[196:199], v[14:17]
	v_mfma_f32_16x16x32_bf16 v[10:13], v[236:239], v[196:199], v[10:13]
	v_mfma_f32_16x16x32_bf16 v[6:9], v[228:231], v[206:209], v[6:9]
	v_mfma_f32_16x16x32_bf16 v[2:5], v[236:239], v[206:209], v[2:5]
	v_mfma_f32_16x16x32_bf16 v[30:33], v[232:235], v[184:187], v[30:33]
	v_mfma_f32_16x16x32_bf16 v[26:29], v[240:243], v[184:187], v[26:29]
	v_mfma_f32_16x16x32_bf16 v[22:25], v[232:235], v[192:195], v[22:25]
	v_mfma_f32_16x16x32_bf16 v[18:21], v[240:243], v[192:195], v[18:21]
	v_mfma_f32_16x16x32_bf16 v[14:17], v[232:235], v[202:205], v[14:17]
	v_mfma_f32_16x16x32_bf16 v[10:13], v[240:243], v[202:205], v[10:13]
	v_mfma_f32_16x16x32_bf16 v[6:9], v[232:235], v[216:219], v[6:9]
	v_mfma_f32_16x16x32_bf16 v[2:5], v[240:243], v[216:219], v[2:5]
	s_barrier
	ds_read_b128 v[164:167], v149
	ds_read_b128 v[168:171], v149 offset:1024
	ds_read_b128 v[172:175], v149 offset:2048
	ds_read_b128 v[176:179], v149 offset:3072
	ds_read_b128 v[180:183], v147 offset:32768
	ds_read_b128 v[184:187], v147 offset:33792
	ds_read_b128 v[188:191], v146 offset:32768
	ds_read_b128 v[192:195], v146 offset:33792
	ds_read_b128 v[196:199], v145 offset:32768
	ds_read_b128 v[202:205], v145 offset:33792
	ds_read_b128 v[206:209], v144 offset:32768
	ds_read_b128 v[216:219], v144 offset:33792
	s_waitcnt lgkmcnt(6)
	ds_read_b128 v[228:231], v148
	ds_read_b128 v[232:235], v148 offset:1024
	ds_read_b128 v[236:239], v148 offset:2048
	ds_read_b128 v[240:243], v148 offset:3072
	v_readfirstlane_b32 s2, v134
	v_lshl_add_u64 v[222:223], v[210:211], 0, s[44:45]
	s_mov_b32 m0, s2
	v_readfirstlane_b32 s2, v133
	global_load_lds_dwordx4 v[222:223], off
	v_lshl_add_u64 v[222:223], v[210:211], 0, s[46:47]
	s_mov_b32 m0, s2
	s_nop 0
	global_load_lds_dwordx4 v[222:223], off
	s_waitcnt vmcnt(8)
	s_barrier
	s_waitcnt lgkmcnt(0)
	v_mfma_f32_16x16x32_bf16 v[126:129], v[164:167], v[180:183], v[126:129]
	v_mfma_f32_16x16x32_bf16 v[122:125], v[172:175], v[180:183], v[122:125]
	v_mfma_f32_16x16x32_bf16 v[118:121], v[164:167], v[188:191], v[118:121]
	v_mfma_f32_16x16x32_bf16 v[114:117], v[172:175], v[188:191], v[114:117]
	v_mfma_f32_16x16x32_bf16 v[110:113], v[164:167], v[196:199], v[110:113]
	v_mfma_f32_16x16x32_bf16 v[106:109], v[172:175], v[196:199], v[106:109]
	v_mfma_f32_16x16x32_bf16 v[102:105], v[164:167], v[206:209], v[102:105]
	v_mfma_f32_16x16x32_bf16 v[98:101], v[172:175], v[206:209], v[98:101]
	v_mfma_f32_16x16x32_bf16 v[126:129], v[168:171], v[184:187], v[126:129]
	v_mfma_f32_16x16x32_bf16 v[122:125], v[176:179], v[184:187], v[122:125]
	v_mfma_f32_16x16x32_bf16 v[118:121], v[168:171], v[192:195], v[118:121]
	v_mfma_f32_16x16x32_bf16 v[114:117], v[176:179], v[192:195], v[114:117]
	v_mfma_f32_16x16x32_bf16 v[110:113], v[168:171], v[202:205], v[110:113]
	v_mfma_f32_16x16x32_bf16 v[106:109], v[176:179], v[202:205], v[106:109]
	v_mfma_f32_16x16x32_bf16 v[102:105], v[168:171], v[216:219], v[102:105]
	v_mfma_f32_16x16x32_bf16 v[98:101], v[176:179], v[216:219], v[98:101]
	v_mfma_f32_16x16x32_bf16 v[94:97], v[228:231], v[180:183], v[94:97]
	v_mfma_f32_16x16x32_bf16 v[90:93], v[236:239], v[180:183], v[90:93]
	v_mfma_f32_16x16x32_bf16 v[86:89], v[228:231], v[188:191], v[86:89]
	v_mfma_f32_16x16x32_bf16 v[82:85], v[236:239], v[188:191], v[82:85]
	v_mfma_f32_16x16x32_bf16 v[78:81], v[228:231], v[196:199], v[78:81]
	v_mfma_f32_16x16x32_bf16 v[74:77], v[236:239], v[196:199], v[74:77]
	v_mfma_f32_16x16x32_bf16 v[70:73], v[228:231], v[206:209], v[70:73]
	v_mfma_f32_16x16x32_bf16 v[66:69], v[236:239], v[206:209], v[66:69]
	v_mfma_f32_16x16x32_bf16 v[94:97], v[232:235], v[184:187], v[94:97]
	v_mfma_f32_16x16x32_bf16 v[90:93], v[240:243], v[184:187], v[90:93]
	v_mfma_f32_16x16x32_bf16 v[86:89], v[232:235], v[192:195], v[86:89]
	v_mfma_f32_16x16x32_bf16 v[82:85], v[240:243], v[192:195], v[82:85]
	v_mfma_f32_16x16x32_bf16 v[78:81], v[232:235], v[202:205], v[78:81]
	v_mfma_f32_16x16x32_bf16 v[74:77], v[240:243], v[202:205], v[74:77]
	v_mfma_f32_16x16x32_bf16 v[70:73], v[232:235], v[216:219], v[70:73]
	v_mfma_f32_16x16x32_bf16 v[66:69], v[240:243], v[216:219], v[66:69]
	s_barrier
; #define STAGE_B(P, br, kt) do { const char* _gb = (const char*)(Bt + ((long)(br) * K + (long)(kt) * BK)); \
;     __builtin_amdgcn_global_load_lds((const unsigned*)(_gb + bofl0), (unsigned*)((char*)(P) + gtid_ * 16), 16, 0, 0); \
;     __builtin_amdgcn_global_load_lds((const unsigned*)(_gb + (long)K * 128 + bofl0), (unsigned*)((char*)(P) + gtid_ * 16 + 8192), 16, 0, 0); } while (0)
; #define LDA(dst, b, h) for (int m = 0; m < 4; ++m) for (int k = 0; k < 2; ++k) \
;     dst[m][k] = *reinterpret_cast<const bf16x8*>((char*)SA(b, h) + lds_byte(wr * 64 + m * 16 + fr, k * 32 + fq * 8))
; #define LDB(dst, b, h) for (int n = 0; n < 2; ++n) for (int k = 0; k < 2; ++k) \
;     dst[n][k] = *reinterpret_cast<const bf16x8*>((char*)SB(b, h) + lds_byte(wc * 32 + n * 16 + fr, k * 32 + fq * 8))
; #define MMA(ai, bj, At_, Bt_) do { __builtin_amdgcn_s_setprio(1); \
;     for (int m = 0; m < 4; ++m) for (int n = 0; n < 2; ++n) for (int k = 0; k < 2; ++k) \
;       acc[ai][bj][m][n] = __builtin_amdgcn_mfma_f32_16x16x32_bf16(At_[m][k], Bt_[n][k], acc[ai][bj][m][n], 0, 0, 0); \
;     __builtin_amdgcn_s_setprio(0); } while (0)
; #define WAIT_V(n) asm volatile("s_waitcnt vmcnt(" #n ")" ::: "memory")
; #define WAIT_L(n) asm volatile("s_waitcnt lgkmcnt(" #n ")" ::: "memory")
; #define BAR __builtin_amdgcn_s_barrier()
; #define SCHED __builtin_amdgcn_sched_barrier(0)
; template <int EPI>
; __device__ __forceinline__ void gemm_tile(const GemmArgs& g, int brow, int bcol, int parity, bool first, bool nvalid, int nbrow, int nbcol) {
;     ...
;     LDB(B1, 1, 1); STAGE_B(SB(1, 0), bcol, t + 3);
;     BAR; WAIT_L(0); MMA(0, 1, At, B1); BAR; SCHED;
;     LDA(At, 1, 1); STAGE_A(SA(1, 0), brow, t + 3);
;     BAR; WAIT_L(0); MMA(1, 0, At, B0); BAR; SCHED;
;     STAGE_B(SB(1, 1), bcol + HALF, t + 3);
;     WAIT_V(6); BAR; MMA(1, 1, At, B1); BAR; SCHED;
;   }
;   { LDB(B0, 0, 0); LDA(At, 0, 0); STAGE_A(SA(1, 1), brow + HALF, nt - 1);
;     BAR; WAIT_L(0); MMA(0, 0, At, B0); BAR;
	ds_read_b128 v[180:183], v147 offset:49152
	ds_read_b128 v[184:187], v147 offset:50176
	ds_read_b128 v[188:191], v146 offset:49152
	ds_read_b128 v[192:195], v146 offset:50176
	ds_read_b128 v[196:199], v145 offset:49152
	ds_read_b128 v[202:205], v145 offset:50176
	ds_read_b128 v[206:209], v144 offset:49152
	ds_read_b128 v[216:219], v144 offset:50176
	v_readfirstlane_b32 s2, v150
	v_lshl_add_u64 v[222:223], v[212:213], 0, s[58:59]
	s_mov_b32 m0, s2
	v_readfirstlane_b32 s2, v151
	global_load_lds_dwordx4 v[222:223], off
	v_lshl_add_u64 v[222:223], v[212:213], 0, vcc
	s_mov_b32 m0, s2
	s_nop 0
	global_load_lds_dwordx4 v[222:223], off
	v_readfirstlane_b32 s2, v152
	v_lshl_add_u64 v[222:223], v[210:211], 0, s[48:49]
	s_mov_b32 m0, s2
	v_readfirstlane_b32 s2, v153
	global_load_lds_dwordx4 v[222:223], off
	v_lshl_add_u64 v[210:211], v[210:211], 0, s[50:51]
	s_mov_b32 m0, s2
	s_nop 0
	global_load_lds_dwordx4 v[210:211], off
	v_readfirstlane_b32 s2, v155
	v_lshl_add_u64 v[244:245], v[212:213], 0, s[60:61]
	s_mov_b32 m0, s2
	v_readfirstlane_b32 s2, v156
	global_load_lds_dwordx4 v[244:245], off
	v_lshl_add_u64 v[244:245], v[212:213], 0, s[94:95]
	s_mov_b32 m0, s2
	s_nop 0
	global_load_lds_dwordx4 v[244:245], off
	s_waitcnt vmcnt(8)
	s_barrier
	s_waitcnt lgkmcnt(0)
	v_mfma_f32_16x16x32_bf16 v[62:65], v[164:167], v[180:183], v[62:65]
	v_mfma_f32_16x16x32_bf16 v[58:61], v[172:175], v[180:183], v[58:61]
	v_mfma_f32_16x16x32_bf16 v[54:57], v[164:167], v[188:191], v[54:57]
	v_mfma_f32_16x16x32_bf16 v[50:53], v[172:175], v[188:191], v[50:53]
	v_mfma_f32_16x16x32_bf16 v[46:49], v[164:167], v[196:199], v[46:49]
	v_mfma_f32_16x16x32_bf16 v[42:45], v[172:175], v[196:199], v[42:45]
	v_mfma_f32_16x16x32_bf16 v[38:41], v[164:167], v[206:209], v[38:41]
	v_mfma_f32_16x16x32_bf16 v[34:37], v[172:175], v[206:209], v[34:37]
	v_mfma_f32_16x16x32_bf16 v[62:65], v[168:171], v[184:187], v[62:65]
	v_mfma_f32_16x16x32_bf16 v[58:61], v[176:179], v[184:187], v[58:61]
	v_mfma_f32_16x16x32_bf16 v[54:57], v[168:171], v[192:195], v[54:57]
	v_mfma_f32_16x16x32_bf16 v[50:53], v[176:179], v[192:195], v[50:53]
	v_mfma_f32_16x16x32_bf16 v[46:49], v[168:171], v[202:205], v[46:49]
	v_mfma_f32_16x16x32_bf16 v[42:45], v[176:179], v[202:205], v[42:45]
	v_mfma_f32_16x16x32_bf16 v[38:41], v[168:171], v[216:219], v[38:41]
	v_mfma_f32_16x16x32_bf16 v[34:37], v[176:179], v[216:219], v[34:37]
	v_mfma_f32_16x16x32_bf16 v[30:33], v[228:231], v[180:183], v[30:33]
	v_mfma_f32_16x16x32_bf16 v[26:29], v[236:239], v[180:183], v[26:29]
	v_mfma_f32_16x16x32_bf16 v[22:25], v[228:231], v[188:191], v[22:25]
	v_mfma_f32_16x16x32_bf16 v[18:21], v[236:239], v[188:191], v[18:21]
	v_mfma_f32_16x16x32_bf16 v[14:17], v[228:231], v[196:199], v[14:17]
	v_mfma_f32_16x16x32_bf16 v[10:13], v[236:239], v[196:199], v[10:13]
	v_mfma_f32_16x16x32_bf16 v[6:9], v[228:231], v[206:209], v[6:9]
	v_mfma_f32_16x16x32_bf16 v[2:5], v[236:239], v[206:209], v[2:5]
	v_mfma_f32_16x16x32_bf16 v[30:33], v[232:235], v[184:187], v[30:33]
	v_mfma_f32_16x16x32_bf16 v[26:29], v[240:243], v[184:187], v[26:29]
	v_mfma_f32_16x16x32_bf16 v[22:25], v[232:235], v[192:195], v[22:25]
	v_mfma_f32_16x16x32_bf16 v[18:21], v[240:243], v[192:195], v[18:21]
	v_mfma_f32_16x16x32_bf16 v[14:17], v[232:235], v[202:205], v[14:17]
	v_mfma_f32_16x16x32_bf16 v[10:13], v[240:243], v[202:205], v[10:13]
	v_mfma_f32_16x16x32_bf16 v[6:9], v[232:235], v[216:219], v[6:9]
	v_mfma_f32_16x16x32_bf16 v[2:5], v[240:243], v[216:219], v[2:5]
	s_add_i32 s23, s23, 2
	s_add_u32 s12, s12, 0x100
	s_addc_u32 s13, s13, 0
	s_add_u32 s0, s0, 0x100
	s_addc_u32 s1, s1, 0
	s_cmp_lt_u32 s23, 12
	s_cbranch_scc1 .LBB0_640
	s_barrier
	s_or_b32 s0, s40, 0x80
	s_ashr_i32 s1, s0, 31
	s_lshl_b64 s[0:1], s[0:1], 11
	s_add_u32 s0, s80, s0
	s_addc_u32 s1, s81, s1
	v_lshl_add_u64 v[130:131], s[0:1], 0, v[0:1]
	s_mov_b64 s[0:1], 0x780
	ds_read_b128 v[150:153], v157
	ds_read_b128 v[164:167], v157 offset:1024
	ds_read_b128 v[168:171], v157 offset:2048
	ds_read_b128 v[172:175], v157 offset:3072
	ds_read_b128 v[176:179], v147
	ds_read_b128 v[180:183], v147 offset:1024
	ds_read_b128 v[184:187], v146
	ds_read_b128 v[188:191], v146 offset:1024
	ds_read_b128 v[192:195], v145
	ds_read_b128 v[196:199], v145 offset:1024
	ds_read_b128 v[202:205], v144
	ds_read_b128 v[206:209], v144 offset:1024
	v_lshl_add_u64 v[156:157], v[130:131], 0, s[0:1]
	v_readfirstlane_b32 s0, v161
	s_mov_b32 m0, s0
	s_mov_b64 s[0:1], 0x20780
	v_lshl_add_u64 v[130:131], v[130:131], 0, s[0:1]
	v_readfirstlane_b32 s0, v162
	global_load_lds_dwordx4 v[156:157], off
	s_mov_b32 m0, s0
	s_nop 0
	global_load_lds_dwordx4 v[130:131], off
	s_waitcnt vmcnt(8)
	s_barrier
	s_waitcnt lgkmcnt(0)
	s_setprio 1
	s_waitcnt lgkmcnt(0)
	v_mfma_f32_16x16x32_bf16 v[126:129], v[150:153], v[176:179], v[126:129]
	v_mfma_f32_16x16x32_bf16 v[118:121], v[150:153], v[184:187], v[118:121]
	v_mfma_f32_16x16x32_bf16 v[110:113], v[150:153], v[192:195], v[110:113]
	v_mfma_f32_16x16x32_bf16 v[102:105], v[150:153], v[202:205], v[102:105]
	v_mfma_f32_16x16x32_bf16 v[126:129], v[164:167], v[180:183], v[126:129]
	v_mfma_f32_16x16x32_bf16 v[122:125], v[168:171], v[176:179], v[122:125]
	v_mfma_f32_16x16x32_bf16 v[118:121], v[164:167], v[188:191], v[118:121]
	v_mfma_f32_16x16x32_bf16 v[114:117], v[168:171], v[184:187], v[114:117]
	v_mfma_f32_16x16x32_bf16 v[110:113], v[164:167], v[196:199], v[110:113]
	v_mfma_f32_16x16x32_bf16 v[106:109], v[168:171], v[192:195], v[106:109]
	v_mfma_f32_16x16x32_bf16 v[102:105], v[164:167], v[206:209], v[102:105]
	v_mfma_f32_16x16x32_bf16 v[98:101], v[168:171], v[202:205], v[98:101]
	v_mfma_f32_16x16x32_bf16 v[216:219], v[172:175], v[180:183], v[122:125]
	v_mfma_f32_16x16x32_bf16 v[228:231], v[172:175], v[188:191], v[114:117]
	v_mfma_f32_16x16x32_bf16 v[232:235], v[172:175], v[196:199], v[106:109]
	v_mfma_f32_16x16x32_bf16 v[236:239], v[172:175], v[206:209], v[98:101]
	s_setprio 0
	s_barrier
; #define LDA(dst, b, h) for (int m = 0; m < 4; ++m) for (int k = 0; k < 2; ++k) \
;     dst[m][k] = *reinterpret_cast<const bf16x8*>((char*)SA(b, h) + lds_byte(wr * 64 + m * 16 + fr, k * 32 + fq * 8))
; #define LDB(dst, b, h) for (int n = 0; n < 2; ++n) for (int k = 0; k < 2; ++k) \
;     dst[n][k] = *reinterpret_cast<const bf16x8*>((char*)SB(b, h) + lds_byte(wc * 32 + n * 16 + fr, k * 32 + fq * 8))
; #define MMA(ai, bj, At_, Bt_) do { __builtin_amdgcn_s_setprio(1); \
;     for (int m = 0; m < 4; ++m) for (int n = 0; n < 2; ++n) for (int k = 0; k < 2; ++k) \
;       acc[ai][bj][m][n] = __builtin_amdgcn_mfma_f32_16x16x32_bf16(At_[m][k], Bt_[n][k], acc[ai][bj][m][n], 0, 0, 0); \
;     __builtin_amdgcn_s_setprio(0); } while (0)
; #define WAIT_V(n) asm volatile("s_waitcnt vmcnt(" #n ")" ::: "memory")
; #define WAIT_L(n) asm volatile("s_waitcnt lgkmcnt(" #n ")" ::: "memory")
; #define BAR __builtin_amdgcn_s_barrier()
; #define SCHED __builtin_amdgcn_sched_barrier(0)
; template <int EPI>
; __device__ __forceinline__ void gemm_tile(const GemmArgs& g, int brow, int bcol, int parity, bool first, bool nvalid, int nbrow, int nbcol) {
;     ...
;     BAR; WAIT_L(0); MMA(0, 0, At, B0); BAR;
;     LDB(B1, 0, 1); BAR; WAIT_L(0); MMA(0, 1, At, B1); BAR; SCHED;
;     LDA(At, 0, 1); WAIT_V(4); BAR; WAIT_L(0); MMA(1, 0, At, B0); MMA(1, 1, At, B1); BAR; }
;   { LDB(B0, 1, 0); LDA(At, 1, 0); WAIT_V(2); BAR; WAIT_L(0); MMA(0, 0, At, B0); BAR;
	s_nop 1
	ds_read_b128 v[98:101], v154
	ds_read_b128 v[106:109], v154 offset:1024
	ds_read_b128 v[114:117], v154 offset:2048
	ds_read_b128 v[122:125], v154 offset:3072
	s_barrier
	s_waitcnt lgkmcnt(0)
	s_setprio 1
	s_waitcnt lgkmcnt(0)
	v_mfma_f32_16x16x32_bf16 v[94:97], v[98:101], v[176:179], v[94:97]
	v_mfma_f32_16x16x32_bf16 v[86:89], v[98:101], v[184:187], v[86:89]
	v_mfma_f32_16x16x32_bf16 v[78:81], v[98:101], v[192:195], v[78:81]
	v_mfma_f32_16x16x32_bf16 v[70:73], v[98:101], v[202:205], v[70:73]
	v_mfma_f32_16x16x32_bf16 v[94:97], v[106:109], v[180:183], v[94:97]
	v_mfma_f32_16x16x32_bf16 v[90:93], v[114:117], v[176:179], v[90:93]
	v_mfma_f32_16x16x32_bf16 v[86:89], v[106:109], v[188:191], v[86:89]
	v_mfma_f32_16x16x32_bf16 v[82:85], v[114:117], v[184:187], v[82:85]
	v_mfma_f32_16x16x32_bf16 v[78:81], v[106:109], v[196:199], v[78:81]
	v_mfma_f32_16x16x32_bf16 v[74:77], v[114:117], v[192:195], v[74:77]
	v_mfma_f32_16x16x32_bf16 v[70:73], v[106:109], v[206:209], v[70:73]
	v_mfma_f32_16x16x32_bf16 v[66:69], v[114:117], v[202:205], v[66:69]
	v_mfma_f32_16x16x32_bf16 v[154:157], v[122:125], v[180:183], v[90:93]
	v_mfma_f32_16x16x32_bf16 v[176:179], v[122:125], v[188:191], v[82:85]
	v_mfma_f32_16x16x32_bf16 v[180:183], v[122:125], v[196:199], v[74:77]
	v_mfma_f32_16x16x32_bf16 v[184:187], v[122:125], v[206:209], v[66:69]
	s_setprio 0
	s_barrier
	s_nop 1
	ds_read_b128 v[66:69], v147 offset:16384
	ds_read_b128 v[74:77], v147 offset:17408
	ds_read_b128 v[82:85], v146 offset:16384
	ds_read_b128 v[90:93], v146 offset:17408
	ds_read_b128 v[188:191], v145 offset:16384
	ds_read_b128 v[192:195], v145 offset:17408
	ds_read_b128 v[196:199], v144 offset:16384
	ds_read_b128 v[202:205], v144 offset:17408
	s_waitcnt vmcnt(4)
	s_barrier
	s_waitcnt lgkmcnt(0)
	s_setprio 1
	s_waitcnt lgkmcnt(0)
	v_mfma_f32_16x16x32_bf16 v[62:65], v[150:153], v[66:69], v[62:65]
	v_mfma_f32_16x16x32_bf16 v[54:57], v[150:153], v[82:85], v[54:57]
	v_mfma_f32_16x16x32_bf16 v[46:49], v[150:153], v[188:191], v[46:49]
	v_mfma_f32_16x16x32_bf16 v[38:41], v[150:153], v[196:199], v[38:41]
	v_mfma_f32_16x16x32_bf16 v[62:65], v[164:167], v[74:77], v[62:65]
	v_mfma_f32_16x16x32_bf16 v[58:61], v[168:171], v[66:69], v[58:61]
	v_mfma_f32_16x16x32_bf16 v[54:57], v[164:167], v[90:93], v[54:57]
	v_mfma_f32_16x16x32_bf16 v[50:53], v[168:171], v[82:85], v[50:53]
	v_mfma_f32_16x16x32_bf16 v[46:49], v[164:167], v[192:195], v[46:49]
	v_mfma_f32_16x16x32_bf16 v[42:45], v[168:171], v[188:191], v[42:45]
	v_mfma_f32_16x16x32_bf16 v[38:41], v[164:167], v[202:205], v[38:41]
	v_mfma_f32_16x16x32_bf16 v[34:37], v[168:171], v[196:199], v[34:37]
	v_mfma_f32_16x16x32_bf16 v[206:209], v[172:175], v[74:77], v[58:61]
	v_mfma_f32_16x16x32_bf16 v[240:243], v[172:175], v[90:93], v[50:53]
	v_mfma_f32_16x16x32_bf16 v[244:247], v[172:175], v[192:195], v[42:45]
	v_mfma_f32_16x16x32_bf16 v[150:153], v[172:175], v[202:205], v[34:37]
	s_setprio 0
	s_setprio 1
	v_mfma_f32_16x16x32_bf16 v[30:33], v[98:101], v[66:69], v[30:33]
	v_mfma_f32_16x16x32_bf16 v[22:25], v[98:101], v[82:85], v[22:25]
	v_mfma_f32_16x16x32_bf16 v[14:17], v[98:101], v[188:191], v[14:17]
	v_mfma_f32_16x16x32_bf16 v[6:9], v[98:101], v[196:199], v[6:9]
	v_mfma_f32_16x16x32_bf16 v[30:33], v[106:109], v[74:77], v[30:33]
	v_mfma_f32_16x16x32_bf16 v[26:29], v[114:117], v[66:69], v[26:29]
	v_mfma_f32_16x16x32_bf16 v[22:25], v[106:109], v[90:93], v[22:25]
	v_mfma_f32_16x16x32_bf16 v[18:21], v[114:117], v[82:85], v[18:21]
	v_mfma_f32_16x16x32_bf16 v[14:17], v[106:109], v[192:195], v[14:17]
	v_mfma_f32_16x16x32_bf16 v[10:13], v[114:117], v[188:191], v[10:13]
	v_mfma_f32_16x16x32_bf16 v[6:9], v[106:109], v[202:205], v[6:9]
	v_mfma_f32_16x16x32_bf16 v[2:5], v[114:117], v[196:199], v[2:5]
	v_mfma_f32_16x16x32_bf16 v[162:165], v[122:125], v[74:77], v[26:29]
	v_mfma_f32_16x16x32_bf16 v[166:169], v[122:125], v[90:93], v[18:21]
	v_mfma_f32_16x16x32_bf16 v[170:173], v[122:125], v[192:195], v[10:13]
	v_mfma_f32_16x16x32_bf16 v[188:191], v[122:125], v[202:205], v[2:5]
	s_setprio 0
	s_barrier
	s_nop 1
	ds_read_b128 v[2:5], v149
	ds_read_b128 v[10:13], v149 offset:1024
	ds_read_b128 v[18:21], v149 offset:2048
	ds_read_b128 v[26:29], v149 offset:3072
	ds_read_b128 v[34:37], v147 offset:32768
	ds_read_b128 v[42:45], v147 offset:33792
	ds_read_b128 v[50:53], v146 offset:32768
	ds_read_b128 v[58:61], v146 offset:33792
	ds_read_b128 v[66:69], v145 offset:32768
	ds_read_b128 v[192:195], v145 offset:33792
	ds_read_b128 v[196:199], v144 offset:32768
	ds_read_b128 v[202:205], v144 offset:33792
	s_waitcnt vmcnt(2)
	s_barrier
; #define LDA(dst, b, h) for (int m = 0; m < 4; ++m) for (int k = 0; k < 2; ++k) \
;     dst[m][k] = *reinterpret_cast<const bf16x8*>((char*)SA(b, h) + lds_byte(wr * 64 + m * 16 + fr, k * 32 + fq * 8))
; #define LDB(dst, b, h) for (int n = 0; n < 2; ++n) for (int k = 0; k < 2; ++k) \
;     dst[n][k] = *reinterpret_cast<const bf16x8*>((char*)SB(b, h) + lds_byte(wc * 32 + n * 16 + fr, k * 32 + fq * 8))
; #define MMA(ai, bj, At_, Bt_) do { __builtin_amdgcn_s_setprio(1); \
;     for (int m = 0; m < 4; ++m) for (int n = 0; n < 2; ++n) for (int k = 0; k < 2; ++k) \
;       acc[ai][bj][m][n] = __builtin_amdgcn_mfma_f32_16x16x32_bf16(At_[m][k], Bt_[n][k], acc[ai][bj][m][n], 0, 0, 0); \
;     __builtin_amdgcn_s_setprio(0); } while (0)
; #define WAIT_V(n) asm volatile("s_waitcnt vmcnt(" #n ")" ::: "memory")
; #define WAIT_L(n) asm volatile("s_waitcnt lgkmcnt(" #n ")" ::: "memory")
; #define BAR __builtin_amdgcn_s_barrier()
; #define SCHED __builtin_amdgcn_sched_barrier(0)
; template <int EPI>
; __device__ __forceinline__ void gemm_tile(const GemmArgs& g, int brow, int bcol, int parity, bool first, bool nvalid, int nbrow, int nbcol) {
;     ...
;   { LDB(B0, 1, 0); LDA(At, 1, 0); WAIT_V(2); BAR; WAIT_L(0); MMA(0, 0, At, B0); BAR;
;     LDB(B1, 1, 1); WAIT_V(0); BAR; WAIT_L(0); MMA(0, 1, At, B1); BAR; SCHED;
;     LDA(At, 1, 1); BAR; WAIT_L(0); MMA(1, 0, At, B0); MMA(1, 1, At, B1); BAR; }
;   if (wr == 0) BAR;
	s_waitcnt lgkmcnt(0)
	s_setprio 1
	s_waitcnt lgkmcnt(0)
	v_mfma_f32_16x16x32_bf16 v[74:77], v[2:5], v[34:37], v[126:129]
	v_mfma_f32_16x16x32_bf16 v[122:125], v[10:13], v[42:45], v[74:77]
	v_mfma_f32_16x16x32_bf16 v[74:77], v[18:21], v[34:37], v[216:219]
	v_mfma_f32_16x16x32_bf16 v[126:129], v[26:29], v[42:45], v[74:77]
	v_mfma_f32_16x16x32_bf16 v[74:77], v[2:5], v[50:53], v[118:121]
	v_mfma_f32_16x16x32_bf16 v[114:117], v[10:13], v[58:61], v[74:77]
	v_mfma_f32_16x16x32_bf16 v[74:77], v[18:21], v[50:53], v[228:231]
	v_mfma_f32_16x16x32_bf16 v[118:121], v[26:29], v[58:61], v[74:77]
	v_mfma_f32_16x16x32_bf16 v[74:77], v[2:5], v[66:69], v[110:113]
	v_mfma_f32_16x16x32_bf16 v[106:109], v[10:13], v[192:195], v[74:77]
	v_mfma_f32_16x16x32_bf16 v[74:77], v[18:21], v[66:69], v[232:235]
	v_mfma_f32_16x16x32_bf16 v[110:113], v[26:29], v[192:195], v[74:77]
	v_mfma_f32_16x16x32_bf16 v[74:77], v[2:5], v[196:199], v[102:105]
	v_mfma_f32_16x16x32_bf16 v[98:101], v[10:13], v[202:205], v[74:77]
	v_mfma_f32_16x16x32_bf16 v[74:77], v[18:21], v[196:199], v[236:239]
	v_mfma_f32_16x16x32_bf16 v[102:105], v[26:29], v[202:205], v[74:77]
	s_setprio 0
	s_barrier
	ds_read_b128 v[216:219], v148
	ds_read_b128 v[228:231], v148 offset:1024
	ds_read_b128 v[232:235], v148 offset:2048
	ds_read_b128 v[236:239], v148 offset:3072
	s_waitcnt vmcnt(0)
	s_barrier
	s_waitcnt lgkmcnt(0)
	s_setprio 1
	s_waitcnt lgkmcnt(0)
	v_mfma_f32_16x16x32_bf16 v[74:77], v[216:219], v[34:37], v[94:97]
	v_mfma_f32_16x16x32_bf16 v[34:37], v[232:235], v[34:37], v[154:157]
	v_mfma_f32_16x16x32_bf16 v[94:97], v[236:239], v[42:45], v[34:37]
	v_mfma_f32_16x16x32_bf16 v[34:37], v[216:219], v[50:53], v[86:89]
	v_mfma_f32_16x16x32_bf16 v[82:85], v[228:231], v[58:61], v[34:37]
	v_mfma_f32_16x16x32_bf16 v[34:37], v[232:235], v[50:53], v[176:179]
	v_mfma_f32_16x16x32_bf16 v[86:89], v[236:239], v[58:61], v[34:37]
	v_mfma_f32_16x16x32_bf16 v[34:37], v[216:219], v[66:69], v[78:81]
	v_mfma_f32_16x16x32_bf16 v[90:93], v[228:231], v[42:45], v[74:77]
	v_mfma_f32_16x16x32_bf16 v[74:77], v[228:231], v[192:195], v[34:37]
	v_mfma_f32_16x16x32_bf16 v[34:37], v[232:235], v[66:69], v[180:183]
	v_mfma_f32_16x16x32_bf16 v[78:81], v[236:239], v[192:195], v[34:37]
	v_mfma_f32_16x16x32_bf16 v[34:37], v[216:219], v[196:199], v[70:73]
	v_mfma_f32_16x16x32_bf16 v[66:69], v[228:231], v[202:205], v[34:37]
	v_mfma_f32_16x16x32_bf16 v[34:37], v[232:235], v[196:199], v[184:187]
	v_mfma_f32_16x16x32_bf16 v[70:73], v[236:239], v[202:205], v[34:37]
	s_setprio 0
	s_barrier
	ds_read_b128 v[154:157], v147 offset:49152
	ds_read_b128 v[174:177], v147 offset:50176
	ds_read_b128 v[178:181], v146 offset:49152
	ds_read_b128 v[146:149], v146 offset:50176
	ds_read_b128 v[182:185], v145 offset:49152
	ds_read_b128 v[192:195], v145 offset:50176
	ds_read_b128 v[196:199], v144 offset:49152
	ds_read_b128 v[202:205], v144 offset:50176
	s_barrier
	s_waitcnt lgkmcnt(0)
	s_setprio 1
	s_waitcnt lgkmcnt(0)
	v_mfma_f32_16x16x32_bf16 v[34:37], v[2:5], v[154:157], v[62:65]
	v_mfma_f32_16x16x32_bf16 v[58:61], v[10:13], v[174:177], v[34:37]
	v_mfma_f32_16x16x32_bf16 v[34:37], v[18:21], v[154:157], v[206:209]
	v_mfma_f32_16x16x32_bf16 v[62:65], v[26:29], v[174:177], v[34:37]
	v_mfma_f32_16x16x32_bf16 v[34:37], v[2:5], v[178:181], v[54:57]
	v_mfma_f32_16x16x32_bf16 v[50:53], v[10:13], v[146:149], v[34:37]
	v_mfma_f32_16x16x32_bf16 v[34:37], v[18:21], v[178:181], v[240:243]
	v_mfma_f32_16x16x32_bf16 v[54:57], v[26:29], v[146:149], v[34:37]
	v_mfma_f32_16x16x32_bf16 v[34:37], v[2:5], v[182:185], v[46:49]
	v_mfma_f32_16x16x32_bf16 v[42:45], v[10:13], v[192:195], v[34:37]
	v_mfma_f32_16x16x32_bf16 v[34:37], v[18:21], v[182:185], v[244:247]
	v_mfma_f32_16x16x32_bf16 v[2:5], v[2:5], v[196:199], v[38:41]
	v_mfma_f32_16x16x32_bf16 v[46:49], v[26:29], v[192:195], v[34:37]
	v_mfma_f32_16x16x32_bf16 v[34:37], v[10:13], v[202:205], v[2:5]
	v_mfma_f32_16x16x32_bf16 v[2:5], v[18:21], v[196:199], v[150:153]
	v_mfma_f32_16x16x32_bf16 v[38:41], v[26:29], v[202:205], v[2:5]
	s_setprio 0
	s_setprio 1
	v_mfma_f32_16x16x32_bf16 v[2:5], v[216:219], v[154:157], v[30:33]
	v_mfma_f32_16x16x32_bf16 v[26:29], v[228:231], v[174:177], v[2:5]
	v_mfma_f32_16x16x32_bf16 v[2:5], v[232:235], v[154:157], v[162:165]
	v_mfma_f32_16x16x32_bf16 v[30:33], v[236:239], v[174:177], v[2:5]
	v_mfma_f32_16x16x32_bf16 v[2:5], v[216:219], v[178:181], v[22:25]
	v_mfma_f32_16x16x32_bf16 v[18:21], v[228:231], v[146:149], v[2:5]
	v_mfma_f32_16x16x32_bf16 v[2:5], v[232:235], v[178:181], v[166:169]
	v_mfma_f32_16x16x32_bf16 v[22:25], v[236:239], v[146:149], v[2:5]
	v_mfma_f32_16x16x32_bf16 v[2:5], v[216:219], v[182:185], v[14:17]
	v_mfma_f32_16x16x32_bf16 v[10:13], v[228:231], v[192:195], v[2:5]
	v_mfma_f32_16x16x32_bf16 v[2:5], v[232:235], v[182:185], v[170:173]
	v_mfma_f32_16x16x32_bf16 v[14:17], v[236:239], v[192:195], v[2:5]
	v_mfma_f32_16x16x32_bf16 v[2:5], v[216:219], v[196:199], v[6:9]
	v_mfma_f32_16x16x32_bf16 v[6:9], v[232:235], v[196:199], v[188:191]
	v_mfma_f32_16x16x32_bf16 v[2:5], v[228:231], v[202:205], v[2:5]
	v_mfma_f32_16x16x32_bf16 v[6:9], v[236:239], v[202:205], v[6:9]
	s_setprio 0
	s_movk_i32 s0, 0x100
	v_cmp_gt_u32_e32 vcc, s0, v138
	s_barrier
	s_and_saveexec_b64 s[0:1], vcc
	s_cbranch_execz .LBB0_643
	s_barrier
